# k22 plus GEMM segment-3 reordered: the 8 invariant-address LDS fragment reads issued first after the barrier, address math and DMA setup after
# baseline (speedup 1.0000x reference)
; #define PG8_STAGE(bufoff, gbase, voff) do { _Pragma("unroll") for (int _i = 0; _i < 2; ++_i) \
;         __builtin_amdgcn_global_load_lds((const unsigned*)((const char*)(gbase) + (voff)[_i]), (PG8_LAS unsigned*)(lds + (bufoff) + ldsw + _i * 8192), 16, 0, 0); } while (0)
; #define PG8_LDA(dst, b, h) do { _Pragma("unroll") for (int m = 0; m < 4; ++m) _Pragma("unroll") for (int k = 0; k < 2; ++k) dst[m][k] = *(const PG8_LAS bf16x8*)(lds + PG8_SA(b, h) + aoff + m * 2048 + k * 1024); } while (0)
; #define PG8_LDB(dst, b, h) do { _Pragma("unroll") for (int n = 0; n < 2; ++n) _Pragma("unroll") for (int k = 0; k < 2; ++k) dst[n][k] = *(const PG8_LAS bf16x8*)(lds + PG8_SB(b, h) + boff + n * 2048 + k * 1024); } while (0)
; #define PG8_MMA(ai, bj, At, Bt) do { __builtin_amdgcn_s_setprio(1); _Pragma("unroll") for (int m = 0; m < 4; ++m) _Pragma("unroll") for (int n = 0; n < 2; ++n) _Pragma("unroll") for (int k = 0; k < 2; ++k) \
;         acc[ai][bj][m][n] = __builtin_amdgcn_mfma_f32_16x16x32_bf16(Bt[n][k], At[m][k], acc[ai][bj][m][n], 0, 0, 0); __builtin_amdgcn_s_setprio(0); } while (0)
; #define PG8_WAIT_V(n) asm volatile("s_waitcnt vmcnt(" #n ")" ::: "memory")
; #define PG8_WAIT_L(n) asm volatile("s_waitcnt lgkmcnt(" #n ")" ::: "memory")
; template <class Epi, class Sched, bool ALIGN_EPI = false, bool SP2 = false>
; __device__ __forceinline__ void gemm_phase(PG8_LAS unsigned char* lds, const Gemm g, const Sched& S, const Epi& E, const int wv0) {
;     ...
;         for (int t = 0; t < nt; t += 2) {
;             const bool last = (t == nt - 2);
;             const char* a1 = cA + (size_t)(t + 1) * kstep;
;             const char* a2 = last ? nA : cA + (size_t)(t + 2) * kstep; const char* b2 = last ? nB : cB + (size_t)(t + 2) * kstep;
;             const char* a3 = a2 + kstep; const char* b3 = b2 + kstep;
;             if constexpr (SP2) {
;             PG8_LDB(B0, 0, 0); PG8_LDB(B1, 0, 1); PG8_SCHED; PG8_LDA(At, 0, 0); PG8_STAGE(PG8_SA(1, 1), a1 + hstepA, voffA);
;             PG8_WAIT_V(8); PG8_WAIT_L(0); PG8_BAR; PG8_MMA(0, 0, At, B0); PG8_MMA(0, 1, At, B1); PG8_BAR; PG8_SCHED;
;             PG8_LDA(At, 0, 1); PG8_STAGE(PG8_SB(0, 0), b2, voffB); PG8_STAGE(PG8_SB(0, 1), b2 + hstepB, voffB); PG8_STAGE(PG8_SA(0, 0), a2, voffA);
;             PG8_WAIT_V(8); PG8_WAIT_L(0); PG8_BAR; PG8_MMA(1, 0, At, B0); PG8_MMA(1, 1, At, B1); PG8_BAR; PG8_SCHED;
.LBB0_82:
	ds_read_b128 v[156:159], v152
	ds_read_b128 v[160:163], v152 offset:1024
	ds_read_b128 v[164:167], v152 offset:2048
	ds_read_b128 v[168:171], v152 offset:3072
	ds_read_b128 v[172:175], v153
	ds_read_b128 v[176:179], v153 offset:1024
	ds_read_b128 v[180:183], v153 offset:2048
	ds_read_b128 v[184:187], v153 offset:3072
	ds_read_b128 v[188:191], v154
	ds_read_b128 v[192:195], v154 offset:1024
	ds_read_b128 v[196:199], v154 offset:2048
	ds_read_b128 v[200:203], v154 offset:3072
	ds_read_b128 v[206:209], v154 offset:4096
	ds_read_b128 v[210:213], v154 offset:5120
	ds_read_b128 v[214:217], v154 offset:6144
	ds_read_b128 v[218:221], v154 offset:7168
	s_add_u32 s34, s30, 0xfff80080
	s_addc_u32 s35, s31, -1
	s_cmp_eq_u32 s38, 28
	s_cselect_b32 s37, s25, s35
	s_cselect_b32 s36, s24, s34
	s_cselect_b32 s35, s27, s23
	s_cselect_b32 s34, s26, s21
	s_add_i32 m0, s29, 0xc000
	v_lshl_add_u64 v[146:147], s[30:31], 0, v[140:141]
	global_load_lds_dwordx4 v[146:147], off
	v_lshl_add_u64 v[146:147], s[30:31], 0, v[138:139]
	s_add_i32 m0, s29, 0xe000
	s_nop 0
	global_load_lds_dwordx4 v[146:147], off
	s_waitcnt vmcnt(8)
	s_waitcnt lgkmcnt(0)
	s_barrier
	v_mfma_f32_16x16x32_bf16 v[124:127], v[156:159], v[188:191], v[124:127]
	v_mfma_f32_16x16x32_bf16 v[120:123], v[164:167], v[188:191], v[120:123]
	v_mfma_f32_16x16x32_bf16 v[116:119], v[156:159], v[196:199], v[116:119]
	v_mfma_f32_16x16x32_bf16 v[108:111], v[164:167], v[196:199], v[108:111]
	v_mfma_f32_16x16x32_bf16 v[100:103], v[156:159], v[206:209], v[100:103]
	v_mfma_f32_16x16x32_bf16 v[92:95], v[164:167], v[206:209], v[92:95]
	v_mfma_f32_16x16x32_bf16 v[84:87], v[156:159], v[214:217], v[84:87]
	v_mfma_f32_16x16x32_bf16 v[76:79], v[164:167], v[214:217], v[76:79]
	v_mfma_f32_16x16x32_bf16 v[124:127], v[160:163], v[192:195], v[124:127]
	v_mfma_f32_16x16x32_bf16 v[120:123], v[168:171], v[192:195], v[120:123]
	v_mfma_f32_16x16x32_bf16 v[116:119], v[160:163], v[200:203], v[116:119]
	v_mfma_f32_16x16x32_bf16 v[108:111], v[168:171], v[200:203], v[108:111]
	v_mfma_f32_16x16x32_bf16 v[100:103], v[160:163], v[210:213], v[100:103]
	v_mfma_f32_16x16x32_bf16 v[92:95], v[168:171], v[210:213], v[92:95]
	v_mfma_f32_16x16x32_bf16 v[84:87], v[160:163], v[218:221], v[84:87]
	v_mfma_f32_16x16x32_bf16 v[76:79], v[168:171], v[218:221], v[76:79]
	v_mfma_f32_16x16x32_bf16 v[112:115], v[172:175], v[188:191], v[112:115]
	v_mfma_f32_16x16x32_bf16 v[104:107], v[180:183], v[188:191], v[104:107]
	v_mfma_f32_16x16x32_bf16 v[96:99], v[172:175], v[196:199], v[96:99]
	v_mfma_f32_16x16x32_bf16 v[88:91], v[180:183], v[196:199], v[88:91]
	v_mfma_f32_16x16x32_bf16 v[80:83], v[172:175], v[206:209], v[80:83]
	v_mfma_f32_16x16x32_bf16 v[72:75], v[180:183], v[206:209], v[72:75]
	v_mfma_f32_16x16x32_bf16 v[68:71], v[172:175], v[214:217], v[68:71]
	v_mfma_f32_16x16x32_bf16 v[64:67], v[180:183], v[214:217], v[64:67]
	v_mfma_f32_16x16x32_bf16 v[112:115], v[176:179], v[192:195], v[112:115]
	v_mfma_f32_16x16x32_bf16 v[104:107], v[184:187], v[192:195], v[104:107]
	v_mfma_f32_16x16x32_bf16 v[96:99], v[176:179], v[200:203], v[96:99]
	v_mfma_f32_16x16x32_bf16 v[88:91], v[184:187], v[200:203], v[88:91]
	v_mfma_f32_16x16x32_bf16 v[80:83], v[176:179], v[210:213], v[80:83]
	v_mfma_f32_16x16x32_bf16 v[72:75], v[184:187], v[210:213], v[72:75]
	v_mfma_f32_16x16x32_bf16 v[68:71], v[176:179], v[218:221], v[68:71]
	v_mfma_f32_16x16x32_bf16 v[64:67], v[184:187], v[218:221], v[64:67]
	s_barrier
	ds_read_b128 v[188:191], v154 offset:16384
	ds_read_b128 v[192:195], v154 offset:17408
	ds_read_b128 v[196:199], v154 offset:18432
	ds_read_b128 v[200:203], v154 offset:19456
	ds_read_b128 v[206:209], v154 offset:20480
	ds_read_b128 v[210:213], v154 offset:21504
	ds_read_b128 v[214:217], v154 offset:22528
	ds_read_b128 v[218:221], v154 offset:23552
	s_add_i32 s39, s62, s47
	s_mov_b32 m0, s39
	v_lshl_add_u64 v[146:147], s[34:35], 0, v[132:133]
	global_load_lds_dwordx4 v[146:147], off
	s_add_i32 m0, s39, 0x2000
	s_add_u32 s68, s34, 0x80000
	v_lshl_add_u64 v[222:223], s[34:35], 0, v[128:129]
	s_addc_u32 s69, s35, 0
	s_add_i32 s39, s63, s47
	global_load_lds_dwordx4 v[222:223], off
	v_lshl_add_u64 v[224:225], s[68:69], 0, v[132:133]
	s_mov_b32 m0, s39
	v_lshl_add_u64 v[226:227], s[36:37], 0, v[130:131]
	global_load_lds_dwordx4 v[224:225], off
	v_lshl_add_u64 v[224:225], s[68:69], 0, v[128:129]
	s_add_i32 m0, s39, 0x2000
	s_nop 0
	global_load_lds_dwordx4 v[224:225], off
	v_lshl_add_u64 v[224:225], s[36:37], 0, v[134:135]
	s_mov_b32 m0, s29
	s_nop 0
	global_load_lds_dwordx4 v[224:225], off
	s_mov_b32 m0, s49
	s_nop 0
	global_load_lds_dwordx4 v[226:227], off
	s_waitcnt vmcnt(8)
	s_waitcnt lgkmcnt(0)
	s_barrier
; #define PG8_STAGE(bufoff, gbase, voff) do { _Pragma("unroll") for (int _i = 0; _i < 2; ++_i) \
;         __builtin_amdgcn_global_load_lds((const unsigned*)((const char*)(gbase) + (voff)[_i]), (PG8_LAS unsigned*)(lds + (bufoff) + ldsw + _i * 8192), 16, 0, 0); } while (0)
; #define PG8_LDA(dst, b, h) do { _Pragma("unroll") for (int m = 0; m < 4; ++m) _Pragma("unroll") for (int k = 0; k < 2; ++k) dst[m][k] = *(const PG8_LAS bf16x8*)(lds + PG8_SA(b, h) + aoff + m * 2048 + k * 1024); } while (0)
; #define PG8_LDB(dst, b, h) do { _Pragma("unroll") for (int n = 0; n < 2; ++n) _Pragma("unroll") for (int k = 0; k < 2; ++k) dst[n][k] = *(const PG8_LAS bf16x8*)(lds + PG8_SB(b, h) + boff + n * 2048 + k * 1024); } while (0)
; #define PG8_MMA(ai, bj, At, Bt) do { __builtin_amdgcn_s_setprio(1); _Pragma("unroll") for (int m = 0; m < 4; ++m) _Pragma("unroll") for (int n = 0; n < 2; ++n) _Pragma("unroll") for (int k = 0; k < 2; ++k) \
;         acc[ai][bj][m][n] = __builtin_amdgcn_mfma_f32_16x16x32_bf16(Bt[n][k], At[m][k], acc[ai][bj][m][n], 0, 0, 0); __builtin_amdgcn_s_setprio(0); } while (0)
; #define PG8_WAIT_V(n) asm volatile("s_waitcnt vmcnt(" #n ")" ::: "memory")
; #define PG8_WAIT_L(n) asm volatile("s_waitcnt lgkmcnt(" #n ")" ::: "memory")
; #define PG8_BAR __builtin_amdgcn_s_barrier()
; #define PG8_SCHED __builtin_amdgcn_sched_barrier(0)
; template <class Epi, class Sched, bool ALIGN_EPI = false, bool SP2 = false>
; __device__ __forceinline__ void gemm_phase(PG8_LAS unsigned char* lds, const Gemm g, const Sched& S, const Epi& E, const int wv0) {
;     ...
;             PG8_WAIT_V(8); PG8_WAIT_L(0); PG8_BAR; PG8_MMA(1, 0, At, B0); PG8_MMA(1, 1, At, B1); PG8_BAR; PG8_SCHED;
;             PG8_LDB(B0, 1, 0); PG8_LDB(B1, 1, 1); PG8_SCHED; PG8_LDA(At, 1, 0); PG8_STAGE(PG8_SA(0, 1), a2 + hstepA, voffA);
;             PG8_WAIT_V(8); PG8_WAIT_L(0); PG8_BAR; PG8_MMA(0, 0, At, B0); PG8_MMA(0, 1, At, B1); PG8_BAR; PG8_SCHED;
	v_mfma_f32_16x16x32_bf16 v[60:63], v[156:159], v[188:191], v[60:63]
	v_mfma_f32_16x16x32_bf16 v[56:59], v[164:167], v[188:191], v[56:59]
	v_mfma_f32_16x16x32_bf16 v[52:55], v[156:159], v[196:199], v[52:55]
	v_mfma_f32_16x16x32_bf16 v[44:47], v[164:167], v[196:199], v[44:47]
	v_mfma_f32_16x16x32_bf16 v[36:39], v[156:159], v[206:209], v[36:39]
	v_mfma_f32_16x16x32_bf16 v[28:31], v[164:167], v[206:209], v[28:31]
	v_mfma_f32_16x16x32_bf16 v[20:23], v[156:159], v[214:217], v[20:23]
	v_mfma_f32_16x16x32_bf16 v[12:15], v[164:167], v[214:217], v[12:15]
	v_mfma_f32_16x16x32_bf16 v[60:63], v[160:163], v[192:195], v[60:63]
	v_mfma_f32_16x16x32_bf16 v[56:59], v[168:171], v[192:195], v[56:59]
	v_mfma_f32_16x16x32_bf16 v[52:55], v[160:163], v[200:203], v[52:55]
	v_mfma_f32_16x16x32_bf16 v[44:47], v[168:171], v[200:203], v[44:47]
	v_mfma_f32_16x16x32_bf16 v[36:39], v[160:163], v[210:213], v[36:39]
	v_mfma_f32_16x16x32_bf16 v[28:31], v[168:171], v[210:213], v[28:31]
	v_mfma_f32_16x16x32_bf16 v[20:23], v[160:163], v[218:221], v[20:23]
	v_mfma_f32_16x16x32_bf16 v[12:15], v[168:171], v[218:221], v[12:15]
	v_mfma_f32_16x16x32_bf16 v[48:51], v[172:175], v[188:191], v[48:51]
	v_mfma_f32_16x16x32_bf16 v[40:43], v[180:183], v[188:191], v[40:43]
	v_mfma_f32_16x16x32_bf16 v[32:35], v[172:175], v[196:199], v[32:35]
	v_mfma_f32_16x16x32_bf16 v[24:27], v[180:183], v[196:199], v[24:27]
	v_mfma_f32_16x16x32_bf16 v[16:19], v[172:175], v[206:209], v[16:19]
	v_mfma_f32_16x16x32_bf16 v[8:11], v[180:183], v[206:209], v[8:11]
	v_mfma_f32_16x16x32_bf16 v[4:7], v[172:175], v[214:217], v[4:7]
	v_mfma_f32_16x16x32_bf16 v[0:3], v[180:183], v[214:217], v[0:3]
	v_mfma_f32_16x16x32_bf16 v[48:51], v[176:179], v[192:195], v[48:51]
	v_mfma_f32_16x16x32_bf16 v[40:43], v[184:187], v[192:195], v[40:43]
	v_mfma_f32_16x16x32_bf16 v[32:35], v[176:179], v[200:203], v[32:35]
	v_mfma_f32_16x16x32_bf16 v[24:27], v[184:187], v[200:203], v[24:27]
	v_mfma_f32_16x16x32_bf16 v[16:19], v[176:179], v[210:213], v[16:19]
	v_mfma_f32_16x16x32_bf16 v[8:11], v[184:187], v[210:213], v[8:11]
	v_mfma_f32_16x16x32_bf16 v[4:7], v[176:179], v[218:221], v[4:7]
	v_mfma_f32_16x16x32_bf16 v[0:3], v[184:187], v[218:221], v[0:3]
	s_barrier
	ds_read_b128 v[188:191], v154 offset:32768
	ds_read_b128 v[192:195], v154 offset:33792
	ds_read_b128 v[196:199], v154 offset:34816
	ds_read_b128 v[200:203], v154 offset:35840
	ds_read_b128 v[206:209], v154 offset:36864
	ds_read_b128 v[210:213], v154 offset:37888
	ds_read_b128 v[214:217], v154 offset:38912
	ds_read_b128 v[218:221], v154 offset:39936
	s_add_i32 s39, 0, 0x18000
	v_add_u32_e32 v155, s39, v150
	s_add_i32 s68, 0, 0x1c000
	ds_read_b128 v[156:159], v155
	ds_read_b128 v[160:163], v155 offset:1024
	ds_read_b128 v[164:167], v155 offset:2048
	ds_read_b128 v[168:171], v155 offset:3072
	v_add_u32_e32 v155, s68, v150
	ds_read_b128 v[172:175], v155
	ds_read_b128 v[176:179], v155 offset:1024
	ds_read_b128 v[180:183], v155 offset:2048
	ds_read_b128 v[184:187], v155 offset:3072
	s_add_u32 s36, s36, 0x80000
	s_addc_u32 s37, s37, 0
	s_mov_b32 m0, s50
	v_lshl_add_u64 v[228:229], s[36:37], 0, v[134:135]
	global_load_lds_dwordx4 v[228:229], off
	v_lshl_add_u64 v[228:229], s[36:37], 0, v[130:131]
	s_mov_b32 m0, s51
	s_nop 0
	global_load_lds_dwordx4 v[228:229], off
	s_waitcnt vmcnt(8)
	s_waitcnt lgkmcnt(0)
	s_barrier
	v_mfma_f32_16x16x32_bf16 v[124:127], v[156:159], v[188:191], v[124:127]
	v_mfma_f32_16x16x32_bf16 v[120:123], v[164:167], v[188:191], v[120:123]
	v_mfma_f32_16x16x32_bf16 v[116:119], v[156:159], v[196:199], v[116:119]
	v_mfma_f32_16x16x32_bf16 v[108:111], v[164:167], v[196:199], v[108:111]
	v_mfma_f32_16x16x32_bf16 v[100:103], v[156:159], v[206:209], v[100:103]
	v_mfma_f32_16x16x32_bf16 v[92:95], v[164:167], v[206:209], v[92:95]
	v_mfma_f32_16x16x32_bf16 v[84:87], v[156:159], v[214:217], v[84:87]
	v_mfma_f32_16x16x32_bf16 v[76:79], v[164:167], v[214:217], v[76:79]
	v_mfma_f32_16x16x32_bf16 v[124:127], v[160:163], v[192:195], v[124:127]
	v_mfma_f32_16x16x32_bf16 v[120:123], v[168:171], v[192:195], v[120:123]
	v_mfma_f32_16x16x32_bf16 v[116:119], v[160:163], v[200:203], v[116:119]
	v_mfma_f32_16x16x32_bf16 v[108:111], v[168:171], v[200:203], v[108:111]
	v_mfma_f32_16x16x32_bf16 v[100:103], v[160:163], v[210:213], v[100:103]
	v_mfma_f32_16x16x32_bf16 v[92:95], v[168:171], v[210:213], v[92:95]
	v_mfma_f32_16x16x32_bf16 v[84:87], v[160:163], v[218:221], v[84:87]
	v_mfma_f32_16x16x32_bf16 v[76:79], v[168:171], v[218:221], v[76:79]
	v_mfma_f32_16x16x32_bf16 v[112:115], v[172:175], v[188:191], v[112:115]
	v_mfma_f32_16x16x32_bf16 v[104:107], v[180:183], v[188:191], v[104:107]
	v_mfma_f32_16x16x32_bf16 v[96:99], v[172:175], v[196:199], v[96:99]
	v_mfma_f32_16x16x32_bf16 v[88:91], v[180:183], v[196:199], v[88:91]
	v_mfma_f32_16x16x32_bf16 v[80:83], v[172:175], v[206:209], v[80:83]
	v_mfma_f32_16x16x32_bf16 v[72:75], v[180:183], v[206:209], v[72:75]
	v_mfma_f32_16x16x32_bf16 v[68:71], v[172:175], v[214:217], v[68:71]
	v_mfma_f32_16x16x32_bf16 v[64:67], v[180:183], v[214:217], v[64:67]
	v_mfma_f32_16x16x32_bf16 v[112:115], v[176:179], v[192:195], v[112:115]
	v_mfma_f32_16x16x32_bf16 v[104:107], v[184:187], v[192:195], v[104:107]
	v_mfma_f32_16x16x32_bf16 v[96:99], v[176:179], v[200:203], v[96:99]
	v_mfma_f32_16x16x32_bf16 v[88:91], v[184:187], v[200:203], v[88:91]
	v_mfma_f32_16x16x32_bf16 v[80:83], v[176:179], v[210:213], v[80:83]
	v_mfma_f32_16x16x32_bf16 v[72:75], v[184:187], v[210:213], v[72:75]
	v_mfma_f32_16x16x32_bf16 v[68:71], v[176:179], v[218:221], v[68:71]
	v_mfma_f32_16x16x32_bf16 v[64:67], v[184:187], v[218:221], v[64:67]
	s_barrier
; #define PG8_STAGE(bufoff, gbase, voff) do { _Pragma("unroll") for (int _i = 0; _i < 2; ++_i) \
;         __builtin_amdgcn_global_load_lds((const unsigned*)((const char*)(gbase) + (voff)[_i]), (PG8_LAS unsigned*)(lds + (bufoff) + ldsw + _i * 8192), 16, 0, 0); } while (0)
; #define PG8_LDA(dst, b, h) do { _Pragma("unroll") for (int m = 0; m < 4; ++m) _Pragma("unroll") for (int k = 0; k < 2; ++k) dst[m][k] = *(const PG8_LAS bf16x8*)(lds + PG8_SA(b, h) + aoff + m * 2048 + k * 1024); } while (0)
; #define PG8_MMA(ai, bj, At, Bt) do { __builtin_amdgcn_s_setprio(1); _Pragma("unroll") for (int m = 0; m < 4; ++m) _Pragma("unroll") for (int n = 0; n < 2; ++n) _Pragma("unroll") for (int k = 0; k < 2; ++k) \
;         acc[ai][bj][m][n] = __builtin_amdgcn_mfma_f32_16x16x32_bf16(Bt[n][k], At[m][k], acc[ai][bj][m][n], 0, 0, 0); __builtin_amdgcn_s_setprio(0); } while (0)
; #define PG8_WAIT_V(n) asm volatile("s_waitcnt vmcnt(" #n ")" ::: "memory")
; #define PG8_WAIT_L(n) asm volatile("s_waitcnt lgkmcnt(" #n ")" ::: "memory")
; #define PG8_BAR __builtin_amdgcn_s_barrier()
; #define PG8_SCHED __builtin_amdgcn_sched_barrier(0)
; template <class Epi, class Sched, bool ALIGN_EPI = false, bool SP2 = false>
; __device__ __forceinline__ void gemm_phase(PG8_LAS unsigned char* lds, const Gemm g, const Sched& S, const Epi& E, const int wv0) {
;     ...
;             PG8_LDA(At, 1, 1); PG8_STAGE(PG8_SB(1, 0), b3, voffB); PG8_STAGE(PG8_SB(1, 1), b3 + hstepB, voffB); PG8_STAGE(PG8_SA(1, 0), a3, voffA);
;             PG8_WAIT_V(8); PG8_WAIT_L(0); PG8_BAR; PG8_MMA(1, 0, At, B0); PG8_MMA(1, 1, At, B1); PG8_BAR; PG8_SCHED;
;     ...
;         if constexpr (ALIGN_EPI) { if (wr == 0) PG8_BAR; }
	ds_read_b128 v[188:191], v154 offset:49152
	ds_read_b128 v[192:195], v154 offset:50176
	ds_read_b128 v[196:199], v154 offset:51200
	ds_read_b128 v[200:203], v154 offset:52224
	ds_read_b128 v[206:209], v154 offset:53248
	ds_read_b128 v[210:213], v154 offset:54272
	ds_read_b128 v[214:217], v154 offset:55296
	ds_read_b128 v[218:221], v154 offset:56320
	s_add_i32 s36, s39, s47
	s_mov_b32 m0, s36
	v_lshl_add_u64 v[146:147], v[146:147], 0, s[14:15]
	global_load_lds_dwordx4 v[146:147], off
	s_add_i32 m0, s36, 0x2000
	s_add_u32 s34, s34, 0x80080
	v_lshl_add_u64 v[146:147], v[222:223], 0, s[14:15]
	s_addc_u32 s35, s35, 0
	s_add_i32 s36, s68, s47
	global_load_lds_dwordx4 v[146:147], off
	v_lshl_add_u64 v[146:147], s[34:35], 0, v[132:133]
	s_mov_b32 m0, s36
	s_nop 0
	global_load_lds_dwordx4 v[146:147], off
	v_lshl_add_u64 v[146:147], s[34:35], 0, v[128:129]
	s_add_i32 m0, s36, 0x2000
	s_nop 0
	global_load_lds_dwordx4 v[146:147], off
	v_lshl_add_u64 v[146:147], v[224:225], 0, s[14:15]
	s_mov_b32 m0, s58
	s_nop 0
	global_load_lds_dwordx4 v[146:147], off
	v_lshl_add_u64 v[146:147], v[226:227], 0, s[14:15]
	s_mov_b32 m0, s59
	s_nop 0
	global_load_lds_dwordx4 v[146:147], off
	s_waitcnt vmcnt(8)
	s_waitcnt lgkmcnt(0)
	s_barrier
	v_mfma_f32_16x16x32_bf16 v[60:63], v[156:159], v[188:191], v[60:63]
	v_mfma_f32_16x16x32_bf16 v[56:59], v[164:167], v[188:191], v[56:59]
	v_mfma_f32_16x16x32_bf16 v[52:55], v[156:159], v[196:199], v[52:55]
	v_mfma_f32_16x16x32_bf16 v[44:47], v[164:167], v[196:199], v[44:47]
	v_mfma_f32_16x16x32_bf16 v[36:39], v[156:159], v[206:209], v[36:39]
	v_mfma_f32_16x16x32_bf16 v[28:31], v[164:167], v[206:209], v[28:31]
	v_mfma_f32_16x16x32_bf16 v[20:23], v[156:159], v[214:217], v[20:23]
	v_mfma_f32_16x16x32_bf16 v[12:15], v[164:167], v[214:217], v[12:15]
	v_mfma_f32_16x16x32_bf16 v[60:63], v[160:163], v[192:195], v[60:63]
	v_mfma_f32_16x16x32_bf16 v[56:59], v[168:171], v[192:195], v[56:59]
	v_mfma_f32_16x16x32_bf16 v[52:55], v[160:163], v[200:203], v[52:55]
	v_mfma_f32_16x16x32_bf16 v[44:47], v[168:171], v[200:203], v[44:47]
	v_mfma_f32_16x16x32_bf16 v[36:39], v[160:163], v[210:213], v[36:39]
	v_mfma_f32_16x16x32_bf16 v[28:31], v[168:171], v[210:213], v[28:31]
	v_mfma_f32_16x16x32_bf16 v[20:23], v[160:163], v[218:221], v[20:23]
	v_mfma_f32_16x16x32_bf16 v[12:15], v[168:171], v[218:221], v[12:15]
	v_mfma_f32_16x16x32_bf16 v[48:51], v[172:175], v[188:191], v[48:51]
	v_mfma_f32_16x16x32_bf16 v[40:43], v[180:183], v[188:191], v[40:43]
	v_mfma_f32_16x16x32_bf16 v[32:35], v[172:175], v[196:199], v[32:35]
	v_mfma_f32_16x16x32_bf16 v[24:27], v[180:183], v[196:199], v[24:27]
	v_mfma_f32_16x16x32_bf16 v[16:19], v[172:175], v[206:209], v[16:19]
	v_mfma_f32_16x16x32_bf16 v[8:11], v[180:183], v[206:209], v[8:11]
	v_mfma_f32_16x16x32_bf16 v[4:7], v[172:175], v[214:217], v[4:7]
	v_mfma_f32_16x16x32_bf16 v[0:3], v[180:183], v[214:217], v[0:3]
	v_mfma_f32_16x16x32_bf16 v[48:51], v[176:179], v[192:195], v[48:51]
	v_mfma_f32_16x16x32_bf16 v[40:43], v[184:187], v[192:195], v[40:43]
	v_mfma_f32_16x16x32_bf16 v[32:35], v[176:179], v[200:203], v[32:35]
	v_mfma_f32_16x16x32_bf16 v[24:27], v[184:187], v[200:203], v[24:27]
	v_mfma_f32_16x16x32_bf16 v[16:19], v[176:179], v[210:213], v[16:19]
	v_mfma_f32_16x16x32_bf16 v[8:11], v[184:187], v[210:213], v[8:11]
	v_mfma_f32_16x16x32_bf16 v[4:7], v[176:179], v[218:221], v[4:7]
	v_mfma_f32_16x16x32_bf16 v[0:3], v[184:187], v[218:221], v[0:3]
	s_barrier
	s_add_i32 s38, s38, 2
	s_add_u32 s21, s21, 0x100
	s_addc_u32 s23, s23, 0
	s_add_u32 s30, s30, 0x100
	s_addc_u32 s31, s31, 0
	s_cmp_gt_u32 s38, 29
	s_cbranch_scc0 .LBB0_82
	s_and_b64 vcc, exec, s[18:19]
	s_cbranch_vccz .LBB0_85
	s_barrier

; #define PG8_STAGE(bufoff, gbase, voff) do { _Pragma("unroll") for (int _i = 0; _i < 2; ++_i) \
;         __builtin_amdgcn_global_load_lds((const unsigned*)((const char*)(gbase) + (voff)[_i]), (PG8_LAS unsigned*)(lds + (bufoff) + ldsw + _i * 8192), 16, 0, 0); } while (0)
; #define PG8_LDA(dst, b, h) do { _Pragma("unroll") for (int m = 0; m < 4; ++m) _Pragma("unroll") for (int k = 0; k < 2; ++k) dst[m][k] = *(const PG8_LAS bf16x8*)(lds + PG8_SA(b, h) + aoff + m * 2048 + k * 1024); } while (0)
; #define PG8_LDB(dst, b, h) do { _Pragma("unroll") for (int n = 0; n < 2; ++n) _Pragma("unroll") for (int k = 0; k < 2; ++k) dst[n][k] = *(const PG8_LAS bf16x8*)(lds + PG8_SB(b, h) + boff + n * 2048 + k * 1024); } while (0)
; #define PG8_MMA(ai, bj, At, Bt) do { __builtin_amdgcn_s_setprio(1); _Pragma("unroll") for (int m = 0; m < 4; ++m) _Pragma("unroll") for (int n = 0; n < 2; ++n) _Pragma("unroll") for (int k = 0; k < 2; ++k) \
;         acc[ai][bj][m][n] = __builtin_amdgcn_mfma_f32_16x16x32_bf16(Bt[n][k], At[m][k], acc[ai][bj][m][n], 0, 0, 0); __builtin_amdgcn_s_setprio(0); } while (0)
; #define PG8_WAIT_V(n) asm volatile("s_waitcnt vmcnt(" #n ")" ::: "memory")
; #define PG8_WAIT_L(n) asm volatile("s_waitcnt lgkmcnt(" #n ")" ::: "memory")
; template <class Epi, class Sched, bool ALIGN_EPI = false, bool SP2 = false>
; __device__ __forceinline__ void gemm_phase(PG8_LAS unsigned char* lds, const Gemm g, const Sched& S, const Epi& E, const int wv0) {
;     ...
;         for (int t = 0; t < nt; t += 2) {
;             const bool last = (t == nt - 2);
;             const char* a1 = cA + (size_t)(t + 1) * kstep;
;             const char* a2 = last ? nA : cA + (size_t)(t + 2) * kstep; const char* b2 = last ? nB : cB + (size_t)(t + 2) * kstep;
;             const char* a3 = a2 + kstep; const char* b3 = b2 + kstep;
;             if constexpr (SP2) {
;             PG8_LDB(B0, 0, 0); PG8_LDB(B1, 0, 1); PG8_SCHED; PG8_LDA(At, 0, 0); PG8_STAGE(PG8_SA(1, 1), a1 + hstepA, voffA);
;             PG8_WAIT_V(8); PG8_WAIT_L(0); PG8_BAR; PG8_MMA(0, 0, At, B0); PG8_MMA(0, 1, At, B1); PG8_BAR; PG8_SCHED;
;             PG8_LDA(At, 0, 1); PG8_STAGE(PG8_SB(0, 0), b2, voffB); PG8_STAGE(PG8_SB(0, 1), b2 + hstepB, voffB); PG8_STAGE(PG8_SA(0, 0), a2, voffA);
;             PG8_WAIT_V(8); PG8_WAIT_L(0); PG8_BAR; PG8_MMA(1, 0, At, B0); PG8_MMA(1, 1, At, B1); PG8_BAR; PG8_SCHED;
.LBB0_494:
	v_add_u32_e32 v158, s61, v207
	v_add_u32_e32 v174, s62, v207
	ds_read_b128 v[146:149], v158
	ds_read_b128 v[150:153], v158 offset:1024
	ds_read_b128 v[154:157], v158 offset:2048
	ds_read_b128 v[158:161], v158 offset:3072
	ds_read_b128 v[162:165], v174
	ds_read_b128 v[166:169], v174 offset:1024
	ds_read_b128 v[170:173], v174 offset:2048
	ds_read_b128 v[174:177], v174 offset:3072
	s_add_u32 s41, s38, 0xfffc0080
	s_addc_u32 s44, s39, -1
	s_cmp_eq_u32 s29, 12
	s_cselect_b32 s47, s5, s44
	s_cselect_b32 s46, s4, s41
	s_cselect_b32 s45, s37, s27
	s_cselect_b32 s44, s36, s25
	v_lshl_add_u64 v[202:203], s[38:39], 0, v[140:141]
	s_add_i32 m0, s55, 0xc000
	ds_read_b128 v[178:181], v209
	ds_read_b128 v[182:185], v209 offset:1024
	ds_read_b128 v[186:189], v209 offset:2048
	ds_read_b128 v[190:193], v209 offset:3072
	ds_read_b128 v[194:197], v209 offset:4096
	ds_read_b128 v[198:201], v209 offset:5120
	ds_read_b128 v[210:213], v209 offset:6144
	ds_read_b128 v[214:217], v209 offset:7168
	global_load_lds_dwordx4 v[202:203], off
	v_lshl_add_u64 v[202:203], s[38:39], 0, v[138:139]
	s_add_i32 m0, s55, 0xe000
	s_nop 0
	global_load_lds_dwordx4 v[202:203], off
	s_waitcnt vmcnt(8)
	s_waitcnt lgkmcnt(0)
	s_barrier
	v_mfma_f32_16x16x32_bf16 v[124:127], v[146:149], v[178:181], v[124:127]
	v_mfma_f32_16x16x32_bf16 v[120:123], v[154:157], v[178:181], v[120:123]
	v_mfma_f32_16x16x32_bf16 v[108:111], v[146:149], v[186:189], v[108:111]
	v_mfma_f32_16x16x32_bf16 v[104:107], v[154:157], v[186:189], v[104:107]
	v_mfma_f32_16x16x32_bf16 v[92:95], v[146:149], v[194:197], v[92:95]
	v_mfma_f32_16x16x32_bf16 v[88:91], v[154:157], v[194:197], v[88:91]
	v_mfma_f32_16x16x32_bf16 v[76:79], v[146:149], v[210:213], v[76:79]
	v_mfma_f32_16x16x32_bf16 v[72:75], v[154:157], v[210:213], v[72:75]
	v_mfma_f32_16x16x32_bf16 v[124:127], v[150:153], v[182:185], v[124:127]
	v_mfma_f32_16x16x32_bf16 v[120:123], v[158:161], v[182:185], v[120:123]
	v_mfma_f32_16x16x32_bf16 v[108:111], v[150:153], v[190:193], v[108:111]
	v_mfma_f32_16x16x32_bf16 v[104:107], v[158:161], v[190:193], v[104:107]
	v_mfma_f32_16x16x32_bf16 v[92:95], v[150:153], v[198:201], v[92:95]
	v_mfma_f32_16x16x32_bf16 v[88:91], v[158:161], v[198:201], v[88:91]
	v_mfma_f32_16x16x32_bf16 v[76:79], v[150:153], v[214:217], v[76:79]
	v_mfma_f32_16x16x32_bf16 v[72:75], v[158:161], v[214:217], v[72:75]
	v_mfma_f32_16x16x32_bf16 v[116:119], v[162:165], v[178:181], v[116:119]
	v_mfma_f32_16x16x32_bf16 v[112:115], v[170:173], v[178:181], v[112:115]
	v_mfma_f32_16x16x32_bf16 v[100:103], v[162:165], v[186:189], v[100:103]
	v_mfma_f32_16x16x32_bf16 v[96:99], v[170:173], v[186:189], v[96:99]
	v_mfma_f32_16x16x32_bf16 v[84:87], v[162:165], v[194:197], v[84:87]
	v_mfma_f32_16x16x32_bf16 v[80:83], v[170:173], v[194:197], v[80:83]
	v_mfma_f32_16x16x32_bf16 v[68:71], v[162:165], v[210:213], v[68:71]
	v_mfma_f32_16x16x32_bf16 v[64:67], v[170:173], v[210:213], v[64:67]
	v_mfma_f32_16x16x32_bf16 v[116:119], v[166:169], v[182:185], v[116:119]
	v_mfma_f32_16x16x32_bf16 v[112:115], v[174:177], v[182:185], v[112:115]
	v_mfma_f32_16x16x32_bf16 v[100:103], v[166:169], v[190:193], v[100:103]
	v_mfma_f32_16x16x32_bf16 v[96:99], v[174:177], v[190:193], v[96:99]
	v_mfma_f32_16x16x32_bf16 v[84:87], v[166:169], v[198:201], v[84:87]
	v_mfma_f32_16x16x32_bf16 v[80:83], v[174:177], v[198:201], v[80:83]
	v_mfma_f32_16x16x32_bf16 v[68:71], v[166:169], v[214:217], v[68:71]
	v_mfma_f32_16x16x32_bf16 v[64:67], v[174:177], v[214:217], v[64:67]
	s_barrier
	ds_read_b128 v[178:181], v209 offset:16384
	ds_read_b128 v[182:185], v209 offset:17408
	ds_read_b128 v[186:189], v209 offset:18432
	ds_read_b128 v[190:193], v209 offset:19456
	ds_read_b128 v[194:197], v209 offset:20480
	ds_read_b128 v[198:201], v209 offset:21504
	ds_read_b128 v[210:213], v209 offset:22528
	ds_read_b128 v[214:217], v209 offset:23552
	s_add_i32 s41, s61, s54
	s_mov_b32 m0, s41
	v_lshl_add_u64 v[202:203], s[44:45], 0, v[130:131]
	global_load_lds_dwordx4 v[202:203], off
	s_add_i32 m0, s41, 0x2000
	s_add_u32 s64, s44, 0x40000
	v_lshl_add_u64 v[218:219], s[44:45], 0, v[134:135]
	s_addc_u32 s65, s45, 0
	s_add_i32 s41, s62, s54
	global_load_lds_dwordx4 v[218:219], off
	v_lshl_add_u64 v[220:221], s[64:65], 0, v[130:131]
	s_mov_b32 m0, s41
	v_lshl_add_u64 v[222:223], s[46:47], 0, v[132:133]
	global_load_lds_dwordx4 v[220:221], off
	v_lshl_add_u64 v[220:221], s[64:65], 0, v[134:135]
	s_add_i32 m0, s41, 0x2000
	s_nop 0
	global_load_lds_dwordx4 v[220:221], off
	v_lshl_add_u64 v[220:221], s[46:47], 0, v[128:129]
	s_mov_b32 m0, s55
	s_nop 0
	global_load_lds_dwordx4 v[220:221], off
	s_mov_b32 m0, s56
	s_nop 0
	global_load_lds_dwordx4 v[222:223], off
	s_waitcnt vmcnt(8)
	s_waitcnt lgkmcnt(0)
	s_barrier
; #define PG8_STAGE(bufoff, gbase, voff) do { _Pragma("unroll") for (int _i = 0; _i < 2; ++_i) \
;         __builtin_amdgcn_global_load_lds((const unsigned*)((const char*)(gbase) + (voff)[_i]), (PG8_LAS unsigned*)(lds + (bufoff) + ldsw + _i * 8192), 16, 0, 0); } while (0)
; #define PG8_LDA(dst, b, h) do { _Pragma("unroll") for (int m = 0; m < 4; ++m) _Pragma("unroll") for (int k = 0; k < 2; ++k) dst[m][k] = *(const PG8_LAS bf16x8*)(lds + PG8_SA(b, h) + aoff + m * 2048 + k * 1024); } while (0)
; #define PG8_LDB(dst, b, h) do { _Pragma("unroll") for (int n = 0; n < 2; ++n) _Pragma("unroll") for (int k = 0; k < 2; ++k) dst[n][k] = *(const PG8_LAS bf16x8*)(lds + PG8_SB(b, h) + boff + n * 2048 + k * 1024); } while (0)
; #define PG8_MMA(ai, bj, At, Bt) do { __builtin_amdgcn_s_setprio(1); _Pragma("unroll") for (int m = 0; m < 4; ++m) _Pragma("unroll") for (int n = 0; n < 2; ++n) _Pragma("unroll") for (int k = 0; k < 2; ++k) \
;         acc[ai][bj][m][n] = __builtin_amdgcn_mfma_f32_16x16x32_bf16(Bt[n][k], At[m][k], acc[ai][bj][m][n], 0, 0, 0); __builtin_amdgcn_s_setprio(0); } while (0)
; #define PG8_WAIT_V(n) asm volatile("s_waitcnt vmcnt(" #n ")" ::: "memory")
; #define PG8_WAIT_L(n) asm volatile("s_waitcnt lgkmcnt(" #n ")" ::: "memory")
; #define PG8_BAR __builtin_amdgcn_s_barrier()
; #define PG8_SCHED __builtin_amdgcn_sched_barrier(0)
; template <class Epi, class Sched, bool ALIGN_EPI = false, bool SP2 = false>
; __device__ __forceinline__ void gemm_phase(PG8_LAS unsigned char* lds, const Gemm g, const Sched& S, const Epi& E, const int wv0) {
;     ...
;             PG8_WAIT_V(8); PG8_WAIT_L(0); PG8_BAR; PG8_MMA(1, 0, At, B0); PG8_MMA(1, 1, At, B1); PG8_BAR; PG8_SCHED;
;             PG8_LDB(B0, 1, 0); PG8_LDB(B1, 1, 1); PG8_SCHED; PG8_LDA(At, 1, 0); PG8_STAGE(PG8_SA(0, 1), a2 + hstepA, voffA);
;             PG8_WAIT_V(8); PG8_WAIT_L(0); PG8_BAR; PG8_MMA(0, 0, At, B0); PG8_MMA(0, 1, At, B1); PG8_BAR; PG8_SCHED;
	v_mfma_f32_16x16x32_bf16 v[60:63], v[146:149], v[178:181], v[60:63]
	v_mfma_f32_16x16x32_bf16 v[56:59], v[154:157], v[178:181], v[56:59]
	v_mfma_f32_16x16x32_bf16 v[44:47], v[146:149], v[186:189], v[44:47]
	v_mfma_f32_16x16x32_bf16 v[40:43], v[154:157], v[186:189], v[40:43]
	v_mfma_f32_16x16x32_bf16 v[28:31], v[146:149], v[194:197], v[28:31]
	v_mfma_f32_16x16x32_bf16 v[24:27], v[154:157], v[194:197], v[24:27]
	v_mfma_f32_16x16x32_bf16 v[12:15], v[146:149], v[210:213], v[12:15]
	v_mfma_f32_16x16x32_bf16 v[8:11], v[154:157], v[210:213], v[8:11]
	v_mfma_f32_16x16x32_bf16 v[60:63], v[150:153], v[182:185], v[60:63]
	v_mfma_f32_16x16x32_bf16 v[56:59], v[158:161], v[182:185], v[56:59]
	v_mfma_f32_16x16x32_bf16 v[44:47], v[150:153], v[190:193], v[44:47]
	v_mfma_f32_16x16x32_bf16 v[40:43], v[158:161], v[190:193], v[40:43]
	v_mfma_f32_16x16x32_bf16 v[28:31], v[150:153], v[198:201], v[28:31]
	v_mfma_f32_16x16x32_bf16 v[24:27], v[158:161], v[198:201], v[24:27]
	v_mfma_f32_16x16x32_bf16 v[12:15], v[150:153], v[214:217], v[12:15]
	v_mfma_f32_16x16x32_bf16 v[8:11], v[158:161], v[214:217], v[8:11]
	v_mfma_f32_16x16x32_bf16 v[52:55], v[162:165], v[178:181], v[52:55]
	v_mfma_f32_16x16x32_bf16 v[48:51], v[170:173], v[178:181], v[48:51]
	v_mfma_f32_16x16x32_bf16 v[36:39], v[162:165], v[186:189], v[36:39]
	v_mfma_f32_16x16x32_bf16 v[32:35], v[170:173], v[186:189], v[32:35]
	v_mfma_f32_16x16x32_bf16 v[20:23], v[162:165], v[194:197], v[20:23]
	v_mfma_f32_16x16x32_bf16 v[16:19], v[170:173], v[194:197], v[16:19]
	v_mfma_f32_16x16x32_bf16 v[4:7], v[162:165], v[210:213], v[4:7]
	v_mfma_f32_16x16x32_bf16 v[0:3], v[170:173], v[210:213], v[0:3]
	v_mfma_f32_16x16x32_bf16 v[52:55], v[166:169], v[182:185], v[52:55]
	v_mfma_f32_16x16x32_bf16 v[48:51], v[174:177], v[182:185], v[48:51]
	v_mfma_f32_16x16x32_bf16 v[36:39], v[166:169], v[190:193], v[36:39]
	v_mfma_f32_16x16x32_bf16 v[32:35], v[174:177], v[190:193], v[32:35]
	v_mfma_f32_16x16x32_bf16 v[20:23], v[166:169], v[198:201], v[20:23]
	v_mfma_f32_16x16x32_bf16 v[16:19], v[174:177], v[198:201], v[16:19]
	v_mfma_f32_16x16x32_bf16 v[4:7], v[166:169], v[214:217], v[4:7]
	v_mfma_f32_16x16x32_bf16 v[0:3], v[174:177], v[214:217], v[0:3]
	s_barrier
	ds_read_b128 v[178:181], v209 offset:32768
	ds_read_b128 v[182:185], v209 offset:33792
	ds_read_b128 v[186:189], v209 offset:34816
	ds_read_b128 v[190:193], v209 offset:35840
	ds_read_b128 v[194:197], v209 offset:36864
	ds_read_b128 v[198:201], v209 offset:37888
	ds_read_b128 v[210:213], v209 offset:38912
	ds_read_b128 v[214:217], v209 offset:39936
	s_add_i32 s41, 0, 0x18000
	s_add_i32 s64, 0, 0x1c000
	v_add_u32_e32 v158, s41, v207
	v_add_u32_e32 v174, s64, v207
	ds_read_b128 v[146:149], v158
	ds_read_b128 v[150:153], v158 offset:1024
	ds_read_b128 v[154:157], v158 offset:2048
	ds_read_b128 v[158:161], v158 offset:3072
	ds_read_b128 v[162:165], v174
	ds_read_b128 v[166:169], v174 offset:1024
	ds_read_b128 v[170:173], v174 offset:2048
	ds_read_b128 v[174:177], v174 offset:3072
	s_add_u32 s46, s46, 0x40000
	s_addc_u32 s47, s47, 0
	s_mov_b32 m0, s57
	v_lshl_add_u64 v[224:225], s[46:47], 0, v[128:129]
	global_load_lds_dwordx4 v[224:225], off
	v_lshl_add_u64 v[224:225], s[46:47], 0, v[132:133]
	s_mov_b32 m0, s58
	s_nop 0
	global_load_lds_dwordx4 v[224:225], off
	s_waitcnt vmcnt(8)
	s_waitcnt lgkmcnt(0)
	s_barrier
	v_mfma_f32_16x16x32_bf16 v[124:127], v[146:149], v[178:181], v[124:127]
	v_mfma_f32_16x16x32_bf16 v[120:123], v[154:157], v[178:181], v[120:123]
	v_mfma_f32_16x16x32_bf16 v[108:111], v[146:149], v[186:189], v[108:111]
	v_mfma_f32_16x16x32_bf16 v[104:107], v[154:157], v[186:189], v[104:107]
	v_mfma_f32_16x16x32_bf16 v[92:95], v[146:149], v[194:197], v[92:95]
	v_mfma_f32_16x16x32_bf16 v[88:91], v[154:157], v[194:197], v[88:91]
	v_mfma_f32_16x16x32_bf16 v[76:79], v[146:149], v[210:213], v[76:79]
	v_mfma_f32_16x16x32_bf16 v[72:75], v[154:157], v[210:213], v[72:75]
	v_mfma_f32_16x16x32_bf16 v[124:127], v[150:153], v[182:185], v[124:127]
	v_mfma_f32_16x16x32_bf16 v[120:123], v[158:161], v[182:185], v[120:123]
	v_mfma_f32_16x16x32_bf16 v[108:111], v[150:153], v[190:193], v[108:111]
	v_mfma_f32_16x16x32_bf16 v[104:107], v[158:161], v[190:193], v[104:107]
	v_mfma_f32_16x16x32_bf16 v[92:95], v[150:153], v[198:201], v[92:95]
	v_mfma_f32_16x16x32_bf16 v[88:91], v[158:161], v[198:201], v[88:91]
	v_mfma_f32_16x16x32_bf16 v[76:79], v[150:153], v[214:217], v[76:79]
	v_mfma_f32_16x16x32_bf16 v[72:75], v[158:161], v[214:217], v[72:75]
	v_mfma_f32_16x16x32_bf16 v[116:119], v[162:165], v[178:181], v[116:119]
	v_mfma_f32_16x16x32_bf16 v[112:115], v[170:173], v[178:181], v[112:115]
	v_mfma_f32_16x16x32_bf16 v[100:103], v[162:165], v[186:189], v[100:103]
	v_mfma_f32_16x16x32_bf16 v[96:99], v[170:173], v[186:189], v[96:99]
	v_mfma_f32_16x16x32_bf16 v[84:87], v[162:165], v[194:197], v[84:87]
	v_mfma_f32_16x16x32_bf16 v[80:83], v[170:173], v[194:197], v[80:83]
	v_mfma_f32_16x16x32_bf16 v[68:71], v[162:165], v[210:213], v[68:71]
	v_mfma_f32_16x16x32_bf16 v[64:67], v[170:173], v[210:213], v[64:67]
	v_mfma_f32_16x16x32_bf16 v[116:119], v[166:169], v[182:185], v[116:119]
	v_mfma_f32_16x16x32_bf16 v[112:115], v[174:177], v[182:185], v[112:115]
	v_mfma_f32_16x16x32_bf16 v[100:103], v[166:169], v[190:193], v[100:103]
	v_mfma_f32_16x16x32_bf16 v[96:99], v[174:177], v[190:193], v[96:99]
	v_mfma_f32_16x16x32_bf16 v[84:87], v[166:169], v[198:201], v[84:87]
	v_mfma_f32_16x16x32_bf16 v[80:83], v[174:177], v[198:201], v[80:83]
	v_mfma_f32_16x16x32_bf16 v[68:71], v[166:169], v[214:217], v[68:71]
	v_mfma_f32_16x16x32_bf16 v[64:67], v[174:177], v[214:217], v[64:67]
	s_barrier
; #define PG8_STAGE(bufoff, gbase, voff) do { _Pragma("unroll") for (int _i = 0; _i < 2; ++_i) \
;         __builtin_amdgcn_global_load_lds((const unsigned*)((const char*)(gbase) + (voff)[_i]), (PG8_LAS unsigned*)(lds + (bufoff) + ldsw + _i * 8192), 16, 0, 0); } while (0)
; #define PG8_LDA(dst, b, h) do { _Pragma("unroll") for (int m = 0; m < 4; ++m) _Pragma("unroll") for (int k = 0; k < 2; ++k) dst[m][k] = *(const PG8_LAS bf16x8*)(lds + PG8_SA(b, h) + aoff + m * 2048 + k * 1024); } while (0)
; #define PG8_MMA(ai, bj, At, Bt) do { __builtin_amdgcn_s_setprio(1); _Pragma("unroll") for (int m = 0; m < 4; ++m) _Pragma("unroll") for (int n = 0; n < 2; ++n) _Pragma("unroll") for (int k = 0; k < 2; ++k) \
;         acc[ai][bj][m][n] = __builtin_amdgcn_mfma_f32_16x16x32_bf16(Bt[n][k], At[m][k], acc[ai][bj][m][n], 0, 0, 0); __builtin_amdgcn_s_setprio(0); } while (0)
; #define PG8_WAIT_V(n) asm volatile("s_waitcnt vmcnt(" #n ")" ::: "memory")
; #define PG8_WAIT_L(n) asm volatile("s_waitcnt lgkmcnt(" #n ")" ::: "memory")
; #define PG8_BAR __builtin_amdgcn_s_barrier()
; #define PG8_SCHED __builtin_amdgcn_sched_barrier(0)
; template <class Epi, class Sched, bool ALIGN_EPI = false, bool SP2 = false>
; __device__ __forceinline__ void gemm_phase(PG8_LAS unsigned char* lds, const Gemm g, const Sched& S, const Epi& E, const int wv0) {
;     ...
;             PG8_LDA(At, 1, 1); PG8_STAGE(PG8_SB(1, 0), b3, voffB); PG8_STAGE(PG8_SB(1, 1), b3 + hstepB, voffB); PG8_STAGE(PG8_SA(1, 0), a3, voffA);
;             PG8_WAIT_V(8); PG8_WAIT_L(0); PG8_BAR; PG8_MMA(1, 0, At, B0); PG8_MMA(1, 1, At, B1); PG8_BAR; PG8_SCHED;
;     ...
;         if constexpr (ALIGN_EPI) { if (wr == 0) PG8_BAR; }
	s_add_i32 s41, s41, s54
	v_lshl_add_u64 v[202:203], v[202:203], 0, s[10:11]
	s_mov_b32 m0, s41
	ds_read_b128 v[178:181], v209 offset:49152
	ds_read_b128 v[182:185], v209 offset:50176
	ds_read_b128 v[186:189], v209 offset:51200
	ds_read_b128 v[190:193], v209 offset:52224
	ds_read_b128 v[194:197], v209 offset:53248
	ds_read_b128 v[198:201], v209 offset:54272
	ds_read_b128 v[210:213], v209 offset:55296
	ds_read_b128 v[214:217], v209 offset:56320
	global_load_lds_dwordx4 v[202:203], off
	s_add_i32 m0, s41, 0x2000
	s_add_u32 s44, s44, 0x40080
	v_lshl_add_u64 v[202:203], v[218:219], 0, s[10:11]
	s_addc_u32 s45, s45, 0
	s_add_i32 s41, s64, s54
	global_load_lds_dwordx4 v[202:203], off
	v_lshl_add_u64 v[202:203], s[44:45], 0, v[130:131]
	s_mov_b32 m0, s41
	s_nop 0
	global_load_lds_dwordx4 v[202:203], off
	v_lshl_add_u64 v[202:203], s[44:45], 0, v[134:135]
	s_add_i32 m0, s41, 0x2000
	s_nop 0
	global_load_lds_dwordx4 v[202:203], off
	v_lshl_add_u64 v[202:203], v[220:221], 0, s[10:11]
	s_mov_b32 m0, s59
	s_nop 0
	global_load_lds_dwordx4 v[202:203], off
	v_lshl_add_u64 v[202:203], v[222:223], 0, s[10:11]
	s_mov_b32 m0, s60
	s_nop 0
	global_load_lds_dwordx4 v[202:203], off
	s_waitcnt vmcnt(8)
	s_waitcnt lgkmcnt(0)
	s_barrier
	v_mfma_f32_16x16x32_bf16 v[60:63], v[146:149], v[178:181], v[60:63]
	v_mfma_f32_16x16x32_bf16 v[56:59], v[154:157], v[178:181], v[56:59]
	v_mfma_f32_16x16x32_bf16 v[44:47], v[146:149], v[186:189], v[44:47]
	v_mfma_f32_16x16x32_bf16 v[40:43], v[154:157], v[186:189], v[40:43]
	v_mfma_f32_16x16x32_bf16 v[28:31], v[146:149], v[194:197], v[28:31]
	v_mfma_f32_16x16x32_bf16 v[24:27], v[154:157], v[194:197], v[24:27]
	v_mfma_f32_16x16x32_bf16 v[12:15], v[146:149], v[210:213], v[12:15]
	v_mfma_f32_16x16x32_bf16 v[8:11], v[154:157], v[210:213], v[8:11]
	v_mfma_f32_16x16x32_bf16 v[60:63], v[150:153], v[182:185], v[60:63]
	v_mfma_f32_16x16x32_bf16 v[56:59], v[158:161], v[182:185], v[56:59]
	v_mfma_f32_16x16x32_bf16 v[44:47], v[150:153], v[190:193], v[44:47]
	v_mfma_f32_16x16x32_bf16 v[40:43], v[158:161], v[190:193], v[40:43]
	v_mfma_f32_16x16x32_bf16 v[28:31], v[150:153], v[198:201], v[28:31]
	v_mfma_f32_16x16x32_bf16 v[24:27], v[158:161], v[198:201], v[24:27]
	v_mfma_f32_16x16x32_bf16 v[12:15], v[150:153], v[214:217], v[12:15]
	v_mfma_f32_16x16x32_bf16 v[8:11], v[158:161], v[214:217], v[8:11]
	v_mfma_f32_16x16x32_bf16 v[52:55], v[162:165], v[178:181], v[52:55]
	v_mfma_f32_16x16x32_bf16 v[48:51], v[170:173], v[178:181], v[48:51]
	v_mfma_f32_16x16x32_bf16 v[36:39], v[162:165], v[186:189], v[36:39]
	v_mfma_f32_16x16x32_bf16 v[32:35], v[170:173], v[186:189], v[32:35]
	v_mfma_f32_16x16x32_bf16 v[20:23], v[162:165], v[194:197], v[20:23]
	v_mfma_f32_16x16x32_bf16 v[16:19], v[170:173], v[194:197], v[16:19]
	v_mfma_f32_16x16x32_bf16 v[4:7], v[162:165], v[210:213], v[4:7]
	v_mfma_f32_16x16x32_bf16 v[0:3], v[170:173], v[210:213], v[0:3]
	v_mfma_f32_16x16x32_bf16 v[52:55], v[166:169], v[182:185], v[52:55]
	v_mfma_f32_16x16x32_bf16 v[48:51], v[174:177], v[182:185], v[48:51]
	v_mfma_f32_16x16x32_bf16 v[36:39], v[166:169], v[190:193], v[36:39]
	v_mfma_f32_16x16x32_bf16 v[32:35], v[174:177], v[190:193], v[32:35]
	v_mfma_f32_16x16x32_bf16 v[20:23], v[166:169], v[198:201], v[20:23]
	v_mfma_f32_16x16x32_bf16 v[16:19], v[174:177], v[198:201], v[16:19]
	v_mfma_f32_16x16x32_bf16 v[4:7], v[166:169], v[214:217], v[4:7]
	v_mfma_f32_16x16x32_bf16 v[0:3], v[174:177], v[214:217], v[0:3]
	s_barrier
	s_add_i32 s29, s29, 2
	s_add_u32 s25, s25, 0x100
	s_addc_u32 s27, s27, 0
	s_add_u32 s38, s38, 0x100
	s_addc_u32 s39, s39, 0
	s_cmp_gt_u32 s29, 13
	s_cbranch_scc0 .LBB0_494
	s_and_b64 vcc, exec, s[12:13]
	s_cbranch_vccz .LBB0_497
	s_barrier

; #define PG8_STAGE(bufoff, gbase, voff) do { _Pragma("unroll") for (int _i = 0; _i < 2; ++_i) \
;         __builtin_amdgcn_global_load_lds((const unsigned*)((const char*)(gbase) + (voff)[_i]), (PG8_LAS unsigned*)(lds + (bufoff) + ldsw + _i * 8192), 16, 0, 0); } while (0)
; #define PG8_LDA(dst, b, h) do { _Pragma("unroll") for (int m = 0; m < 4; ++m) _Pragma("unroll") for (int k = 0; k < 2; ++k) dst[m][k] = *(const PG8_LAS bf16x8*)(lds + PG8_SA(b, h) + aoff + m * 2048 + k * 1024); } while (0)
; #define PG8_LDB(dst, b, h) do { _Pragma("unroll") for (int n = 0; n < 2; ++n) _Pragma("unroll") for (int k = 0; k < 2; ++k) dst[n][k] = *(const PG8_LAS bf16x8*)(lds + PG8_SB(b, h) + boff + n * 2048 + k * 1024); } while (0)
; #define PG8_MMA(ai, bj, At, Bt) do { __builtin_amdgcn_s_setprio(1); _Pragma("unroll") for (int m = 0; m < 4; ++m) _Pragma("unroll") for (int n = 0; n < 2; ++n) _Pragma("unroll") for (int k = 0; k < 2; ++k) \
;         acc[ai][bj][m][n] = __builtin_amdgcn_mfma_f32_16x16x32_bf16(Bt[n][k], At[m][k], acc[ai][bj][m][n], 0, 0, 0); __builtin_amdgcn_s_setprio(0); } while (0)
; #define PG8_WAIT_V(n) asm volatile("s_waitcnt vmcnt(" #n ")" ::: "memory")
; #define PG8_WAIT_L(n) asm volatile("s_waitcnt lgkmcnt(" #n ")" ::: "memory")
; template <class Epi, class Sched, bool ALIGN_EPI = false, bool SP2 = false>
; __device__ __forceinline__ void gemm_phase(PG8_LAS unsigned char* lds, const Gemm g, const Sched& S, const Epi& E, const int wv0) {
;     ...
;         for (int t = 0; t < nt; t += 2) {
;             const bool last = (t == nt - 2);
;             const char* a1 = cA + (size_t)(t + 1) * kstep;
;             const char* a2 = last ? nA : cA + (size_t)(t + 2) * kstep; const char* b2 = last ? nB : cB + (size_t)(t + 2) * kstep;
;             const char* a3 = a2 + kstep; const char* b3 = b2 + kstep;
;             if constexpr (SP2) {
;             PG8_LDB(B0, 0, 0); PG8_LDB(B1, 0, 1); PG8_SCHED; PG8_LDA(At, 0, 0); PG8_STAGE(PG8_SA(1, 1), a1 + hstepA, voffA);
;             PG8_WAIT_V(8); PG8_WAIT_L(0); PG8_BAR; PG8_MMA(0, 0, At, B0); PG8_MMA(0, 1, At, B1); PG8_BAR; PG8_SCHED;
;             PG8_LDA(At, 0, 1); PG8_STAGE(PG8_SB(0, 0), b2, voffB); PG8_STAGE(PG8_SB(0, 1), b2 + hstepB, voffB); PG8_STAGE(PG8_SA(0, 0), a2, voffA);
;             PG8_WAIT_V(8); PG8_WAIT_L(0); PG8_BAR; PG8_MMA(1, 0, At, B0); PG8_MMA(1, 1, At, B1); PG8_BAR; PG8_SCHED;
.LBB0_667:
	ds_read_b128 v[144:147], v153
	ds_read_b128 v[156:159], v153 offset:1024
	ds_read_b128 v[160:163], v153 offset:2048
	ds_read_b128 v[164:167], v153 offset:3072
	ds_read_b128 v[168:171], v154
	ds_read_b128 v[172:175], v154 offset:1024
	ds_read_b128 v[176:179], v154 offset:2048
	ds_read_b128 v[180:183], v154 offset:3072
	ds_read_b128 v[184:187], v155
	ds_read_b128 v[188:191], v155 offset:1024
	ds_read_b128 v[192:195], v155 offset:2048
	ds_read_b128 v[196:199], v155 offset:3072
	ds_read_b128 v[200:203], v155 offset:4096
	ds_read_b128 v[206:209], v155 offset:5120
	ds_read_b128 v[210:213], v155 offset:6144
	ds_read_b128 v[214:217], v155 offset:7168
	s_add_u32 s24, s22, 0xfff80080
	s_addc_u32 s25, s23, -1
	s_cmp_eq_u32 s50, 28
	s_cselect_b32 s27, s17, s25
	s_cselect_b32 s26, s16, s24
	s_cselect_b32 s25, s19, s15
	s_cselect_b32 s24, s18, s13
	s_add_i32 m0, s21, 0xc000
	v_lshl_add_u64 v[148:149], s[22:23], 0, v[138:139]
	global_load_lds_dwordx4 v[148:149], off
	v_lshl_add_u64 v[148:149], s[22:23], 0, v[136:137]
	s_add_i32 m0, s21, 0xe000
	s_nop 0
	global_load_lds_dwordx4 v[148:149], off
	s_waitcnt vmcnt(8)
	s_waitcnt lgkmcnt(0)
	s_barrier
	v_mfma_f32_16x16x32_bf16 v[124:127], v[144:147], v[184:187], v[124:127]
	v_mfma_f32_16x16x32_bf16 v[120:123], v[160:163], v[184:187], v[120:123]
	v_mfma_f32_16x16x32_bf16 v[116:119], v[144:147], v[192:195], v[116:119]
	v_mfma_f32_16x16x32_bf16 v[112:115], v[160:163], v[192:195], v[112:115]
	v_mfma_f32_16x16x32_bf16 v[92:95], v[144:147], v[200:203], v[92:95]
	v_mfma_f32_16x16x32_bf16 v[88:91], v[160:163], v[200:203], v[88:91]
	v_mfma_f32_16x16x32_bf16 v[84:87], v[144:147], v[210:213], v[84:87]
	v_mfma_f32_16x16x32_bf16 v[80:83], v[160:163], v[210:213], v[80:83]
	v_mfma_f32_16x16x32_bf16 v[124:127], v[156:159], v[188:191], v[124:127]
	v_mfma_f32_16x16x32_bf16 v[120:123], v[164:167], v[188:191], v[120:123]
	v_mfma_f32_16x16x32_bf16 v[116:119], v[156:159], v[196:199], v[116:119]
	v_mfma_f32_16x16x32_bf16 v[112:115], v[164:167], v[196:199], v[112:115]
	v_mfma_f32_16x16x32_bf16 v[92:95], v[156:159], v[206:209], v[92:95]
	v_mfma_f32_16x16x32_bf16 v[88:91], v[164:167], v[206:209], v[88:91]
	v_mfma_f32_16x16x32_bf16 v[84:87], v[156:159], v[214:217], v[84:87]
	v_mfma_f32_16x16x32_bf16 v[80:83], v[164:167], v[214:217], v[80:83]
	v_mfma_f32_16x16x32_bf16 v[108:111], v[168:171], v[184:187], v[108:111]
	v_mfma_f32_16x16x32_bf16 v[104:107], v[176:179], v[184:187], v[104:107]
	v_mfma_f32_16x16x32_bf16 v[100:103], v[168:171], v[192:195], v[100:103]
	v_mfma_f32_16x16x32_bf16 v[96:99], v[176:179], v[192:195], v[96:99]
	v_mfma_f32_16x16x32_bf16 v[76:79], v[168:171], v[200:203], v[76:79]
	v_mfma_f32_16x16x32_bf16 v[72:75], v[176:179], v[200:203], v[72:75]
	v_mfma_f32_16x16x32_bf16 v[68:71], v[168:171], v[210:213], v[68:71]
	v_mfma_f32_16x16x32_bf16 v[64:67], v[176:179], v[210:213], v[64:67]
	v_mfma_f32_16x16x32_bf16 v[108:111], v[172:175], v[188:191], v[108:111]
	v_mfma_f32_16x16x32_bf16 v[104:107], v[180:183], v[188:191], v[104:107]
	v_mfma_f32_16x16x32_bf16 v[100:103], v[172:175], v[196:199], v[100:103]
	v_mfma_f32_16x16x32_bf16 v[96:99], v[180:183], v[196:199], v[96:99]
	v_mfma_f32_16x16x32_bf16 v[76:79], v[172:175], v[206:209], v[76:79]
	v_mfma_f32_16x16x32_bf16 v[72:75], v[180:183], v[206:209], v[72:75]
	v_mfma_f32_16x16x32_bf16 v[68:71], v[172:175], v[214:217], v[68:71]
	v_mfma_f32_16x16x32_bf16 v[64:67], v[180:183], v[214:217], v[64:67]
	s_barrier
	ds_read_b128 v[184:187], v155 offset:16384
	ds_read_b128 v[188:191], v155 offset:17408
	ds_read_b128 v[192:195], v155 offset:18432
	ds_read_b128 v[196:199], v155 offset:19456
	ds_read_b128 v[200:203], v155 offset:20480
	ds_read_b128 v[206:209], v155 offset:21504
	ds_read_b128 v[210:213], v155 offset:22528
	ds_read_b128 v[214:217], v155 offset:23552
	s_add_i32 s51, s47, s37
	s_mov_b32 m0, s51
	v_lshl_add_u64 v[148:149], s[24:25], 0, v[130:131]
	global_load_lds_dwordx4 v[148:149], off
	s_add_i32 m0, s51, 0x2000
	s_add_u32 s52, s24, 0x80000
	v_lshl_add_u64 v[218:219], s[24:25], 0, v[134:135]
	s_addc_u32 s53, s25, 0
	s_add_i32 s51, s48, s37
	global_load_lds_dwordx4 v[218:219], off
	v_lshl_add_u64 v[220:221], s[52:53], 0, v[130:131]
	s_mov_b32 m0, s51
	v_lshl_add_u64 v[222:223], s[26:27], 0, v[132:133]
	global_load_lds_dwordx4 v[220:221], off
	v_lshl_add_u64 v[220:221], s[52:53], 0, v[134:135]
	s_add_i32 m0, s51, 0x2000
	s_nop 0
	global_load_lds_dwordx4 v[220:221], off
	v_lshl_add_u64 v[220:221], s[26:27], 0, v[128:129]
	s_mov_b32 m0, s21
	s_nop 0
	global_load_lds_dwordx4 v[220:221], off
	s_mov_b32 m0, s38
	s_nop 0
	global_load_lds_dwordx4 v[222:223], off
	s_waitcnt vmcnt(8)
	s_waitcnt lgkmcnt(0)
	s_barrier
; #define PG8_STAGE(bufoff, gbase, voff) do { _Pragma("unroll") for (int _i = 0; _i < 2; ++_i) \
;         __builtin_amdgcn_global_load_lds((const unsigned*)((const char*)(gbase) + (voff)[_i]), (PG8_LAS unsigned*)(lds + (bufoff) + ldsw + _i * 8192), 16, 0, 0); } while (0)
; #define PG8_LDA(dst, b, h) do { _Pragma("unroll") for (int m = 0; m < 4; ++m) _Pragma("unroll") for (int k = 0; k < 2; ++k) dst[m][k] = *(const PG8_LAS bf16x8*)(lds + PG8_SA(b, h) + aoff + m * 2048 + k * 1024); } while (0)
; #define PG8_LDB(dst, b, h) do { _Pragma("unroll") for (int n = 0; n < 2; ++n) _Pragma("unroll") for (int k = 0; k < 2; ++k) dst[n][k] = *(const PG8_LAS bf16x8*)(lds + PG8_SB(b, h) + boff + n * 2048 + k * 1024); } while (0)
; #define PG8_MMA(ai, bj, At, Bt) do { __builtin_amdgcn_s_setprio(1); _Pragma("unroll") for (int m = 0; m < 4; ++m) _Pragma("unroll") for (int n = 0; n < 2; ++n) _Pragma("unroll") for (int k = 0; k < 2; ++k) \
;         acc[ai][bj][m][n] = __builtin_amdgcn_mfma_f32_16x16x32_bf16(Bt[n][k], At[m][k], acc[ai][bj][m][n], 0, 0, 0); __builtin_amdgcn_s_setprio(0); } while (0)
; #define PG8_WAIT_V(n) asm volatile("s_waitcnt vmcnt(" #n ")" ::: "memory")
; #define PG8_WAIT_L(n) asm volatile("s_waitcnt lgkmcnt(" #n ")" ::: "memory")
; #define PG8_BAR __builtin_amdgcn_s_barrier()
; #define PG8_SCHED __builtin_amdgcn_sched_barrier(0)
; template <class Epi, class Sched, bool ALIGN_EPI = false, bool SP2 = false>
; __device__ __forceinline__ void gemm_phase(PG8_LAS unsigned char* lds, const Gemm g, const Sched& S, const Epi& E, const int wv0) {
;     ...
;             PG8_WAIT_V(8); PG8_WAIT_L(0); PG8_BAR; PG8_MMA(1, 0, At, B0); PG8_MMA(1, 1, At, B1); PG8_BAR; PG8_SCHED;
;             PG8_LDB(B0, 1, 0); PG8_LDB(B1, 1, 1); PG8_SCHED; PG8_LDA(At, 1, 0); PG8_STAGE(PG8_SA(0, 1), a2 + hstepA, voffA);
;             PG8_WAIT_V(8); PG8_WAIT_L(0); PG8_BAR; PG8_MMA(0, 0, At, B0); PG8_MMA(0, 1, At, B1); PG8_BAR; PG8_SCHED;
	v_mfma_f32_16x16x32_bf16 v[60:63], v[144:147], v[184:187], v[60:63]
	v_mfma_f32_16x16x32_bf16 v[56:59], v[160:163], v[184:187], v[56:59]
	v_mfma_f32_16x16x32_bf16 v[52:55], v[144:147], v[192:195], v[52:55]
	v_mfma_f32_16x16x32_bf16 v[48:51], v[160:163], v[192:195], v[48:51]
	v_mfma_f32_16x16x32_bf16 v[28:31], v[144:147], v[200:203], v[28:31]
	v_mfma_f32_16x16x32_bf16 v[24:27], v[160:163], v[200:203], v[24:27]
	v_mfma_f32_16x16x32_bf16 v[20:23], v[144:147], v[210:213], v[20:23]
	v_mfma_f32_16x16x32_bf16 v[16:19], v[160:163], v[210:213], v[16:19]
	v_mfma_f32_16x16x32_bf16 v[60:63], v[156:159], v[188:191], v[60:63]
	v_mfma_f32_16x16x32_bf16 v[56:59], v[164:167], v[188:191], v[56:59]
	v_mfma_f32_16x16x32_bf16 v[52:55], v[156:159], v[196:199], v[52:55]
	v_mfma_f32_16x16x32_bf16 v[48:51], v[164:167], v[196:199], v[48:51]
	v_mfma_f32_16x16x32_bf16 v[28:31], v[156:159], v[206:209], v[28:31]
	v_mfma_f32_16x16x32_bf16 v[24:27], v[164:167], v[206:209], v[24:27]
	v_mfma_f32_16x16x32_bf16 v[20:23], v[156:159], v[214:217], v[20:23]
	v_mfma_f32_16x16x32_bf16 v[16:19], v[164:167], v[214:217], v[16:19]
	v_mfma_f32_16x16x32_bf16 v[44:47], v[168:171], v[184:187], v[44:47]
	v_mfma_f32_16x16x32_bf16 v[40:43], v[176:179], v[184:187], v[40:43]
	v_mfma_f32_16x16x32_bf16 v[36:39], v[168:171], v[192:195], v[36:39]
	v_mfma_f32_16x16x32_bf16 v[32:35], v[176:179], v[192:195], v[32:35]
	v_mfma_f32_16x16x32_bf16 v[12:15], v[168:171], v[200:203], v[12:15]
	v_mfma_f32_16x16x32_bf16 v[8:11], v[176:179], v[200:203], v[8:11]
	v_mfma_f32_16x16x32_bf16 v[4:7], v[168:171], v[210:213], v[4:7]
	v_mfma_f32_16x16x32_bf16 v[0:3], v[176:179], v[210:213], v[0:3]
	v_mfma_f32_16x16x32_bf16 v[44:47], v[172:175], v[188:191], v[44:47]
	v_mfma_f32_16x16x32_bf16 v[40:43], v[180:183], v[188:191], v[40:43]
	v_mfma_f32_16x16x32_bf16 v[36:39], v[172:175], v[196:199], v[36:39]
	v_mfma_f32_16x16x32_bf16 v[32:35], v[180:183], v[196:199], v[32:35]
	v_mfma_f32_16x16x32_bf16 v[12:15], v[172:175], v[206:209], v[12:15]
	v_mfma_f32_16x16x32_bf16 v[8:11], v[180:183], v[206:209], v[8:11]
	v_mfma_f32_16x16x32_bf16 v[4:7], v[172:175], v[214:217], v[4:7]
	v_mfma_f32_16x16x32_bf16 v[0:3], v[180:183], v[214:217], v[0:3]
	s_barrier
	ds_read_b128 v[184:187], v155 offset:32768
	ds_read_b128 v[188:191], v155 offset:33792
	ds_read_b128 v[192:195], v155 offset:34816
	ds_read_b128 v[196:199], v155 offset:35840
	ds_read_b128 v[200:203], v155 offset:36864
	ds_read_b128 v[206:209], v155 offset:37888
	ds_read_b128 v[210:213], v155 offset:38912
	ds_read_b128 v[214:217], v155 offset:39936
	s_add_i32 s51, 0, 0x18000
	s_add_i32 s52, 0, 0x1c000
	v_add_u32_e32 v164, s51, v151
	v_add_u32_e32 v180, s52, v151
	ds_read_b128 v[144:147], v164
	ds_read_b128 v[156:159], v164 offset:1024
	ds_read_b128 v[160:163], v164 offset:2048
	ds_read_b128 v[164:167], v164 offset:3072
	ds_read_b128 v[168:171], v180
	ds_read_b128 v[172:175], v180 offset:1024
	ds_read_b128 v[176:179], v180 offset:2048
	ds_read_b128 v[180:183], v180 offset:3072
	s_add_u32 s26, s26, 0x80000
	s_addc_u32 s27, s27, 0
	s_mov_b32 m0, s39
	v_lshl_add_u64 v[224:225], s[26:27], 0, v[128:129]
	global_load_lds_dwordx4 v[224:225], off
	v_lshl_add_u64 v[224:225], s[26:27], 0, v[132:133]
	s_mov_b32 m0, s40
	s_nop 0
	global_load_lds_dwordx4 v[224:225], off
	s_waitcnt vmcnt(8)
	s_waitcnt lgkmcnt(0)
	s_barrier
	v_mfma_f32_16x16x32_bf16 v[124:127], v[144:147], v[184:187], v[124:127]
	v_mfma_f32_16x16x32_bf16 v[120:123], v[160:163], v[184:187], v[120:123]
	v_mfma_f32_16x16x32_bf16 v[116:119], v[144:147], v[192:195], v[116:119]
	v_mfma_f32_16x16x32_bf16 v[112:115], v[160:163], v[192:195], v[112:115]
	v_mfma_f32_16x16x32_bf16 v[92:95], v[144:147], v[200:203], v[92:95]
	v_mfma_f32_16x16x32_bf16 v[88:91], v[160:163], v[200:203], v[88:91]
	v_mfma_f32_16x16x32_bf16 v[84:87], v[144:147], v[210:213], v[84:87]
	v_mfma_f32_16x16x32_bf16 v[80:83], v[160:163], v[210:213], v[80:83]
	v_mfma_f32_16x16x32_bf16 v[124:127], v[156:159], v[188:191], v[124:127]
	v_mfma_f32_16x16x32_bf16 v[120:123], v[164:167], v[188:191], v[120:123]
	v_mfma_f32_16x16x32_bf16 v[116:119], v[156:159], v[196:199], v[116:119]
	v_mfma_f32_16x16x32_bf16 v[112:115], v[164:167], v[196:199], v[112:115]
	v_mfma_f32_16x16x32_bf16 v[92:95], v[156:159], v[206:209], v[92:95]
	v_mfma_f32_16x16x32_bf16 v[88:91], v[164:167], v[206:209], v[88:91]
	v_mfma_f32_16x16x32_bf16 v[84:87], v[156:159], v[214:217], v[84:87]
	v_mfma_f32_16x16x32_bf16 v[80:83], v[164:167], v[214:217], v[80:83]
	v_mfma_f32_16x16x32_bf16 v[108:111], v[168:171], v[184:187], v[108:111]
	v_mfma_f32_16x16x32_bf16 v[104:107], v[176:179], v[184:187], v[104:107]
	v_mfma_f32_16x16x32_bf16 v[100:103], v[168:171], v[192:195], v[100:103]
	v_mfma_f32_16x16x32_bf16 v[96:99], v[176:179], v[192:195], v[96:99]
	v_mfma_f32_16x16x32_bf16 v[76:79], v[168:171], v[200:203], v[76:79]
	v_mfma_f32_16x16x32_bf16 v[72:75], v[176:179], v[200:203], v[72:75]
	v_mfma_f32_16x16x32_bf16 v[68:71], v[168:171], v[210:213], v[68:71]
	v_mfma_f32_16x16x32_bf16 v[64:67], v[176:179], v[210:213], v[64:67]
	v_mfma_f32_16x16x32_bf16 v[108:111], v[172:175], v[188:191], v[108:111]
	v_mfma_f32_16x16x32_bf16 v[104:107], v[180:183], v[188:191], v[104:107]
	v_mfma_f32_16x16x32_bf16 v[100:103], v[172:175], v[196:199], v[100:103]
	v_mfma_f32_16x16x32_bf16 v[96:99], v[180:183], v[196:199], v[96:99]
	v_mfma_f32_16x16x32_bf16 v[76:79], v[172:175], v[206:209], v[76:79]
	v_mfma_f32_16x16x32_bf16 v[72:75], v[180:183], v[206:209], v[72:75]
	v_mfma_f32_16x16x32_bf16 v[68:71], v[172:175], v[214:217], v[68:71]
	v_mfma_f32_16x16x32_bf16 v[64:67], v[180:183], v[214:217], v[64:67]
	s_barrier
; #define PG8_STAGE(bufoff, gbase, voff) do { _Pragma("unroll") for (int _i = 0; _i < 2; ++_i) \
;         __builtin_amdgcn_global_load_lds((const unsigned*)((const char*)(gbase) + (voff)[_i]), (PG8_LAS unsigned*)(lds + (bufoff) + ldsw + _i * 8192), 16, 0, 0); } while (0)
; #define PG8_LDA(dst, b, h) do { _Pragma("unroll") for (int m = 0; m < 4; ++m) _Pragma("unroll") for (int k = 0; k < 2; ++k) dst[m][k] = *(const PG8_LAS bf16x8*)(lds + PG8_SA(b, h) + aoff + m * 2048 + k * 1024); } while (0)
; #define PG8_MMA(ai, bj, At, Bt) do { __builtin_amdgcn_s_setprio(1); _Pragma("unroll") for (int m = 0; m < 4; ++m) _Pragma("unroll") for (int n = 0; n < 2; ++n) _Pragma("unroll") for (int k = 0; k < 2; ++k) \
;         acc[ai][bj][m][n] = __builtin_amdgcn_mfma_f32_16x16x32_bf16(Bt[n][k], At[m][k], acc[ai][bj][m][n], 0, 0, 0); __builtin_amdgcn_s_setprio(0); } while (0)
; #define PG8_WAIT_V(n) asm volatile("s_waitcnt vmcnt(" #n ")" ::: "memory")
; #define PG8_WAIT_L(n) asm volatile("s_waitcnt lgkmcnt(" #n ")" ::: "memory")
; #define PG8_BAR __builtin_amdgcn_s_barrier()
; #define PG8_SCHED __builtin_amdgcn_sched_barrier(0)
; template <class Epi, class Sched, bool ALIGN_EPI = false, bool SP2 = false>
; __device__ __forceinline__ void gemm_phase(PG8_LAS unsigned char* lds, const Gemm g, const Sched& S, const Epi& E, const int wv0) {
;     ...
;             PG8_LDA(At, 1, 1); PG8_STAGE(PG8_SB(1, 0), b3, voffB); PG8_STAGE(PG8_SB(1, 1), b3 + hstepB, voffB); PG8_STAGE(PG8_SA(1, 0), a3, voffA);
;             PG8_WAIT_V(8); PG8_WAIT_L(0); PG8_BAR; PG8_MMA(1, 0, At, B0); PG8_MMA(1, 1, At, B1); PG8_BAR; PG8_SCHED;
;     ...
;         if constexpr (ALIGN_EPI) { if (wr == 0) PG8_BAR; }
	ds_read_b128 v[184:187], v155 offset:49152
	ds_read_b128 v[188:191], v155 offset:50176
	ds_read_b128 v[192:195], v155 offset:51200
	ds_read_b128 v[196:199], v155 offset:52224
	ds_read_b128 v[200:203], v155 offset:53248
	ds_read_b128 v[206:209], v155 offset:54272
	ds_read_b128 v[210:213], v155 offset:55296
	ds_read_b128 v[214:217], v155 offset:56320
	s_add_i32 s26, s51, s37
	s_mov_b32 m0, s26
	v_lshl_add_u64 v[148:149], v[148:149], 0, s[8:9]
	global_load_lds_dwordx4 v[148:149], off
	s_add_i32 m0, s26, 0x2000
	s_add_u32 s24, s24, 0x80080
	v_lshl_add_u64 v[148:149], v[218:219], 0, s[8:9]
	s_addc_u32 s25, s25, 0
	s_add_i32 s26, s52, s37
	global_load_lds_dwordx4 v[148:149], off
	v_lshl_add_u64 v[148:149], s[24:25], 0, v[130:131]
	s_mov_b32 m0, s26
	s_nop 0
	global_load_lds_dwordx4 v[148:149], off
	v_lshl_add_u64 v[148:149], s[24:25], 0, v[134:135]
	s_add_i32 m0, s26, 0x2000
	s_nop 0
	global_load_lds_dwordx4 v[148:149], off
	v_lshl_add_u64 v[148:149], v[220:221], 0, s[8:9]
	s_mov_b32 m0, s44
	s_nop 0
	global_load_lds_dwordx4 v[148:149], off
	v_lshl_add_u64 v[148:149], v[222:223], 0, s[8:9]
	s_mov_b32 m0, s45
	s_nop 0
	global_load_lds_dwordx4 v[148:149], off
	s_waitcnt vmcnt(8)
	s_waitcnt lgkmcnt(0)
	s_barrier
	v_mfma_f32_16x16x32_bf16 v[60:63], v[144:147], v[184:187], v[60:63]
	v_mfma_f32_16x16x32_bf16 v[56:59], v[160:163], v[184:187], v[56:59]
	v_mfma_f32_16x16x32_bf16 v[52:55], v[144:147], v[192:195], v[52:55]
	v_mfma_f32_16x16x32_bf16 v[48:51], v[160:163], v[192:195], v[48:51]
	v_mfma_f32_16x16x32_bf16 v[28:31], v[144:147], v[200:203], v[28:31]
	v_mfma_f32_16x16x32_bf16 v[24:27], v[160:163], v[200:203], v[24:27]
	v_mfma_f32_16x16x32_bf16 v[20:23], v[144:147], v[210:213], v[20:23]
	v_mfma_f32_16x16x32_bf16 v[16:19], v[160:163], v[210:213], v[16:19]
	v_mfma_f32_16x16x32_bf16 v[60:63], v[156:159], v[188:191], v[60:63]
	v_mfma_f32_16x16x32_bf16 v[56:59], v[164:167], v[188:191], v[56:59]
	v_mfma_f32_16x16x32_bf16 v[52:55], v[156:159], v[196:199], v[52:55]
	v_mfma_f32_16x16x32_bf16 v[48:51], v[164:167], v[196:199], v[48:51]
	v_mfma_f32_16x16x32_bf16 v[28:31], v[156:159], v[206:209], v[28:31]
	v_mfma_f32_16x16x32_bf16 v[24:27], v[164:167], v[206:209], v[24:27]
	v_mfma_f32_16x16x32_bf16 v[20:23], v[156:159], v[214:217], v[20:23]
	v_mfma_f32_16x16x32_bf16 v[16:19], v[164:167], v[214:217], v[16:19]
	v_mfma_f32_16x16x32_bf16 v[44:47], v[168:171], v[184:187], v[44:47]
	v_mfma_f32_16x16x32_bf16 v[40:43], v[176:179], v[184:187], v[40:43]
	v_mfma_f32_16x16x32_bf16 v[36:39], v[168:171], v[192:195], v[36:39]
	v_mfma_f32_16x16x32_bf16 v[32:35], v[176:179], v[192:195], v[32:35]
	v_mfma_f32_16x16x32_bf16 v[12:15], v[168:171], v[200:203], v[12:15]
	v_mfma_f32_16x16x32_bf16 v[8:11], v[176:179], v[200:203], v[8:11]
	v_mfma_f32_16x16x32_bf16 v[4:7], v[168:171], v[210:213], v[4:7]
	v_mfma_f32_16x16x32_bf16 v[0:3], v[176:179], v[210:213], v[0:3]
	v_mfma_f32_16x16x32_bf16 v[44:47], v[172:175], v[188:191], v[44:47]
	v_mfma_f32_16x16x32_bf16 v[40:43], v[180:183], v[188:191], v[40:43]
	v_mfma_f32_16x16x32_bf16 v[36:39], v[172:175], v[196:199], v[36:39]
	v_mfma_f32_16x16x32_bf16 v[32:35], v[180:183], v[196:199], v[32:35]
	v_mfma_f32_16x16x32_bf16 v[12:15], v[172:175], v[206:209], v[12:15]
	v_mfma_f32_16x16x32_bf16 v[8:11], v[180:183], v[206:209], v[8:11]
	v_mfma_f32_16x16x32_bf16 v[4:7], v[172:175], v[214:217], v[4:7]
	v_mfma_f32_16x16x32_bf16 v[0:3], v[180:183], v[214:217], v[0:3]
	s_barrier
	s_add_i32 s50, s50, 2
	s_add_u32 s13, s13, 0x100
	s_addc_u32 s15, s15, 0
	s_add_u32 s22, s22, 0x100
	s_addc_u32 s23, s23, 0
	s_cmp_gt_u32 s50, 29
	s_cbranch_scc0 .LBB0_667
	s_and_b64 vcc, exec, s[10:11]
	s_cbranch_vccz .LBB0_670
	s_barrier

; #define PG8_STAGE(bufoff, gbase, voff) do { _Pragma("unroll") for (int _i = 0; _i < 2; ++_i) \
;         __builtin_amdgcn_global_load_lds((const unsigned*)((const char*)(gbase) + (voff)[_i]), (PG8_LAS unsigned*)(lds + (bufoff) + ldsw + _i * 8192), 16, 0, 0); } while (0)
; #define PG8_LDA(dst, b, h) do { _Pragma("unroll") for (int m = 0; m < 4; ++m) _Pragma("unroll") for (int k = 0; k < 2; ++k) dst[m][k] = *(const PG8_LAS bf16x8*)(lds + PG8_SA(b, h) + aoff + m * 2048 + k * 1024); } while (0)
; #define PG8_LDB(dst, b, h) do { _Pragma("unroll") for (int n = 0; n < 2; ++n) _Pragma("unroll") for (int k = 0; k < 2; ++k) dst[n][k] = *(const PG8_LAS bf16x8*)(lds + PG8_SB(b, h) + boff + n * 2048 + k * 1024); } while (0)
; #define PG8_MMA(ai, bj, At, Bt) do { __builtin_amdgcn_s_setprio(1); _Pragma("unroll") for (int m = 0; m < 4; ++m) _Pragma("unroll") for (int n = 0; n < 2; ++n) _Pragma("unroll") for (int k = 0; k < 2; ++k) \
;         acc[ai][bj][m][n] = __builtin_amdgcn_mfma_f32_16x16x32_bf16(Bt[n][k], At[m][k], acc[ai][bj][m][n], 0, 0, 0); __builtin_amdgcn_s_setprio(0); } while (0)
; #define PG8_WAIT_V(n) asm volatile("s_waitcnt vmcnt(" #n ")" ::: "memory")
; #define PG8_WAIT_L(n) asm volatile("s_waitcnt lgkmcnt(" #n ")" ::: "memory")
; template <class Epi, class Sched, bool ALIGN_EPI = false, bool SP2 = false>
; __device__ __forceinline__ void gemm_phase(PG8_LAS unsigned char* lds, const Gemm g, const Sched& S, const Epi& E, const int wv0) {
;     ...
;         for (int t = 0; t < nt; t += 2) {
;             const bool last = (t == nt - 2);
;             const char* a1 = cA + (size_t)(t + 1) * kstep;
;             const char* a2 = last ? nA : cA + (size_t)(t + 2) * kstep; const char* b2 = last ? nB : cB + (size_t)(t + 2) * kstep;
;             const char* a3 = a2 + kstep; const char* b3 = b2 + kstep;
;             if constexpr (SP2) {
;             PG8_LDB(B0, 0, 0); PG8_LDB(B1, 0, 1); PG8_SCHED; PG8_LDA(At, 0, 0); PG8_STAGE(PG8_SA(1, 1), a1 + hstepA, voffA);
;             PG8_WAIT_V(8); PG8_WAIT_L(0); PG8_BAR; PG8_MMA(0, 0, At, B0); PG8_MMA(0, 1, At, B1); PG8_BAR; PG8_SCHED;
;             PG8_LDA(At, 0, 1); PG8_STAGE(PG8_SB(0, 0), b2, voffB); PG8_STAGE(PG8_SB(0, 1), b2 + hstepB, voffB); PG8_STAGE(PG8_SA(0, 0), a2, voffA);
;             PG8_WAIT_V(8); PG8_WAIT_L(0); PG8_BAR; PG8_MMA(1, 0, At, B0); PG8_MMA(1, 1, At, B1); PG8_BAR; PG8_SCHED;
.LBB0_790:
	ds_read_b128 v[152:155], v149
	ds_read_b128 v[156:159], v149 offset:1024
	ds_read_b128 v[160:163], v149 offset:2048
	ds_read_b128 v[164:167], v149 offset:3072
	ds_read_b128 v[168:171], v150
	ds_read_b128 v[172:175], v150 offset:1024
	ds_read_b128 v[176:179], v150 offset:2048
	ds_read_b128 v[180:183], v150 offset:3072
	ds_read_b128 v[184:187], v151
	ds_read_b128 v[188:191], v151 offset:1024
	ds_read_b128 v[192:195], v151 offset:2048
	ds_read_b128 v[196:199], v151 offset:3072
	ds_read_b128 v[200:203], v151 offset:4096
	ds_read_b128 v[206:209], v151 offset:5120
	ds_read_b128 v[210:213], v151 offset:6144
	ds_read_b128 v[214:217], v151 offset:7168
	s_add_u32 s22, s20, 0xfff80080
	s_addc_u32 s23, s21, -1
	s_cmp_eq_u32 s50, 28
	s_cselect_b32 s25, s15, s23
	s_cselect_b32 s24, s14, s22
	s_cselect_b32 s23, s17, s13
	s_cselect_b32 s22, s16, s11
	s_add_i32 m0, s19, 0xc000
	v_lshl_add_u64 v[144:145], s[20:21], 0, v[138:139]
	global_load_lds_dwordx4 v[144:145], off
	v_lshl_add_u64 v[144:145], s[20:21], 0, v[136:137]
	s_add_i32 m0, s19, 0xe000
	s_nop 0
	global_load_lds_dwordx4 v[144:145], off
	s_waitcnt vmcnt(8)
	s_waitcnt lgkmcnt(0)
	s_barrier
	v_mfma_f32_16x16x32_bf16 v[124:127], v[152:155], v[184:187], v[124:127]
	v_mfma_f32_16x16x32_bf16 v[120:123], v[160:163], v[184:187], v[120:123]
	v_mfma_f32_16x16x32_bf16 v[108:111], v[152:155], v[192:195], v[108:111]
	v_mfma_f32_16x16x32_bf16 v[104:107], v[160:163], v[192:195], v[104:107]
	v_mfma_f32_16x16x32_bf16 v[92:95], v[152:155], v[200:203], v[92:95]
	v_mfma_f32_16x16x32_bf16 v[88:91], v[160:163], v[200:203], v[88:91]
	v_mfma_f32_16x16x32_bf16 v[76:79], v[152:155], v[210:213], v[76:79]
	v_mfma_f32_16x16x32_bf16 v[72:75], v[160:163], v[210:213], v[72:75]
	v_mfma_f32_16x16x32_bf16 v[124:127], v[156:159], v[188:191], v[124:127]
	v_mfma_f32_16x16x32_bf16 v[120:123], v[164:167], v[188:191], v[120:123]
	v_mfma_f32_16x16x32_bf16 v[108:111], v[156:159], v[196:199], v[108:111]
	v_mfma_f32_16x16x32_bf16 v[104:107], v[164:167], v[196:199], v[104:107]
	v_mfma_f32_16x16x32_bf16 v[92:95], v[156:159], v[206:209], v[92:95]
	v_mfma_f32_16x16x32_bf16 v[88:91], v[164:167], v[206:209], v[88:91]
	v_mfma_f32_16x16x32_bf16 v[76:79], v[156:159], v[214:217], v[76:79]
	v_mfma_f32_16x16x32_bf16 v[72:75], v[164:167], v[214:217], v[72:75]
	v_mfma_f32_16x16x32_bf16 v[116:119], v[168:171], v[184:187], v[116:119]
	v_mfma_f32_16x16x32_bf16 v[112:115], v[176:179], v[184:187], v[112:115]
	v_mfma_f32_16x16x32_bf16 v[100:103], v[168:171], v[192:195], v[100:103]
	v_mfma_f32_16x16x32_bf16 v[96:99], v[176:179], v[192:195], v[96:99]
	v_mfma_f32_16x16x32_bf16 v[84:87], v[168:171], v[200:203], v[84:87]
	v_mfma_f32_16x16x32_bf16 v[80:83], v[176:179], v[200:203], v[80:83]
	v_mfma_f32_16x16x32_bf16 v[68:71], v[168:171], v[210:213], v[68:71]
	v_mfma_f32_16x16x32_bf16 v[64:67], v[176:179], v[210:213], v[64:67]
	v_mfma_f32_16x16x32_bf16 v[116:119], v[172:175], v[188:191], v[116:119]
	v_mfma_f32_16x16x32_bf16 v[112:115], v[180:183], v[188:191], v[112:115]
	v_mfma_f32_16x16x32_bf16 v[100:103], v[172:175], v[196:199], v[100:103]
	v_mfma_f32_16x16x32_bf16 v[96:99], v[180:183], v[196:199], v[96:99]
	v_mfma_f32_16x16x32_bf16 v[84:87], v[172:175], v[206:209], v[84:87]
	v_mfma_f32_16x16x32_bf16 v[80:83], v[180:183], v[206:209], v[80:83]
	v_mfma_f32_16x16x32_bf16 v[68:71], v[172:175], v[214:217], v[68:71]
	v_mfma_f32_16x16x32_bf16 v[64:67], v[180:183], v[214:217], v[64:67]
	s_barrier
	ds_read_b128 v[184:187], v151 offset:16384
	ds_read_b128 v[188:191], v151 offset:17408
	ds_read_b128 v[192:195], v151 offset:18432
	ds_read_b128 v[196:199], v151 offset:19456
	ds_read_b128 v[200:203], v151 offset:20480
	ds_read_b128 v[206:209], v151 offset:21504
	ds_read_b128 v[210:213], v151 offset:22528
	ds_read_b128 v[214:217], v151 offset:23552
	s_add_i32 s51, s46, s35
	s_mov_b32 m0, s51
	v_lshl_add_u64 v[144:145], s[22:23], 0, v[132:133]
	global_load_lds_dwordx4 v[144:145], off
	s_add_i32 m0, s51, 0x2000
	s_add_u32 s52, s22, 0x80000
	v_lshl_add_u64 v[218:219], s[22:23], 0, v[128:129]
	s_addc_u32 s53, s23, 0
	s_add_i32 s51, s47, s35
	global_load_lds_dwordx4 v[218:219], off
	v_lshl_add_u64 v[220:221], s[52:53], 0, v[132:133]
	s_mov_b32 m0, s51
	v_lshl_add_u64 v[222:223], s[24:25], 0, v[130:131]
	global_load_lds_dwordx4 v[220:221], off
	v_lshl_add_u64 v[220:221], s[52:53], 0, v[128:129]
	s_add_i32 m0, s51, 0x2000
	s_nop 0
	global_load_lds_dwordx4 v[220:221], off
	v_lshl_add_u64 v[220:221], s[24:25], 0, v[134:135]
	s_mov_b32 m0, s19
	s_nop 0
	global_load_lds_dwordx4 v[220:221], off
	s_mov_b32 m0, s37
	s_nop 0
	global_load_lds_dwordx4 v[222:223], off
	s_waitcnt vmcnt(8)
	s_waitcnt lgkmcnt(0)
	s_barrier
; #define PG8_STAGE(bufoff, gbase, voff) do { _Pragma("unroll") for (int _i = 0; _i < 2; ++_i) \
;         __builtin_amdgcn_global_load_lds((const unsigned*)((const char*)(gbase) + (voff)[_i]), (PG8_LAS unsigned*)(lds + (bufoff) + ldsw + _i * 8192), 16, 0, 0); } while (0)
; #define PG8_LDA(dst, b, h) do { _Pragma("unroll") for (int m = 0; m < 4; ++m) _Pragma("unroll") for (int k = 0; k < 2; ++k) dst[m][k] = *(const PG8_LAS bf16x8*)(lds + PG8_SA(b, h) + aoff + m * 2048 + k * 1024); } while (0)
; #define PG8_LDB(dst, b, h) do { _Pragma("unroll") for (int n = 0; n < 2; ++n) _Pragma("unroll") for (int k = 0; k < 2; ++k) dst[n][k] = *(const PG8_LAS bf16x8*)(lds + PG8_SB(b, h) + boff + n * 2048 + k * 1024); } while (0)
; #define PG8_MMA(ai, bj, At, Bt) do { __builtin_amdgcn_s_setprio(1); _Pragma("unroll") for (int m = 0; m < 4; ++m) _Pragma("unroll") for (int n = 0; n < 2; ++n) _Pragma("unroll") for (int k = 0; k < 2; ++k) \
;         acc[ai][bj][m][n] = __builtin_amdgcn_mfma_f32_16x16x32_bf16(Bt[n][k], At[m][k], acc[ai][bj][m][n], 0, 0, 0); __builtin_amdgcn_s_setprio(0); } while (0)
; #define PG8_WAIT_V(n) asm volatile("s_waitcnt vmcnt(" #n ")" ::: "memory")
; #define PG8_WAIT_L(n) asm volatile("s_waitcnt lgkmcnt(" #n ")" ::: "memory")
; #define PG8_BAR __builtin_amdgcn_s_barrier()
; #define PG8_SCHED __builtin_amdgcn_sched_barrier(0)
; template <class Epi, class Sched, bool ALIGN_EPI = false, bool SP2 = false>
; __device__ __forceinline__ void gemm_phase(PG8_LAS unsigned char* lds, const Gemm g, const Sched& S, const Epi& E, const int wv0) {
;     ...
;             PG8_WAIT_V(8); PG8_WAIT_L(0); PG8_BAR; PG8_MMA(1, 0, At, B0); PG8_MMA(1, 1, At, B1); PG8_BAR; PG8_SCHED;
;             PG8_LDB(B0, 1, 0); PG8_LDB(B1, 1, 1); PG8_SCHED; PG8_LDA(At, 1, 0); PG8_STAGE(PG8_SA(0, 1), a2 + hstepA, voffA);
;             PG8_WAIT_V(8); PG8_WAIT_L(0); PG8_BAR; PG8_MMA(0, 0, At, B0); PG8_MMA(0, 1, At, B1); PG8_BAR; PG8_SCHED;
	v_mfma_f32_16x16x32_bf16 v[60:63], v[152:155], v[184:187], v[60:63]
	v_mfma_f32_16x16x32_bf16 v[56:59], v[160:163], v[184:187], v[56:59]
	v_mfma_f32_16x16x32_bf16 v[44:47], v[152:155], v[192:195], v[44:47]
	v_mfma_f32_16x16x32_bf16 v[40:43], v[160:163], v[192:195], v[40:43]
	v_mfma_f32_16x16x32_bf16 v[28:31], v[152:155], v[200:203], v[28:31]
	v_mfma_f32_16x16x32_bf16 v[24:27], v[160:163], v[200:203], v[24:27]
	v_mfma_f32_16x16x32_bf16 v[12:15], v[152:155], v[210:213], v[12:15]
	v_mfma_f32_16x16x32_bf16 v[8:11], v[160:163], v[210:213], v[8:11]
	v_mfma_f32_16x16x32_bf16 v[60:63], v[156:159], v[188:191], v[60:63]
	v_mfma_f32_16x16x32_bf16 v[56:59], v[164:167], v[188:191], v[56:59]
	v_mfma_f32_16x16x32_bf16 v[44:47], v[156:159], v[196:199], v[44:47]
	v_mfma_f32_16x16x32_bf16 v[40:43], v[164:167], v[196:199], v[40:43]
	v_mfma_f32_16x16x32_bf16 v[28:31], v[156:159], v[206:209], v[28:31]
	v_mfma_f32_16x16x32_bf16 v[24:27], v[164:167], v[206:209], v[24:27]
	v_mfma_f32_16x16x32_bf16 v[12:15], v[156:159], v[214:217], v[12:15]
	v_mfma_f32_16x16x32_bf16 v[8:11], v[164:167], v[214:217], v[8:11]
	v_mfma_f32_16x16x32_bf16 v[52:55], v[168:171], v[184:187], v[52:55]
	v_mfma_f32_16x16x32_bf16 v[48:51], v[176:179], v[184:187], v[48:51]
	v_mfma_f32_16x16x32_bf16 v[36:39], v[168:171], v[192:195], v[36:39]
	v_mfma_f32_16x16x32_bf16 v[32:35], v[176:179], v[192:195], v[32:35]
	v_mfma_f32_16x16x32_bf16 v[20:23], v[168:171], v[200:203], v[20:23]
	v_mfma_f32_16x16x32_bf16 v[16:19], v[176:179], v[200:203], v[16:19]
	v_mfma_f32_16x16x32_bf16 v[4:7], v[168:171], v[210:213], v[4:7]
	v_mfma_f32_16x16x32_bf16 v[0:3], v[176:179], v[210:213], v[0:3]
	v_mfma_f32_16x16x32_bf16 v[52:55], v[172:175], v[188:191], v[52:55]
	v_mfma_f32_16x16x32_bf16 v[48:51], v[180:183], v[188:191], v[48:51]
	v_mfma_f32_16x16x32_bf16 v[36:39], v[172:175], v[196:199], v[36:39]
	v_mfma_f32_16x16x32_bf16 v[32:35], v[180:183], v[196:199], v[32:35]
	v_mfma_f32_16x16x32_bf16 v[20:23], v[172:175], v[206:209], v[20:23]
	v_mfma_f32_16x16x32_bf16 v[16:19], v[180:183], v[206:209], v[16:19]
	v_mfma_f32_16x16x32_bf16 v[4:7], v[172:175], v[214:217], v[4:7]
	v_mfma_f32_16x16x32_bf16 v[0:3], v[180:183], v[214:217], v[0:3]
	s_barrier
	ds_read_b128 v[184:187], v151 offset:32768
	ds_read_b128 v[188:191], v151 offset:33792
	ds_read_b128 v[192:195], v151 offset:34816
	ds_read_b128 v[196:199], v151 offset:35840
	ds_read_b128 v[200:203], v151 offset:36864
	ds_read_b128 v[206:209], v151 offset:37888
	ds_read_b128 v[210:213], v151 offset:38912
	ds_read_b128 v[214:217], v151 offset:39936
	s_add_i32 s51, 0, 0x18000
	s_add_i32 s52, 0, 0x1c000
	v_add_u32_e32 v164, s51, v147
	v_add_u32_e32 v180, s52, v147
	ds_read_b128 v[152:155], v164
	ds_read_b128 v[156:159], v164 offset:1024
	ds_read_b128 v[160:163], v164 offset:2048
	ds_read_b128 v[164:167], v164 offset:3072
	ds_read_b128 v[168:171], v180
	ds_read_b128 v[172:175], v180 offset:1024
	ds_read_b128 v[176:179], v180 offset:2048
	ds_read_b128 v[180:183], v180 offset:3072
	s_add_u32 s24, s24, 0x80000
	s_addc_u32 s25, s25, 0
	s_mov_b32 m0, s38
	v_lshl_add_u64 v[224:225], s[24:25], 0, v[134:135]
	global_load_lds_dwordx4 v[224:225], off
	v_lshl_add_u64 v[224:225], s[24:25], 0, v[130:131]
	s_mov_b32 m0, s39
	s_nop 0
	global_load_lds_dwordx4 v[224:225], off
	s_waitcnt vmcnt(8)
	s_waitcnt lgkmcnt(0)
	s_barrier
	v_mfma_f32_16x16x32_bf16 v[124:127], v[152:155], v[184:187], v[124:127]
	v_mfma_f32_16x16x32_bf16 v[120:123], v[160:163], v[184:187], v[120:123]
	v_mfma_f32_16x16x32_bf16 v[108:111], v[152:155], v[192:195], v[108:111]
	v_mfma_f32_16x16x32_bf16 v[104:107], v[160:163], v[192:195], v[104:107]
	v_mfma_f32_16x16x32_bf16 v[92:95], v[152:155], v[200:203], v[92:95]
	v_mfma_f32_16x16x32_bf16 v[88:91], v[160:163], v[200:203], v[88:91]
	v_mfma_f32_16x16x32_bf16 v[76:79], v[152:155], v[210:213], v[76:79]
	v_mfma_f32_16x16x32_bf16 v[72:75], v[160:163], v[210:213], v[72:75]
	v_mfma_f32_16x16x32_bf16 v[124:127], v[156:159], v[188:191], v[124:127]
	v_mfma_f32_16x16x32_bf16 v[120:123], v[164:167], v[188:191], v[120:123]
	v_mfma_f32_16x16x32_bf16 v[108:111], v[156:159], v[196:199], v[108:111]
	v_mfma_f32_16x16x32_bf16 v[104:107], v[164:167], v[196:199], v[104:107]
	v_mfma_f32_16x16x32_bf16 v[92:95], v[156:159], v[206:209], v[92:95]
	v_mfma_f32_16x16x32_bf16 v[88:91], v[164:167], v[206:209], v[88:91]
	v_mfma_f32_16x16x32_bf16 v[76:79], v[156:159], v[214:217], v[76:79]
	v_mfma_f32_16x16x32_bf16 v[72:75], v[164:167], v[214:217], v[72:75]
	v_mfma_f32_16x16x32_bf16 v[116:119], v[168:171], v[184:187], v[116:119]
	v_mfma_f32_16x16x32_bf16 v[112:115], v[176:179], v[184:187], v[112:115]
	v_mfma_f32_16x16x32_bf16 v[100:103], v[168:171], v[192:195], v[100:103]
	v_mfma_f32_16x16x32_bf16 v[96:99], v[176:179], v[192:195], v[96:99]
	v_mfma_f32_16x16x32_bf16 v[84:87], v[168:171], v[200:203], v[84:87]
	v_mfma_f32_16x16x32_bf16 v[80:83], v[176:179], v[200:203], v[80:83]
	v_mfma_f32_16x16x32_bf16 v[68:71], v[168:171], v[210:213], v[68:71]
	v_mfma_f32_16x16x32_bf16 v[64:67], v[176:179], v[210:213], v[64:67]
	v_mfma_f32_16x16x32_bf16 v[116:119], v[172:175], v[188:191], v[116:119]
	v_mfma_f32_16x16x32_bf16 v[112:115], v[180:183], v[188:191], v[112:115]
	v_mfma_f32_16x16x32_bf16 v[100:103], v[172:175], v[196:199], v[100:103]
	v_mfma_f32_16x16x32_bf16 v[96:99], v[180:183], v[196:199], v[96:99]
	v_mfma_f32_16x16x32_bf16 v[84:87], v[172:175], v[206:209], v[84:87]
	v_mfma_f32_16x16x32_bf16 v[80:83], v[180:183], v[206:209], v[80:83]
	v_mfma_f32_16x16x32_bf16 v[68:71], v[172:175], v[214:217], v[68:71]
	v_mfma_f32_16x16x32_bf16 v[64:67], v[180:183], v[214:217], v[64:67]
	s_barrier
; #define PG8_STAGE(bufoff, gbase, voff) do { _Pragma("unroll") for (int _i = 0; _i < 2; ++_i) \
;         __builtin_amdgcn_global_load_lds((const unsigned*)((const char*)(gbase) + (voff)[_i]), (PG8_LAS unsigned*)(lds + (bufoff) + ldsw + _i * 8192), 16, 0, 0); } while (0)
; #define PG8_LDA(dst, b, h) do { _Pragma("unroll") for (int m = 0; m < 4; ++m) _Pragma("unroll") for (int k = 0; k < 2; ++k) dst[m][k] = *(const PG8_LAS bf16x8*)(lds + PG8_SA(b, h) + aoff + m * 2048 + k * 1024); } while (0)
; #define PG8_MMA(ai, bj, At, Bt) do { __builtin_amdgcn_s_setprio(1); _Pragma("unroll") for (int m = 0; m < 4; ++m) _Pragma("unroll") for (int n = 0; n < 2; ++n) _Pragma("unroll") for (int k = 0; k < 2; ++k) \
;         acc[ai][bj][m][n] = __builtin_amdgcn_mfma_f32_16x16x32_bf16(Bt[n][k], At[m][k], acc[ai][bj][m][n], 0, 0, 0); __builtin_amdgcn_s_setprio(0); } while (0)
; #define PG8_WAIT_V(n) asm volatile("s_waitcnt vmcnt(" #n ")" ::: "memory")
; #define PG8_WAIT_L(n) asm volatile("s_waitcnt lgkmcnt(" #n ")" ::: "memory")
; #define PG8_BAR __builtin_amdgcn_s_barrier()
; #define PG8_SCHED __builtin_amdgcn_sched_barrier(0)
; template <class Epi, class Sched, bool ALIGN_EPI = false, bool SP2 = false>
; __device__ __forceinline__ void gemm_phase(PG8_LAS unsigned char* lds, const Gemm g, const Sched& S, const Epi& E, const int wv0) {
;     ...
;             PG8_LDA(At, 1, 1); PG8_STAGE(PG8_SB(1, 0), b3, voffB); PG8_STAGE(PG8_SB(1, 1), b3 + hstepB, voffB); PG8_STAGE(PG8_SA(1, 0), a3, voffA);
;             PG8_WAIT_V(8); PG8_WAIT_L(0); PG8_BAR; PG8_MMA(1, 0, At, B0); PG8_MMA(1, 1, At, B1); PG8_BAR; PG8_SCHED;
;     ...
;         if constexpr (ALIGN_EPI) { if (wr == 0) PG8_BAR; }
	ds_read_b128 v[184:187], v151 offset:49152
	ds_read_b128 v[188:191], v151 offset:50176
	ds_read_b128 v[192:195], v151 offset:51200
	ds_read_b128 v[196:199], v151 offset:52224
	ds_read_b128 v[200:203], v151 offset:53248
	ds_read_b128 v[206:209], v151 offset:54272
	ds_read_b128 v[210:213], v151 offset:55296
	ds_read_b128 v[214:217], v151 offset:56320
	s_add_i32 s24, s51, s35
	s_mov_b32 m0, s24
	v_lshl_add_u64 v[144:145], v[144:145], 0, s[6:7]
	global_load_lds_dwordx4 v[144:145], off
	s_add_i32 m0, s24, 0x2000
	s_add_u32 s22, s22, 0x80080
	v_lshl_add_u64 v[144:145], v[218:219], 0, s[6:7]
	s_addc_u32 s23, s23, 0
	s_add_i32 s24, s52, s35
	global_load_lds_dwordx4 v[144:145], off
	v_lshl_add_u64 v[144:145], s[22:23], 0, v[132:133]
	s_mov_b32 m0, s24
	s_nop 0
	global_load_lds_dwordx4 v[144:145], off
	v_lshl_add_u64 v[144:145], s[22:23], 0, v[128:129]
	s_add_i32 m0, s24, 0x2000
	s_nop 0
	global_load_lds_dwordx4 v[144:145], off
	v_lshl_add_u64 v[144:145], v[220:221], 0, s[6:7]
	s_mov_b32 m0, s41
	s_nop 0
	global_load_lds_dwordx4 v[144:145], off
	v_lshl_add_u64 v[144:145], v[222:223], 0, s[6:7]
	s_mov_b32 m0, s44
	s_nop 0
	global_load_lds_dwordx4 v[144:145], off
	s_waitcnt vmcnt(8)
	s_waitcnt lgkmcnt(0)
	s_barrier
	v_mfma_f32_16x16x32_bf16 v[60:63], v[152:155], v[184:187], v[60:63]
	v_mfma_f32_16x16x32_bf16 v[56:59], v[160:163], v[184:187], v[56:59]
	v_mfma_f32_16x16x32_bf16 v[44:47], v[152:155], v[192:195], v[44:47]
	v_mfma_f32_16x16x32_bf16 v[40:43], v[160:163], v[192:195], v[40:43]
	v_mfma_f32_16x16x32_bf16 v[28:31], v[152:155], v[200:203], v[28:31]
	v_mfma_f32_16x16x32_bf16 v[24:27], v[160:163], v[200:203], v[24:27]
	v_mfma_f32_16x16x32_bf16 v[12:15], v[152:155], v[210:213], v[12:15]
	v_mfma_f32_16x16x32_bf16 v[8:11], v[160:163], v[210:213], v[8:11]
	v_mfma_f32_16x16x32_bf16 v[60:63], v[156:159], v[188:191], v[60:63]
	v_mfma_f32_16x16x32_bf16 v[56:59], v[164:167], v[188:191], v[56:59]
	v_mfma_f32_16x16x32_bf16 v[44:47], v[156:159], v[196:199], v[44:47]
	v_mfma_f32_16x16x32_bf16 v[40:43], v[164:167], v[196:199], v[40:43]
	v_mfma_f32_16x16x32_bf16 v[28:31], v[156:159], v[206:209], v[28:31]
	v_mfma_f32_16x16x32_bf16 v[24:27], v[164:167], v[206:209], v[24:27]
	v_mfma_f32_16x16x32_bf16 v[12:15], v[156:159], v[214:217], v[12:15]
	v_mfma_f32_16x16x32_bf16 v[8:11], v[164:167], v[214:217], v[8:11]
	v_mfma_f32_16x16x32_bf16 v[52:55], v[168:171], v[184:187], v[52:55]
	v_mfma_f32_16x16x32_bf16 v[48:51], v[176:179], v[184:187], v[48:51]
	v_mfma_f32_16x16x32_bf16 v[36:39], v[168:171], v[192:195], v[36:39]
	v_mfma_f32_16x16x32_bf16 v[32:35], v[176:179], v[192:195], v[32:35]
	v_mfma_f32_16x16x32_bf16 v[20:23], v[168:171], v[200:203], v[20:23]
	v_mfma_f32_16x16x32_bf16 v[16:19], v[176:179], v[200:203], v[16:19]
	v_mfma_f32_16x16x32_bf16 v[4:7], v[168:171], v[210:213], v[4:7]
	v_mfma_f32_16x16x32_bf16 v[0:3], v[176:179], v[210:213], v[0:3]
	v_mfma_f32_16x16x32_bf16 v[52:55], v[172:175], v[188:191], v[52:55]
	v_mfma_f32_16x16x32_bf16 v[48:51], v[180:183], v[188:191], v[48:51]
	v_mfma_f32_16x16x32_bf16 v[36:39], v[172:175], v[196:199], v[36:39]
	v_mfma_f32_16x16x32_bf16 v[32:35], v[180:183], v[196:199], v[32:35]
	v_mfma_f32_16x16x32_bf16 v[20:23], v[172:175], v[206:209], v[20:23]
	v_mfma_f32_16x16x32_bf16 v[16:19], v[180:183], v[206:209], v[16:19]
	v_mfma_f32_16x16x32_bf16 v[4:7], v[172:175], v[214:217], v[4:7]
	v_mfma_f32_16x16x32_bf16 v[0:3], v[180:183], v[214:217], v[0:3]
	s_barrier
	s_add_i32 s50, s50, 2
	s_add_u32 s11, s11, 0x100
	s_addc_u32 s13, s13, 0
	s_add_u32 s20, s20, 0x100
	s_addc_u32 s21, s21, 0
	s_cmp_gt_u32 s50, 29
	s_cbranch_scc0 .LBB0_790
	s_and_b64 vcc, exec, s[8:9]
	s_cbranch_vccz .LBB0_793
	s_barrier

; #define PG8_STAGE(bufoff, gbase, voff) do { _Pragma("unroll") for (int _i = 0; _i < 2; ++_i) \
;         __builtin_amdgcn_global_load_lds((const unsigned*)((const char*)(gbase) + (voff)[_i]), (PG8_LAS unsigned*)(lds + (bufoff) + ldsw + _i * 8192), 16, 0, 0); } while (0)
; #define PG8_LDA(dst, b, h) do { _Pragma("unroll") for (int m = 0; m < 4; ++m) _Pragma("unroll") for (int k = 0; k < 2; ++k) dst[m][k] = *(const PG8_LAS bf16x8*)(lds + PG8_SA(b, h) + aoff + m * 2048 + k * 1024); } while (0)
; #define PG8_LDB(dst, b, h) do { _Pragma("unroll") for (int n = 0; n < 2; ++n) _Pragma("unroll") for (int k = 0; k < 2; ++k) dst[n][k] = *(const PG8_LAS bf16x8*)(lds + PG8_SB(b, h) + boff + n * 2048 + k * 1024); } while (0)
; #define PG8_MMA(ai, bj, At, Bt) do { __builtin_amdgcn_s_setprio(1); _Pragma("unroll") for (int m = 0; m < 4; ++m) _Pragma("unroll") for (int n = 0; n < 2; ++n) _Pragma("unroll") for (int k = 0; k < 2; ++k) \
;         acc[ai][bj][m][n] = __builtin_amdgcn_mfma_f32_16x16x32_bf16(Bt[n][k], At[m][k], acc[ai][bj][m][n], 0, 0, 0); __builtin_amdgcn_s_setprio(0); } while (0)
; #define PG8_WAIT_V(n) asm volatile("s_waitcnt vmcnt(" #n ")" ::: "memory")
; #define PG8_WAIT_L(n) asm volatile("s_waitcnt lgkmcnt(" #n ")" ::: "memory")
; template <class Epi, class Sched, bool ALIGN_EPI = false, bool SP2 = false>
; __device__ __forceinline__ void gemm_phase(PG8_LAS unsigned char* lds, const Gemm g, const Sched& S, const Epi& E, const int wv0) {
;     ...
;         for (int t = 0; t < nt; t += 2) {
;             const bool last = (t == nt - 2);
;             const char* a1 = cA + (size_t)(t + 1) * kstep;
;             const char* a2 = last ? nA : cA + (size_t)(t + 2) * kstep; const char* b2 = last ? nB : cB + (size_t)(t + 2) * kstep;
;             const char* a3 = a2 + kstep; const char* b3 = b2 + kstep;
;             if constexpr (SP2) {
;             PG8_LDB(B0, 0, 0); PG8_LDB(B1, 0, 1); PG8_SCHED; PG8_LDA(At, 0, 0); PG8_STAGE(PG8_SA(1, 1), a1 + hstepA, voffA);
;             PG8_WAIT_V(8); PG8_WAIT_L(0); PG8_BAR; PG8_MMA(0, 0, At, B0); PG8_MMA(0, 1, At, B1); PG8_BAR; PG8_SCHED;
;             PG8_LDA(At, 0, 1); PG8_STAGE(PG8_SB(0, 0), b2, voffB); PG8_STAGE(PG8_SB(0, 1), b2 + hstepB, voffB); PG8_STAGE(PG8_SA(0, 0), a2, voffA);
;             PG8_WAIT_V(8); PG8_WAIT_L(0); PG8_BAR; PG8_MMA(1, 0, At, B0); PG8_MMA(1, 1, At, B1); PG8_BAR; PG8_SCHED;
.LBB0_867:
	ds_read_b128 v[144:147], v155
	ds_read_b128 v[148:151], v155 offset:1024
	ds_read_b128 v[158:161], v155 offset:2048
	ds_read_b128 v[162:165], v155 offset:3072
	ds_read_b128 v[166:169], v156
	ds_read_b128 v[170:173], v156 offset:1024
	ds_read_b128 v[174:177], v156 offset:2048
	ds_read_b128 v[178:181], v156 offset:3072
	ds_read_b128 v[182:185], v157
	ds_read_b128 v[186:189], v157 offset:1024
	ds_read_b128 v[190:193], v157 offset:2048
	ds_read_b128 v[194:197], v157 offset:3072
	ds_read_b128 v[198:201], v157 offset:4096
	ds_read_b128 v[206:209], v157 offset:5120
	ds_read_b128 v[210:213], v157 offset:6144
	ds_read_b128 v[214:217], v157 offset:7168
	s_add_u32 s24, s22, 0x100
	s_addc_u32 s25, s23, 0
	s_cmpk_eq_i32 s58, 0x54
	s_cselect_b32 s29, s19, s25
	s_cselect_b32 s28, s18, s24
	s_cselect_b32 s27, s21, s57
	s_cselect_b32 s26, s20, s56
	s_add_i32 m0, s40, 0xc000
	v_lshl_add_u64 v[202:203], s[22:23], 0, v[138:139]
	global_load_lds_dwordx4 v[202:203], off
	v_lshl_add_u64 v[202:203], s[22:23], 0, v[136:137]
	s_add_i32 m0, s40, 0xe000
	s_nop 0
	global_load_lds_dwordx4 v[202:203], off
	s_waitcnt vmcnt(8)
	s_waitcnt lgkmcnt(0)
	s_barrier
	v_mfma_f32_16x16x32_bf16 v[124:127], v[144:147], v[182:185], v[124:127]
	v_mfma_f32_16x16x32_bf16 v[120:123], v[158:161], v[182:185], v[120:123]
	v_mfma_f32_16x16x32_bf16 v[116:119], v[144:147], v[190:193], v[116:119]
	v_mfma_f32_16x16x32_bf16 v[112:115], v[158:161], v[190:193], v[112:115]
	v_mfma_f32_16x16x32_bf16 v[92:95], v[144:147], v[198:201], v[92:95]
	v_mfma_f32_16x16x32_bf16 v[88:91], v[158:161], v[198:201], v[88:91]
	v_mfma_f32_16x16x32_bf16 v[84:87], v[144:147], v[210:213], v[84:87]
	v_mfma_f32_16x16x32_bf16 v[80:83], v[158:161], v[210:213], v[80:83]
	v_mfma_f32_16x16x32_bf16 v[124:127], v[148:151], v[186:189], v[124:127]
	v_mfma_f32_16x16x32_bf16 v[120:123], v[162:165], v[186:189], v[120:123]
	v_mfma_f32_16x16x32_bf16 v[116:119], v[148:151], v[194:197], v[116:119]
	v_mfma_f32_16x16x32_bf16 v[112:115], v[162:165], v[194:197], v[112:115]
	v_mfma_f32_16x16x32_bf16 v[92:95], v[148:151], v[206:209], v[92:95]
	v_mfma_f32_16x16x32_bf16 v[88:91], v[162:165], v[206:209], v[88:91]
	v_mfma_f32_16x16x32_bf16 v[84:87], v[148:151], v[214:217], v[84:87]
	v_mfma_f32_16x16x32_bf16 v[80:83], v[162:165], v[214:217], v[80:83]
	v_mfma_f32_16x16x32_bf16 v[108:111], v[166:169], v[182:185], v[108:111]
	v_mfma_f32_16x16x32_bf16 v[104:107], v[174:177], v[182:185], v[104:107]
	v_mfma_f32_16x16x32_bf16 v[100:103], v[166:169], v[190:193], v[100:103]
	v_mfma_f32_16x16x32_bf16 v[96:99], v[174:177], v[190:193], v[96:99]
	v_mfma_f32_16x16x32_bf16 v[76:79], v[166:169], v[198:201], v[76:79]
	v_mfma_f32_16x16x32_bf16 v[72:75], v[174:177], v[198:201], v[72:75]
	v_mfma_f32_16x16x32_bf16 v[68:71], v[166:169], v[210:213], v[68:71]
	v_mfma_f32_16x16x32_bf16 v[64:67], v[174:177], v[210:213], v[64:67]
	v_mfma_f32_16x16x32_bf16 v[108:111], v[170:173], v[186:189], v[108:111]
	v_mfma_f32_16x16x32_bf16 v[104:107], v[178:181], v[186:189], v[104:107]
	v_mfma_f32_16x16x32_bf16 v[100:103], v[170:173], v[194:197], v[100:103]
	v_mfma_f32_16x16x32_bf16 v[96:99], v[178:181], v[194:197], v[96:99]
	v_mfma_f32_16x16x32_bf16 v[76:79], v[170:173], v[206:209], v[76:79]
	v_mfma_f32_16x16x32_bf16 v[72:75], v[178:181], v[206:209], v[72:75]
	v_mfma_f32_16x16x32_bf16 v[68:71], v[170:173], v[214:217], v[68:71]
	v_mfma_f32_16x16x32_bf16 v[64:67], v[178:181], v[214:217], v[64:67]
	s_barrier
	ds_read_b128 v[182:185], v157 offset:16384
	ds_read_b128 v[186:189], v157 offset:17408
	ds_read_b128 v[190:193], v157 offset:18432
	ds_read_b128 v[194:197], v157 offset:19456
	ds_read_b128 v[198:201], v157 offset:20480
	ds_read_b128 v[206:209], v157 offset:21504
	ds_read_b128 v[210:213], v157 offset:22528
	ds_read_b128 v[214:217], v157 offset:23552
	s_add_i32 s22, s50, s39
	s_mov_b32 m0, s22
	v_lshl_add_u64 v[202:203], s[26:27], 0, v[130:131]
	global_load_lds_dwordx4 v[202:203], off
	s_add_i32 m0, s22, 0x2000
	s_add_u32 s22, s26, 0x160000
	v_lshl_add_u64 v[218:219], s[26:27], 0, v[134:135]
	s_addc_u32 s23, s27, 0
	s_add_i32 s59, s51, s39
	global_load_lds_dwordx4 v[218:219], off
	v_lshl_add_u64 v[220:221], s[22:23], 0, v[130:131]
	s_mov_b32 m0, s59
	v_lshl_add_u64 v[222:223], s[28:29], 0, v[132:133]
	global_load_lds_dwordx4 v[220:221], off
	v_lshl_add_u64 v[220:221], s[22:23], 0, v[134:135]
	s_add_i32 m0, s59, 0x2000
	s_nop 0
	global_load_lds_dwordx4 v[220:221], off
	v_lshl_add_u64 v[220:221], s[28:29], 0, v[128:129]
	s_mov_b32 m0, s40
	s_nop 0
	global_load_lds_dwordx4 v[220:221], off
	s_mov_b32 m0, s41
	s_nop 0
	global_load_lds_dwordx4 v[222:223], off
	s_waitcnt vmcnt(8)
	s_waitcnt lgkmcnt(0)
	s_barrier
; #define PG8_STAGE(bufoff, gbase, voff) do { _Pragma("unroll") for (int _i = 0; _i < 2; ++_i) \
;         __builtin_amdgcn_global_load_lds((const unsigned*)((const char*)(gbase) + (voff)[_i]), (PG8_LAS unsigned*)(lds + (bufoff) + ldsw + _i * 8192), 16, 0, 0); } while (0)
; #define PG8_LDA(dst, b, h) do { _Pragma("unroll") for (int m = 0; m < 4; ++m) _Pragma("unroll") for (int k = 0; k < 2; ++k) dst[m][k] = *(const PG8_LAS bf16x8*)(lds + PG8_SA(b, h) + aoff + m * 2048 + k * 1024); } while (0)
; #define PG8_LDB(dst, b, h) do { _Pragma("unroll") for (int n = 0; n < 2; ++n) _Pragma("unroll") for (int k = 0; k < 2; ++k) dst[n][k] = *(const PG8_LAS bf16x8*)(lds + PG8_SB(b, h) + boff + n * 2048 + k * 1024); } while (0)
; #define PG8_MMA(ai, bj, At, Bt) do { __builtin_amdgcn_s_setprio(1); _Pragma("unroll") for (int m = 0; m < 4; ++m) _Pragma("unroll") for (int n = 0; n < 2; ++n) _Pragma("unroll") for (int k = 0; k < 2; ++k) \
;         acc[ai][bj][m][n] = __builtin_amdgcn_mfma_f32_16x16x32_bf16(Bt[n][k], At[m][k], acc[ai][bj][m][n], 0, 0, 0); __builtin_amdgcn_s_setprio(0); } while (0)
; #define PG8_WAIT_V(n) asm volatile("s_waitcnt vmcnt(" #n ")" ::: "memory")
; #define PG8_WAIT_L(n) asm volatile("s_waitcnt lgkmcnt(" #n ")" ::: "memory")
; #define PG8_BAR __builtin_amdgcn_s_barrier()
; #define PG8_SCHED __builtin_amdgcn_sched_barrier(0)
; template <class Epi, class Sched, bool ALIGN_EPI = false, bool SP2 = false>
; __device__ __forceinline__ void gemm_phase(PG8_LAS unsigned char* lds, const Gemm g, const Sched& S, const Epi& E, const int wv0) {
;     ...
;             PG8_WAIT_V(8); PG8_WAIT_L(0); PG8_BAR; PG8_MMA(1, 0, At, B0); PG8_MMA(1, 1, At, B1); PG8_BAR; PG8_SCHED;
;             PG8_LDB(B0, 1, 0); PG8_LDB(B1, 1, 1); PG8_SCHED; PG8_LDA(At, 1, 0); PG8_STAGE(PG8_SA(0, 1), a2 + hstepA, voffA);
;             PG8_WAIT_V(8); PG8_WAIT_L(0); PG8_BAR; PG8_MMA(0, 0, At, B0); PG8_MMA(0, 1, At, B1); PG8_BAR; PG8_SCHED;
	v_mfma_f32_16x16x32_bf16 v[60:63], v[144:147], v[182:185], v[60:63]
	v_mfma_f32_16x16x32_bf16 v[56:59], v[158:161], v[182:185], v[56:59]
	v_mfma_f32_16x16x32_bf16 v[52:55], v[144:147], v[190:193], v[52:55]
	v_mfma_f32_16x16x32_bf16 v[48:51], v[158:161], v[190:193], v[48:51]
	v_mfma_f32_16x16x32_bf16 v[28:31], v[144:147], v[198:201], v[28:31]
	v_mfma_f32_16x16x32_bf16 v[24:27], v[158:161], v[198:201], v[24:27]
	v_mfma_f32_16x16x32_bf16 v[20:23], v[144:147], v[210:213], v[20:23]
	v_mfma_f32_16x16x32_bf16 v[16:19], v[158:161], v[210:213], v[16:19]
	v_mfma_f32_16x16x32_bf16 v[60:63], v[148:151], v[186:189], v[60:63]
	v_mfma_f32_16x16x32_bf16 v[56:59], v[162:165], v[186:189], v[56:59]
	v_mfma_f32_16x16x32_bf16 v[52:55], v[148:151], v[194:197], v[52:55]
	v_mfma_f32_16x16x32_bf16 v[48:51], v[162:165], v[194:197], v[48:51]
	v_mfma_f32_16x16x32_bf16 v[28:31], v[148:151], v[206:209], v[28:31]
	v_mfma_f32_16x16x32_bf16 v[24:27], v[162:165], v[206:209], v[24:27]
	v_mfma_f32_16x16x32_bf16 v[20:23], v[148:151], v[214:217], v[20:23]
	v_mfma_f32_16x16x32_bf16 v[16:19], v[162:165], v[214:217], v[16:19]
	v_mfma_f32_16x16x32_bf16 v[44:47], v[166:169], v[182:185], v[44:47]
	v_mfma_f32_16x16x32_bf16 v[40:43], v[174:177], v[182:185], v[40:43]
	v_mfma_f32_16x16x32_bf16 v[36:39], v[166:169], v[190:193], v[36:39]
	v_mfma_f32_16x16x32_bf16 v[32:35], v[174:177], v[190:193], v[32:35]
	v_mfma_f32_16x16x32_bf16 v[12:15], v[166:169], v[198:201], v[12:15]
	v_mfma_f32_16x16x32_bf16 v[8:11], v[174:177], v[198:201], v[8:11]
	v_mfma_f32_16x16x32_bf16 v[4:7], v[166:169], v[210:213], v[4:7]
	v_mfma_f32_16x16x32_bf16 v[0:3], v[174:177], v[210:213], v[0:3]
	v_mfma_f32_16x16x32_bf16 v[44:47], v[170:173], v[186:189], v[44:47]
	v_mfma_f32_16x16x32_bf16 v[40:43], v[178:181], v[186:189], v[40:43]
	v_mfma_f32_16x16x32_bf16 v[36:39], v[170:173], v[194:197], v[36:39]
	v_mfma_f32_16x16x32_bf16 v[32:35], v[178:181], v[194:197], v[32:35]
	v_mfma_f32_16x16x32_bf16 v[12:15], v[170:173], v[206:209], v[12:15]
	v_mfma_f32_16x16x32_bf16 v[8:11], v[178:181], v[206:209], v[8:11]
	v_mfma_f32_16x16x32_bf16 v[4:7], v[170:173], v[214:217], v[4:7]
	v_mfma_f32_16x16x32_bf16 v[0:3], v[178:181], v[214:217], v[0:3]
	s_barrier
	ds_read_b128 v[182:185], v157 offset:32768
	ds_read_b128 v[186:189], v157 offset:33792
	ds_read_b128 v[190:193], v157 offset:34816
	ds_read_b128 v[194:197], v157 offset:35840
	ds_read_b128 v[198:201], v157 offset:36864
	ds_read_b128 v[206:209], v157 offset:37888
	ds_read_b128 v[210:213], v157 offset:38912
	ds_read_b128 v[214:217], v157 offset:39936
	s_add_i32 s59, 0, 0x18000
	s_add_i32 s60, 0, 0x1c000
	v_add_u32_e32 v162, s59, v153
	v_add_u32_e32 v178, s60, v153
	ds_read_b128 v[144:147], v162
	ds_read_b128 v[148:151], v162 offset:1024
	ds_read_b128 v[158:161], v162 offset:2048
	ds_read_b128 v[162:165], v162 offset:3072
	ds_read_b128 v[166:169], v178
	ds_read_b128 v[170:173], v178 offset:1024
	ds_read_b128 v[174:177], v178 offset:2048
	ds_read_b128 v[178:181], v178 offset:3072
	s_add_u32 s22, s28, 0x160000
	s_addc_u32 s23, s29, 0
	s_mov_b32 m0, s44
	v_lshl_add_u64 v[224:225], s[22:23], 0, v[128:129]
	global_load_lds_dwordx4 v[224:225], off
	v_lshl_add_u64 v[224:225], s[22:23], 0, v[132:133]
	s_mov_b32 m0, s45
	s_nop 0
	global_load_lds_dwordx4 v[224:225], off
	s_waitcnt vmcnt(8)
	s_waitcnt lgkmcnt(0)
	s_barrier
	v_mfma_f32_16x16x32_bf16 v[124:127], v[144:147], v[182:185], v[124:127]
	v_mfma_f32_16x16x32_bf16 v[120:123], v[158:161], v[182:185], v[120:123]
	v_mfma_f32_16x16x32_bf16 v[116:119], v[144:147], v[190:193], v[116:119]
	v_mfma_f32_16x16x32_bf16 v[112:115], v[158:161], v[190:193], v[112:115]
	v_mfma_f32_16x16x32_bf16 v[92:95], v[144:147], v[198:201], v[92:95]
	v_mfma_f32_16x16x32_bf16 v[88:91], v[158:161], v[198:201], v[88:91]
	v_mfma_f32_16x16x32_bf16 v[84:87], v[144:147], v[210:213], v[84:87]
	v_mfma_f32_16x16x32_bf16 v[80:83], v[158:161], v[210:213], v[80:83]
	v_mfma_f32_16x16x32_bf16 v[124:127], v[148:151], v[186:189], v[124:127]
	v_mfma_f32_16x16x32_bf16 v[120:123], v[162:165], v[186:189], v[120:123]
	v_mfma_f32_16x16x32_bf16 v[116:119], v[148:151], v[194:197], v[116:119]
	v_mfma_f32_16x16x32_bf16 v[112:115], v[162:165], v[194:197], v[112:115]
	v_mfma_f32_16x16x32_bf16 v[92:95], v[148:151], v[206:209], v[92:95]
	v_mfma_f32_16x16x32_bf16 v[88:91], v[162:165], v[206:209], v[88:91]
	v_mfma_f32_16x16x32_bf16 v[84:87], v[148:151], v[214:217], v[84:87]
	v_mfma_f32_16x16x32_bf16 v[80:83], v[162:165], v[214:217], v[80:83]
	v_mfma_f32_16x16x32_bf16 v[108:111], v[166:169], v[182:185], v[108:111]
	v_mfma_f32_16x16x32_bf16 v[104:107], v[174:177], v[182:185], v[104:107]
	v_mfma_f32_16x16x32_bf16 v[100:103], v[166:169], v[190:193], v[100:103]
	v_mfma_f32_16x16x32_bf16 v[96:99], v[174:177], v[190:193], v[96:99]
	v_mfma_f32_16x16x32_bf16 v[76:79], v[166:169], v[198:201], v[76:79]
	v_mfma_f32_16x16x32_bf16 v[72:75], v[174:177], v[198:201], v[72:75]
	v_mfma_f32_16x16x32_bf16 v[68:71], v[166:169], v[210:213], v[68:71]
	v_mfma_f32_16x16x32_bf16 v[64:67], v[174:177], v[210:213], v[64:67]
	v_mfma_f32_16x16x32_bf16 v[108:111], v[170:173], v[186:189], v[108:111]
	v_mfma_f32_16x16x32_bf16 v[104:107], v[178:181], v[186:189], v[104:107]
	v_mfma_f32_16x16x32_bf16 v[100:103], v[170:173], v[194:197], v[100:103]
	v_mfma_f32_16x16x32_bf16 v[96:99], v[178:181], v[194:197], v[96:99]
	v_mfma_f32_16x16x32_bf16 v[76:79], v[170:173], v[206:209], v[76:79]
	v_mfma_f32_16x16x32_bf16 v[72:75], v[178:181], v[206:209], v[72:75]
	v_mfma_f32_16x16x32_bf16 v[68:71], v[170:173], v[214:217], v[68:71]
	v_mfma_f32_16x16x32_bf16 v[64:67], v[178:181], v[214:217], v[64:67]
	s_barrier
; #define PG8_STAGE(bufoff, gbase, voff) do { _Pragma("unroll") for (int _i = 0; _i < 2; ++_i) \
;         __builtin_amdgcn_global_load_lds((const unsigned*)((const char*)(gbase) + (voff)[_i]), (PG8_LAS unsigned*)(lds + (bufoff) + ldsw + _i * 8192), 16, 0, 0); } while (0)
; #define PG8_LDA(dst, b, h) do { _Pragma("unroll") for (int m = 0; m < 4; ++m) _Pragma("unroll") for (int k = 0; k < 2; ++k) dst[m][k] = *(const PG8_LAS bf16x8*)(lds + PG8_SA(b, h) + aoff + m * 2048 + k * 1024); } while (0)
; #define PG8_MMA(ai, bj, At, Bt) do { __builtin_amdgcn_s_setprio(1); _Pragma("unroll") for (int m = 0; m < 4; ++m) _Pragma("unroll") for (int n = 0; n < 2; ++n) _Pragma("unroll") for (int k = 0; k < 2; ++k) \
;         acc[ai][bj][m][n] = __builtin_amdgcn_mfma_f32_16x16x32_bf16(Bt[n][k], At[m][k], acc[ai][bj][m][n], 0, 0, 0); __builtin_amdgcn_s_setprio(0); } while (0)
; #define PG8_WAIT_V(n) asm volatile("s_waitcnt vmcnt(" #n ")" ::: "memory")
; #define PG8_WAIT_L(n) asm volatile("s_waitcnt lgkmcnt(" #n ")" ::: "memory")
; #define PG8_BAR __builtin_amdgcn_s_barrier()
; #define PG8_SCHED __builtin_amdgcn_sched_barrier(0)
; template <class Epi, class Sched, bool ALIGN_EPI = false, bool SP2 = false>
; __device__ __forceinline__ void gemm_phase(PG8_LAS unsigned char* lds, const Gemm g, const Sched& S, const Epi& E, const int wv0) {
;     ...
;             PG8_LDA(At, 1, 1); PG8_STAGE(PG8_SB(1, 0), b3, voffB); PG8_STAGE(PG8_SB(1, 1), b3 + hstepB, voffB); PG8_STAGE(PG8_SA(1, 0), a3, voffA);
;             PG8_WAIT_V(8); PG8_WAIT_L(0); PG8_BAR; PG8_MMA(1, 0, At, B0); PG8_MMA(1, 1, At, B1); PG8_BAR; PG8_SCHED;
	s_add_i32 s22, s59, s39
	v_lshl_add_u64 v[202:203], v[202:203], 0, s[6:7]
	s_mov_b32 m0, s22
	ds_read_b128 v[182:185], v157 offset:49152
	ds_read_b128 v[186:189], v157 offset:50176
	ds_read_b128 v[190:193], v157 offset:51200
	ds_read_b128 v[194:197], v157 offset:52224
	ds_read_b128 v[198:201], v157 offset:53248
	ds_read_b128 v[206:209], v157 offset:54272
	ds_read_b128 v[210:213], v157 offset:55296
	ds_read_b128 v[214:217], v157 offset:56320
	global_load_lds_dwordx4 v[202:203], off
	s_add_i32 m0, s22, 0x2000
	s_add_u32 s22, s26, 0x160080
	v_lshl_add_u64 v[202:203], v[218:219], 0, s[6:7]
	s_addc_u32 s23, s27, 0
	s_add_i32 s26, s60, s39
	global_load_lds_dwordx4 v[202:203], off
	v_lshl_add_u64 v[202:203], s[22:23], 0, v[130:131]
	s_mov_b32 m0, s26
	s_nop 0
	global_load_lds_dwordx4 v[202:203], off
	v_lshl_add_u64 v[202:203], s[22:23], 0, v[134:135]
	s_add_i32 m0, s26, 0x2000
	s_nop 0
	global_load_lds_dwordx4 v[202:203], off
	v_lshl_add_u64 v[202:203], v[220:221], 0, s[6:7]
	s_mov_b32 m0, s47
	s_nop 0
	global_load_lds_dwordx4 v[202:203], off
	v_lshl_add_u64 v[202:203], v[222:223], 0, s[6:7]
	s_mov_b32 m0, s48
	s_nop 0
	global_load_lds_dwordx4 v[202:203], off
	s_waitcnt vmcnt(8)
	s_waitcnt lgkmcnt(0)
	s_barrier
	v_mfma_f32_16x16x32_bf16 v[60:63], v[144:147], v[182:185], v[60:63]
	v_mfma_f32_16x16x32_bf16 v[56:59], v[158:161], v[182:185], v[56:59]
	v_mfma_f32_16x16x32_bf16 v[52:55], v[144:147], v[190:193], v[52:55]
	v_mfma_f32_16x16x32_bf16 v[48:51], v[158:161], v[190:193], v[48:51]
	v_mfma_f32_16x16x32_bf16 v[28:31], v[144:147], v[198:201], v[28:31]
	v_mfma_f32_16x16x32_bf16 v[24:27], v[158:161], v[198:201], v[24:27]
	v_mfma_f32_16x16x32_bf16 v[20:23], v[144:147], v[210:213], v[20:23]
	v_mfma_f32_16x16x32_bf16 v[16:19], v[158:161], v[210:213], v[16:19]
	v_mfma_f32_16x16x32_bf16 v[60:63], v[148:151], v[186:189], v[60:63]
	v_mfma_f32_16x16x32_bf16 v[56:59], v[162:165], v[186:189], v[56:59]
	v_mfma_f32_16x16x32_bf16 v[52:55], v[148:151], v[194:197], v[52:55]
	v_mfma_f32_16x16x32_bf16 v[48:51], v[162:165], v[194:197], v[48:51]
	v_mfma_f32_16x16x32_bf16 v[28:31], v[148:151], v[206:209], v[28:31]
	v_mfma_f32_16x16x32_bf16 v[24:27], v[162:165], v[206:209], v[24:27]
	v_mfma_f32_16x16x32_bf16 v[20:23], v[148:151], v[214:217], v[20:23]
	v_mfma_f32_16x16x32_bf16 v[16:19], v[162:165], v[214:217], v[16:19]
	v_mfma_f32_16x16x32_bf16 v[44:47], v[166:169], v[182:185], v[44:47]
	v_mfma_f32_16x16x32_bf16 v[40:43], v[174:177], v[182:185], v[40:43]
	v_mfma_f32_16x16x32_bf16 v[36:39], v[166:169], v[190:193], v[36:39]
	v_mfma_f32_16x16x32_bf16 v[32:35], v[174:177], v[190:193], v[32:35]
	v_mfma_f32_16x16x32_bf16 v[12:15], v[166:169], v[198:201], v[12:15]
	v_mfma_f32_16x16x32_bf16 v[8:11], v[174:177], v[198:201], v[8:11]
	v_mfma_f32_16x16x32_bf16 v[4:7], v[166:169], v[210:213], v[4:7]
	v_mfma_f32_16x16x32_bf16 v[0:3], v[174:177], v[210:213], v[0:3]
	v_mfma_f32_16x16x32_bf16 v[44:47], v[170:173], v[186:189], v[44:47]
	v_mfma_f32_16x16x32_bf16 v[40:43], v[178:181], v[186:189], v[40:43]
	v_mfma_f32_16x16x32_bf16 v[36:39], v[170:173], v[194:197], v[36:39]
	v_mfma_f32_16x16x32_bf16 v[32:35], v[178:181], v[194:197], v[32:35]
	v_mfma_f32_16x16x32_bf16 v[12:15], v[170:173], v[206:209], v[12:15]
	v_mfma_f32_16x16x32_bf16 v[8:11], v[178:181], v[206:209], v[8:11]
	v_mfma_f32_16x16x32_bf16 v[4:7], v[170:173], v[214:217], v[4:7]
	v_mfma_f32_16x16x32_bf16 v[0:3], v[178:181], v[214:217], v[0:3]
	s_barrier
	s_add_i32 s58, s58, 2
	s_add_u32 s56, s56, 0x100
	s_addc_u32 s57, s57, 0
	s_cmpk_gt_u32 s58, 0x55
	s_mov_b64 s[22:23], s[24:25]
	s_cbranch_scc0 .LBB0_867
	s_and_b64 vcc, exec, s[8:9]
	s_cbranch_vccz .LBB0_870
	s_barrier

; #define PG8_STAGE(bufoff, gbase, voff) do { _Pragma("unroll") for (int _i = 0; _i < 2; ++_i) \
;         __builtin_amdgcn_global_load_lds((const unsigned*)((const char*)(gbase) + (voff)[_i]), (PG8_LAS unsigned*)(lds + (bufoff) + ldsw + _i * 8192), 16, 0, 0); } while (0)
; #define PG8_LDA(dst, b, h) do { _Pragma("unroll") for (int m = 0; m < 4; ++m) _Pragma("unroll") for (int k = 0; k < 2; ++k) dst[m][k] = *(const PG8_LAS bf16x8*)(lds + PG8_SA(b, h) + aoff + m * 2048 + k * 1024); } while (0)
; #define PG8_LDB(dst, b, h) do { _Pragma("unroll") for (int n = 0; n < 2; ++n) _Pragma("unroll") for (int k = 0; k < 2; ++k) dst[n][k] = *(const PG8_LAS bf16x8*)(lds + PG8_SB(b, h) + boff + n * 2048 + k * 1024); } while (0)
; #define PG8_MMA(ai, bj, At, Bt) do { __builtin_amdgcn_s_setprio(1); _Pragma("unroll") for (int m = 0; m < 4; ++m) _Pragma("unroll") for (int n = 0; n < 2; ++n) _Pragma("unroll") for (int k = 0; k < 2; ++k) \
;         acc[ai][bj][m][n] = __builtin_amdgcn_mfma_f32_16x16x32_bf16(Bt[n][k], At[m][k], acc[ai][bj][m][n], 0, 0, 0); __builtin_amdgcn_s_setprio(0); } while (0)
; #define PG8_WAIT_V(n) asm volatile("s_waitcnt vmcnt(" #n ")" ::: "memory")
; #define PG8_WAIT_L(n) asm volatile("s_waitcnt lgkmcnt(" #n ")" ::: "memory")
; template <class Epi, class Sched, bool ALIGN_EPI = false, bool SP2 = false>
; __device__ __forceinline__ void gemm_phase(PG8_LAS unsigned char* lds, const Gemm g, const Sched& S, const Epi& E, const int wv0) {
;     ...
;         for (int t = 0; t < nt; t += 2) {
;             const bool last = (t == nt - 2);
;             const char* a1 = cA + (size_t)(t + 1) * kstep;
;             const char* a2 = last ? nA : cA + (size_t)(t + 2) * kstep; const char* b2 = last ? nB : cB + (size_t)(t + 2) * kstep;
;             const char* a3 = a2 + kstep; const char* b3 = b2 + kstep;
;             if constexpr (SP2) {
;             PG8_LDB(B0, 0, 0); PG8_LDB(B1, 0, 1); PG8_SCHED; PG8_LDA(At, 0, 0); PG8_STAGE(PG8_SA(1, 1), a1 + hstepA, voffA);
;             PG8_WAIT_V(8); PG8_WAIT_L(0); PG8_BAR; PG8_MMA(0, 0, At, B0); PG8_MMA(0, 1, At, B1); PG8_BAR; PG8_SCHED;
;             PG8_LDA(At, 0, 1); PG8_STAGE(PG8_SB(0, 0), b2, voffB); PG8_STAGE(PG8_SB(0, 1), b2 + hstepB, voffB); PG8_STAGE(PG8_SA(0, 0), a2, voffA);
;             PG8_WAIT_V(8); PG8_WAIT_L(0); PG8_BAR; PG8_MMA(1, 0, At, B0); PG8_MMA(1, 1, At, B1); PG8_BAR; PG8_SCHED;
.LBB0_1608:
	ds_read_b128 v[144:147], v155
	ds_read_b128 v[148:151], v155 offset:1024
	ds_read_b128 v[158:161], v155 offset:2048
	ds_read_b128 v[162:165], v155 offset:3072
	ds_read_b128 v[166:169], v156
	ds_read_b128 v[170:173], v156 offset:1024
	ds_read_b128 v[174:177], v156 offset:2048
	ds_read_b128 v[178:181], v156 offset:3072
	ds_read_b128 v[182:185], v157
	ds_read_b128 v[186:189], v157 offset:1024
	ds_read_b128 v[190:193], v157 offset:2048
	ds_read_b128 v[194:197], v157 offset:3072
	ds_read_b128 v[198:201], v157 offset:4096
	ds_read_b128 v[206:209], v157 offset:5120
	ds_read_b128 v[210:213], v157 offset:6144
	ds_read_b128 v[214:217], v157 offset:7168
	s_add_u32 s30, s28, 0xfff80080
	s_addc_u32 s31, s29, -1
	s_cmp_eq_u32 s56, 28
	s_cselect_b32 s35, s23, s31
	s_cselect_b32 s34, s22, s30
	s_cselect_b32 s31, s25, s21
	s_cselect_b32 s30, s24, s19
	s_add_i32 m0, s27, 0xc000
	v_lshl_add_u64 v[202:203], s[28:29], 0, v[138:139]
	global_load_lds_dwordx4 v[202:203], off
	v_lshl_add_u64 v[202:203], s[28:29], 0, v[136:137]
	s_add_i32 m0, s27, 0xe000
	s_nop 0
	global_load_lds_dwordx4 v[202:203], off
	s_waitcnt vmcnt(8)
	s_waitcnt lgkmcnt(0)
	s_barrier
	v_mfma_f32_16x16x32_bf16 v[124:127], v[144:147], v[182:185], v[124:127]
	v_mfma_f32_16x16x32_bf16 v[120:123], v[158:161], v[182:185], v[120:123]
	v_mfma_f32_16x16x32_bf16 v[116:119], v[144:147], v[190:193], v[116:119]
	v_mfma_f32_16x16x32_bf16 v[112:115], v[158:161], v[190:193], v[112:115]
	v_mfma_f32_16x16x32_bf16 v[92:95], v[144:147], v[198:201], v[92:95]
	v_mfma_f32_16x16x32_bf16 v[88:91], v[158:161], v[198:201], v[88:91]
	v_mfma_f32_16x16x32_bf16 v[84:87], v[144:147], v[210:213], v[84:87]
	v_mfma_f32_16x16x32_bf16 v[80:83], v[158:161], v[210:213], v[80:83]
	v_mfma_f32_16x16x32_bf16 v[124:127], v[148:151], v[186:189], v[124:127]
	v_mfma_f32_16x16x32_bf16 v[120:123], v[162:165], v[186:189], v[120:123]
	v_mfma_f32_16x16x32_bf16 v[116:119], v[148:151], v[194:197], v[116:119]
	v_mfma_f32_16x16x32_bf16 v[112:115], v[162:165], v[194:197], v[112:115]
	v_mfma_f32_16x16x32_bf16 v[92:95], v[148:151], v[206:209], v[92:95]
	v_mfma_f32_16x16x32_bf16 v[88:91], v[162:165], v[206:209], v[88:91]
	v_mfma_f32_16x16x32_bf16 v[84:87], v[148:151], v[214:217], v[84:87]
	v_mfma_f32_16x16x32_bf16 v[80:83], v[162:165], v[214:217], v[80:83]
	v_mfma_f32_16x16x32_bf16 v[108:111], v[166:169], v[182:185], v[108:111]
	v_mfma_f32_16x16x32_bf16 v[104:107], v[174:177], v[182:185], v[104:107]
	v_mfma_f32_16x16x32_bf16 v[100:103], v[166:169], v[190:193], v[100:103]
	v_mfma_f32_16x16x32_bf16 v[96:99], v[174:177], v[190:193], v[96:99]
	v_mfma_f32_16x16x32_bf16 v[76:79], v[166:169], v[198:201], v[76:79]
	v_mfma_f32_16x16x32_bf16 v[72:75], v[174:177], v[198:201], v[72:75]
	v_mfma_f32_16x16x32_bf16 v[68:71], v[166:169], v[210:213], v[68:71]
	v_mfma_f32_16x16x32_bf16 v[64:67], v[174:177], v[210:213], v[64:67]
	v_mfma_f32_16x16x32_bf16 v[108:111], v[170:173], v[186:189], v[108:111]
	v_mfma_f32_16x16x32_bf16 v[104:107], v[178:181], v[186:189], v[104:107]
	v_mfma_f32_16x16x32_bf16 v[100:103], v[170:173], v[194:197], v[100:103]
	v_mfma_f32_16x16x32_bf16 v[96:99], v[178:181], v[194:197], v[96:99]
	v_mfma_f32_16x16x32_bf16 v[76:79], v[170:173], v[206:209], v[76:79]
	v_mfma_f32_16x16x32_bf16 v[72:75], v[178:181], v[206:209], v[72:75]
	v_mfma_f32_16x16x32_bf16 v[68:71], v[170:173], v[214:217], v[68:71]
	v_mfma_f32_16x16x32_bf16 v[64:67], v[178:181], v[214:217], v[64:67]
	s_barrier
	ds_read_b128 v[182:185], v157 offset:16384
	ds_read_b128 v[186:189], v157 offset:17408
	ds_read_b128 v[190:193], v157 offset:18432
	ds_read_b128 v[194:197], v157 offset:19456
	ds_read_b128 v[198:201], v157 offset:20480
	ds_read_b128 v[206:209], v157 offset:21504
	ds_read_b128 v[210:213], v157 offset:22528
	ds_read_b128 v[214:217], v157 offset:23552
	s_add_i32 s57, s53, s45
	s_mov_b32 m0, s57
	v_lshl_add_u64 v[202:203], s[30:31], 0, v[130:131]
	global_load_lds_dwordx4 v[202:203], off
	s_add_i32 m0, s57, 0x2000
	s_add_u32 s58, s30, 0x80000
	v_lshl_add_u64 v[218:219], s[30:31], 0, v[134:135]
	s_addc_u32 s59, s31, 0
	s_add_i32 s57, s54, s45
	global_load_lds_dwordx4 v[218:219], off
	v_lshl_add_u64 v[220:221], s[58:59], 0, v[130:131]
	s_mov_b32 m0, s57
	v_lshl_add_u64 v[222:223], s[34:35], 0, v[132:133]
	global_load_lds_dwordx4 v[220:221], off
	v_lshl_add_u64 v[220:221], s[58:59], 0, v[134:135]
	s_add_i32 m0, s57, 0x2000
	s_nop 0
	global_load_lds_dwordx4 v[220:221], off
	v_lshl_add_u64 v[220:221], s[34:35], 0, v[128:129]
	s_mov_b32 m0, s27
	s_nop 0
	global_load_lds_dwordx4 v[220:221], off
	s_mov_b32 m0, s46
	s_nop 0
	global_load_lds_dwordx4 v[222:223], off
	s_waitcnt vmcnt(8)
	s_waitcnt lgkmcnt(0)
	s_barrier
; #define PG8_STAGE(bufoff, gbase, voff) do { _Pragma("unroll") for (int _i = 0; _i < 2; ++_i) \
;         __builtin_amdgcn_global_load_lds((const unsigned*)((const char*)(gbase) + (voff)[_i]), (PG8_LAS unsigned*)(lds + (bufoff) + ldsw + _i * 8192), 16, 0, 0); } while (0)
; #define PG8_LDA(dst, b, h) do { _Pragma("unroll") for (int m = 0; m < 4; ++m) _Pragma("unroll") for (int k = 0; k < 2; ++k) dst[m][k] = *(const PG8_LAS bf16x8*)(lds + PG8_SA(b, h) + aoff + m * 2048 + k * 1024); } while (0)
; #define PG8_LDB(dst, b, h) do { _Pragma("unroll") for (int n = 0; n < 2; ++n) _Pragma("unroll") for (int k = 0; k < 2; ++k) dst[n][k] = *(const PG8_LAS bf16x8*)(lds + PG8_SB(b, h) + boff + n * 2048 + k * 1024); } while (0)
; #define PG8_MMA(ai, bj, At, Bt) do { __builtin_amdgcn_s_setprio(1); _Pragma("unroll") for (int m = 0; m < 4; ++m) _Pragma("unroll") for (int n = 0; n < 2; ++n) _Pragma("unroll") for (int k = 0; k < 2; ++k) \
;         acc[ai][bj][m][n] = __builtin_amdgcn_mfma_f32_16x16x32_bf16(Bt[n][k], At[m][k], acc[ai][bj][m][n], 0, 0, 0); __builtin_amdgcn_s_setprio(0); } while (0)
; #define PG8_WAIT_V(n) asm volatile("s_waitcnt vmcnt(" #n ")" ::: "memory")
; #define PG8_WAIT_L(n) asm volatile("s_waitcnt lgkmcnt(" #n ")" ::: "memory")
; #define PG8_BAR __builtin_amdgcn_s_barrier()
; #define PG8_SCHED __builtin_amdgcn_sched_barrier(0)
; template <class Epi, class Sched, bool ALIGN_EPI = false, bool SP2 = false>
; __device__ __forceinline__ void gemm_phase(PG8_LAS unsigned char* lds, const Gemm g, const Sched& S, const Epi& E, const int wv0) {
;     ...
;             PG8_WAIT_V(8); PG8_WAIT_L(0); PG8_BAR; PG8_MMA(1, 0, At, B0); PG8_MMA(1, 1, At, B1); PG8_BAR; PG8_SCHED;
;             PG8_LDB(B0, 1, 0); PG8_LDB(B1, 1, 1); PG8_SCHED; PG8_LDA(At, 1, 0); PG8_STAGE(PG8_SA(0, 1), a2 + hstepA, voffA);
;             PG8_WAIT_V(8); PG8_WAIT_L(0); PG8_BAR; PG8_MMA(0, 0, At, B0); PG8_MMA(0, 1, At, B1); PG8_BAR; PG8_SCHED;
	v_mfma_f32_16x16x32_bf16 v[60:63], v[144:147], v[182:185], v[60:63]
	v_mfma_f32_16x16x32_bf16 v[56:59], v[158:161], v[182:185], v[56:59]
	v_mfma_f32_16x16x32_bf16 v[52:55], v[144:147], v[190:193], v[52:55]
	v_mfma_f32_16x16x32_bf16 v[48:51], v[158:161], v[190:193], v[48:51]
	v_mfma_f32_16x16x32_bf16 v[28:31], v[144:147], v[198:201], v[28:31]
	v_mfma_f32_16x16x32_bf16 v[24:27], v[158:161], v[198:201], v[24:27]
	v_mfma_f32_16x16x32_bf16 v[20:23], v[144:147], v[210:213], v[20:23]
	v_mfma_f32_16x16x32_bf16 v[16:19], v[158:161], v[210:213], v[16:19]
	v_mfma_f32_16x16x32_bf16 v[60:63], v[148:151], v[186:189], v[60:63]
	v_mfma_f32_16x16x32_bf16 v[56:59], v[162:165], v[186:189], v[56:59]
	v_mfma_f32_16x16x32_bf16 v[52:55], v[148:151], v[194:197], v[52:55]
	v_mfma_f32_16x16x32_bf16 v[48:51], v[162:165], v[194:197], v[48:51]
	v_mfma_f32_16x16x32_bf16 v[28:31], v[148:151], v[206:209], v[28:31]
	v_mfma_f32_16x16x32_bf16 v[24:27], v[162:165], v[206:209], v[24:27]
	v_mfma_f32_16x16x32_bf16 v[20:23], v[148:151], v[214:217], v[20:23]
	v_mfma_f32_16x16x32_bf16 v[16:19], v[162:165], v[214:217], v[16:19]
	v_mfma_f32_16x16x32_bf16 v[44:47], v[166:169], v[182:185], v[44:47]
	v_mfma_f32_16x16x32_bf16 v[40:43], v[174:177], v[182:185], v[40:43]
	v_mfma_f32_16x16x32_bf16 v[36:39], v[166:169], v[190:193], v[36:39]
	v_mfma_f32_16x16x32_bf16 v[32:35], v[174:177], v[190:193], v[32:35]
	v_mfma_f32_16x16x32_bf16 v[12:15], v[166:169], v[198:201], v[12:15]
	v_mfma_f32_16x16x32_bf16 v[8:11], v[174:177], v[198:201], v[8:11]
	v_mfma_f32_16x16x32_bf16 v[4:7], v[166:169], v[210:213], v[4:7]
	v_mfma_f32_16x16x32_bf16 v[0:3], v[174:177], v[210:213], v[0:3]
	v_mfma_f32_16x16x32_bf16 v[44:47], v[170:173], v[186:189], v[44:47]
	v_mfma_f32_16x16x32_bf16 v[40:43], v[178:181], v[186:189], v[40:43]
	v_mfma_f32_16x16x32_bf16 v[36:39], v[170:173], v[194:197], v[36:39]
	v_mfma_f32_16x16x32_bf16 v[32:35], v[178:181], v[194:197], v[32:35]
	v_mfma_f32_16x16x32_bf16 v[12:15], v[170:173], v[206:209], v[12:15]
	v_mfma_f32_16x16x32_bf16 v[8:11], v[178:181], v[206:209], v[8:11]
	v_mfma_f32_16x16x32_bf16 v[4:7], v[170:173], v[214:217], v[4:7]
	v_mfma_f32_16x16x32_bf16 v[0:3], v[178:181], v[214:217], v[0:3]
	s_barrier
	ds_read_b128 v[182:185], v157 offset:32768
	ds_read_b128 v[186:189], v157 offset:33792
	ds_read_b128 v[190:193], v157 offset:34816
	ds_read_b128 v[194:197], v157 offset:35840
	ds_read_b128 v[198:201], v157 offset:36864
	ds_read_b128 v[206:209], v157 offset:37888
	ds_read_b128 v[210:213], v157 offset:38912
	ds_read_b128 v[214:217], v157 offset:39936
	s_add_i32 s57, 0, 0x18000
	s_add_i32 s58, 0, 0x1c000
	v_add_u32_e32 v162, s57, v153
	v_add_u32_e32 v178, s58, v153
	ds_read_b128 v[144:147], v162
	ds_read_b128 v[148:151], v162 offset:1024
	ds_read_b128 v[158:161], v162 offset:2048
	ds_read_b128 v[162:165], v162 offset:3072
	ds_read_b128 v[166:169], v178
	ds_read_b128 v[170:173], v178 offset:1024
	ds_read_b128 v[174:177], v178 offset:2048
	ds_read_b128 v[178:181], v178 offset:3072
	s_add_u32 s34, s34, 0x80000
	s_addc_u32 s35, s35, 0
	s_mov_b32 m0, s47
	v_lshl_add_u64 v[224:225], s[34:35], 0, v[128:129]
	global_load_lds_dwordx4 v[224:225], off
	v_lshl_add_u64 v[224:225], s[34:35], 0, v[132:133]
	s_mov_b32 m0, s48
	s_nop 0
	global_load_lds_dwordx4 v[224:225], off
	s_waitcnt vmcnt(8)
	s_waitcnt lgkmcnt(0)
	s_barrier
	v_mfma_f32_16x16x32_bf16 v[124:127], v[144:147], v[182:185], v[124:127]
	v_mfma_f32_16x16x32_bf16 v[120:123], v[158:161], v[182:185], v[120:123]
	v_mfma_f32_16x16x32_bf16 v[116:119], v[144:147], v[190:193], v[116:119]
	v_mfma_f32_16x16x32_bf16 v[112:115], v[158:161], v[190:193], v[112:115]
	v_mfma_f32_16x16x32_bf16 v[92:95], v[144:147], v[198:201], v[92:95]
	v_mfma_f32_16x16x32_bf16 v[88:91], v[158:161], v[198:201], v[88:91]
	v_mfma_f32_16x16x32_bf16 v[84:87], v[144:147], v[210:213], v[84:87]
	v_mfma_f32_16x16x32_bf16 v[80:83], v[158:161], v[210:213], v[80:83]
	v_mfma_f32_16x16x32_bf16 v[124:127], v[148:151], v[186:189], v[124:127]
	v_mfma_f32_16x16x32_bf16 v[120:123], v[162:165], v[186:189], v[120:123]
	v_mfma_f32_16x16x32_bf16 v[116:119], v[148:151], v[194:197], v[116:119]
	v_mfma_f32_16x16x32_bf16 v[112:115], v[162:165], v[194:197], v[112:115]
	v_mfma_f32_16x16x32_bf16 v[92:95], v[148:151], v[206:209], v[92:95]
	v_mfma_f32_16x16x32_bf16 v[88:91], v[162:165], v[206:209], v[88:91]
	v_mfma_f32_16x16x32_bf16 v[84:87], v[148:151], v[214:217], v[84:87]
	v_mfma_f32_16x16x32_bf16 v[80:83], v[162:165], v[214:217], v[80:83]
	v_mfma_f32_16x16x32_bf16 v[108:111], v[166:169], v[182:185], v[108:111]
	v_mfma_f32_16x16x32_bf16 v[104:107], v[174:177], v[182:185], v[104:107]
	v_mfma_f32_16x16x32_bf16 v[100:103], v[166:169], v[190:193], v[100:103]
	v_mfma_f32_16x16x32_bf16 v[96:99], v[174:177], v[190:193], v[96:99]
	v_mfma_f32_16x16x32_bf16 v[76:79], v[166:169], v[198:201], v[76:79]
	v_mfma_f32_16x16x32_bf16 v[72:75], v[174:177], v[198:201], v[72:75]
	v_mfma_f32_16x16x32_bf16 v[68:71], v[166:169], v[210:213], v[68:71]
	v_mfma_f32_16x16x32_bf16 v[64:67], v[174:177], v[210:213], v[64:67]
	v_mfma_f32_16x16x32_bf16 v[108:111], v[170:173], v[186:189], v[108:111]
	v_mfma_f32_16x16x32_bf16 v[104:107], v[178:181], v[186:189], v[104:107]
	v_mfma_f32_16x16x32_bf16 v[100:103], v[170:173], v[194:197], v[100:103]
	v_mfma_f32_16x16x32_bf16 v[96:99], v[178:181], v[194:197], v[96:99]
	v_mfma_f32_16x16x32_bf16 v[76:79], v[170:173], v[206:209], v[76:79]
	v_mfma_f32_16x16x32_bf16 v[72:75], v[178:181], v[206:209], v[72:75]
	v_mfma_f32_16x16x32_bf16 v[68:71], v[170:173], v[214:217], v[68:71]
	v_mfma_f32_16x16x32_bf16 v[64:67], v[178:181], v[214:217], v[64:67]
	s_barrier
; #define PG8_STAGE(bufoff, gbase, voff) do { _Pragma("unroll") for (int _i = 0; _i < 2; ++_i) \
;         __builtin_amdgcn_global_load_lds((const unsigned*)((const char*)(gbase) + (voff)[_i]), (PG8_LAS unsigned*)(lds + (bufoff) + ldsw + _i * 8192), 16, 0, 0); } while (0)
; #define PG8_LDA(dst, b, h) do { _Pragma("unroll") for (int m = 0; m < 4; ++m) _Pragma("unroll") for (int k = 0; k < 2; ++k) dst[m][k] = *(const PG8_LAS bf16x8*)(lds + PG8_SA(b, h) + aoff + m * 2048 + k * 1024); } while (0)
; #define PG8_MMA(ai, bj, At, Bt) do { __builtin_amdgcn_s_setprio(1); _Pragma("unroll") for (int m = 0; m < 4; ++m) _Pragma("unroll") for (int n = 0; n < 2; ++n) _Pragma("unroll") for (int k = 0; k < 2; ++k) \
;         acc[ai][bj][m][n] = __builtin_amdgcn_mfma_f32_16x16x32_bf16(Bt[n][k], At[m][k], acc[ai][bj][m][n], 0, 0, 0); __builtin_amdgcn_s_setprio(0); } while (0)
; #define PG8_WAIT_V(n) asm volatile("s_waitcnt vmcnt(" #n ")" ::: "memory")
; #define PG8_WAIT_L(n) asm volatile("s_waitcnt lgkmcnt(" #n ")" ::: "memory")
; #define PG8_BAR __builtin_amdgcn_s_barrier()
; #define PG8_SCHED __builtin_amdgcn_sched_barrier(0)
; template <class Epi, class Sched, bool ALIGN_EPI = false, bool SP2 = false>
; __device__ __forceinline__ void gemm_phase(PG8_LAS unsigned char* lds, const Gemm g, const Sched& S, const Epi& E, const int wv0) {
;     ...
;         for (int t = 0; t < nt; t += 2) {
;             const bool last = (t == nt - 2);
;     ...
;             PG8_LDA(At, 1, 1); PG8_STAGE(PG8_SB(1, 0), b3, voffB); PG8_STAGE(PG8_SB(1, 1), b3 + hstepB, voffB); PG8_STAGE(PG8_SA(1, 0), a3, voffA);
;             PG8_WAIT_V(8); PG8_WAIT_L(0); PG8_BAR; PG8_MMA(1, 0, At, B0); PG8_MMA(1, 1, At, B1); PG8_BAR; PG8_SCHED;
;     ...
;         if constexpr (ALIGN_EPI) { if (wr == 0) PG8_BAR; }
	s_add_i32 s34, s57, s45
	v_lshl_add_u64 v[202:203], v[202:203], 0, s[8:9]
	s_mov_b32 m0, s34
	ds_read_b128 v[182:185], v157 offset:49152
	ds_read_b128 v[186:189], v157 offset:50176
	ds_read_b128 v[190:193], v157 offset:51200
	ds_read_b128 v[194:197], v157 offset:52224
	ds_read_b128 v[198:201], v157 offset:53248
	ds_read_b128 v[206:209], v157 offset:54272
	ds_read_b128 v[210:213], v157 offset:55296
	ds_read_b128 v[214:217], v157 offset:56320
	global_load_lds_dwordx4 v[202:203], off
	s_add_i32 m0, s34, 0x2000
	s_add_u32 s30, s30, 0x80080
	v_lshl_add_u64 v[202:203], v[218:219], 0, s[8:9]
	s_addc_u32 s31, s31, 0
	s_add_i32 s34, s58, s45
	global_load_lds_dwordx4 v[202:203], off
	v_lshl_add_u64 v[202:203], s[30:31], 0, v[130:131]
	s_mov_b32 m0, s34
	s_nop 0
	global_load_lds_dwordx4 v[202:203], off
	v_lshl_add_u64 v[202:203], s[30:31], 0, v[134:135]
	s_add_i32 m0, s34, 0x2000
	s_nop 0
	global_load_lds_dwordx4 v[202:203], off
	v_lshl_add_u64 v[202:203], v[220:221], 0, s[8:9]
	s_mov_b32 m0, s50
	s_nop 0
	global_load_lds_dwordx4 v[202:203], off
	v_lshl_add_u64 v[202:203], v[222:223], 0, s[8:9]
	s_mov_b32 m0, s51
	s_nop 0
	global_load_lds_dwordx4 v[202:203], off
	s_waitcnt vmcnt(8)
	s_waitcnt lgkmcnt(0)
	s_barrier
	v_mfma_f32_16x16x32_bf16 v[60:63], v[144:147], v[182:185], v[60:63]
	v_mfma_f32_16x16x32_bf16 v[56:59], v[158:161], v[182:185], v[56:59]
	v_mfma_f32_16x16x32_bf16 v[52:55], v[144:147], v[190:193], v[52:55]
	v_mfma_f32_16x16x32_bf16 v[48:51], v[158:161], v[190:193], v[48:51]
	v_mfma_f32_16x16x32_bf16 v[28:31], v[144:147], v[198:201], v[28:31]
	v_mfma_f32_16x16x32_bf16 v[24:27], v[158:161], v[198:201], v[24:27]
	v_mfma_f32_16x16x32_bf16 v[20:23], v[144:147], v[210:213], v[20:23]
	v_mfma_f32_16x16x32_bf16 v[16:19], v[158:161], v[210:213], v[16:19]
	v_mfma_f32_16x16x32_bf16 v[60:63], v[148:151], v[186:189], v[60:63]
	v_mfma_f32_16x16x32_bf16 v[56:59], v[162:165], v[186:189], v[56:59]
	v_mfma_f32_16x16x32_bf16 v[52:55], v[148:151], v[194:197], v[52:55]
	v_mfma_f32_16x16x32_bf16 v[48:51], v[162:165], v[194:197], v[48:51]
	v_mfma_f32_16x16x32_bf16 v[28:31], v[148:151], v[206:209], v[28:31]
	v_mfma_f32_16x16x32_bf16 v[24:27], v[162:165], v[206:209], v[24:27]
	v_mfma_f32_16x16x32_bf16 v[20:23], v[148:151], v[214:217], v[20:23]
	v_mfma_f32_16x16x32_bf16 v[16:19], v[162:165], v[214:217], v[16:19]
	v_mfma_f32_16x16x32_bf16 v[44:47], v[166:169], v[182:185], v[44:47]
	v_mfma_f32_16x16x32_bf16 v[40:43], v[174:177], v[182:185], v[40:43]
	v_mfma_f32_16x16x32_bf16 v[36:39], v[166:169], v[190:193], v[36:39]
	v_mfma_f32_16x16x32_bf16 v[32:35], v[174:177], v[190:193], v[32:35]
	v_mfma_f32_16x16x32_bf16 v[12:15], v[166:169], v[198:201], v[12:15]
	v_mfma_f32_16x16x32_bf16 v[8:11], v[174:177], v[198:201], v[8:11]
	v_mfma_f32_16x16x32_bf16 v[4:7], v[166:169], v[210:213], v[4:7]
	v_mfma_f32_16x16x32_bf16 v[0:3], v[174:177], v[210:213], v[0:3]
	v_mfma_f32_16x16x32_bf16 v[44:47], v[170:173], v[186:189], v[44:47]
	v_mfma_f32_16x16x32_bf16 v[40:43], v[178:181], v[186:189], v[40:43]
	v_mfma_f32_16x16x32_bf16 v[36:39], v[170:173], v[194:197], v[36:39]
	v_mfma_f32_16x16x32_bf16 v[32:35], v[178:181], v[194:197], v[32:35]
	v_mfma_f32_16x16x32_bf16 v[12:15], v[170:173], v[206:209], v[12:15]
	v_mfma_f32_16x16x32_bf16 v[8:11], v[178:181], v[206:209], v[8:11]
	v_mfma_f32_16x16x32_bf16 v[4:7], v[170:173], v[214:217], v[4:7]
	v_mfma_f32_16x16x32_bf16 v[0:3], v[178:181], v[214:217], v[0:3]
	s_barrier
	s_add_i32 s56, s56, 2
	s_add_u32 s19, s19, 0x100
	s_addc_u32 s21, s21, 0
	s_add_u32 s28, s28, 0x100
	s_addc_u32 s29, s29, 0
	s_cmp_gt_u32 s56, 29
	s_cbranch_scc0 .LBB0_1608
	s_and_b64 vcc, exec, s[10:11]
	s_cbranch_vccz .LBB0_1611
	s_barrier

; #define PG8_STAGE(bufoff, gbase, voff) do { _Pragma("unroll") for (int _i = 0; _i < 2; ++_i) \
;         __builtin_amdgcn_global_load_lds((const unsigned*)((const char*)(gbase) + (voff)[_i]), (PG8_LAS unsigned*)(lds + (bufoff) + ldsw + _i * 8192), 16, 0, 0); } while (0)
; #define PG8_LDA(dst, b, h) do { _Pragma("unroll") for (int m = 0; m < 4; ++m) _Pragma("unroll") for (int k = 0; k < 2; ++k) dst[m][k] = *(const PG8_LAS bf16x8*)(lds + PG8_SA(b, h) + aoff + m * 2048 + k * 1024); } while (0)
; #define PG8_LDB(dst, b, h) do { _Pragma("unroll") for (int n = 0; n < 2; ++n) _Pragma("unroll") for (int k = 0; k < 2; ++k) dst[n][k] = *(const PG8_LAS bf16x8*)(lds + PG8_SB(b, h) + boff + n * 2048 + k * 1024); } while (0)
; #define PG8_MMA(ai, bj, At, Bt) do { __builtin_amdgcn_s_setprio(1); _Pragma("unroll") for (int m = 0; m < 4; ++m) _Pragma("unroll") for (int n = 0; n < 2; ++n) _Pragma("unroll") for (int k = 0; k < 2; ++k) \
;         acc[ai][bj][m][n] = __builtin_amdgcn_mfma_f32_16x16x32_bf16(Bt[n][k], At[m][k], acc[ai][bj][m][n], 0, 0, 0); __builtin_amdgcn_s_setprio(0); } while (0)
; #define PG8_WAIT_V(n) asm volatile("s_waitcnt vmcnt(" #n ")" ::: "memory")
; #define PG8_WAIT_L(n) asm volatile("s_waitcnt lgkmcnt(" #n ")" ::: "memory")
; #define PG8_BAR __builtin_amdgcn_s_barrier()
; #define PG8_SCHED __builtin_amdgcn_sched_barrier(0)
; template <class Epi, class Sched, bool ALIGN_EPI = false, bool SP2 = false>
; __device__ __forceinline__ void gemm_phase(PG8_LAS unsigned char* lds, const Gemm g, const Sched& S, const Epi& E, const int wv0) {
;     ...
;             PG8_LDB(B0, 0, 0); PG8_LDB(B1, 0, 1); PG8_SCHED; PG8_LDA(At, 0, 0); PG8_STAGE(PG8_SA(1, 1), a1 + hstepA, voffA);
;             PG8_WAIT_V(8); PG8_WAIT_L(0); PG8_BAR; PG8_MMA(0, 0, At, B0); PG8_MMA(0, 1, At, B1); PG8_BAR; PG8_SCHED;
;             PG8_LDA(At, 0, 1); PG8_STAGE(PG8_SB(0, 0), b2, voffB); PG8_STAGE(PG8_SB(0, 1), b2 + hstepB, voffB); PG8_STAGE(PG8_SA(0, 0), a2, voffA);
;             PG8_WAIT_V(8); PG8_WAIT_L(0); PG8_BAR; PG8_MMA(1, 0, At, B0); PG8_MMA(1, 1, At, B1); PG8_BAR; PG8_SCHED;
.LBB0_1808:
	ds_read_b128 v[144:147], v153
	ds_read_b128 v[156:159], v153 offset:1024
	ds_read_b128 v[160:163], v153 offset:2048
	ds_read_b128 v[164:167], v153 offset:3072
	ds_read_b128 v[168:171], v154
	ds_read_b128 v[172:175], v154 offset:1024
	ds_read_b128 v[176:179], v154 offset:2048
	ds_read_b128 v[180:183], v154 offset:3072
	ds_read_b128 v[184:187], v155
	ds_read_b128 v[188:191], v155 offset:1024
	ds_read_b128 v[192:195], v155 offset:2048
	ds_read_b128 v[196:199], v155 offset:3072
	ds_read_b128 v[200:203], v155 offset:4096
	ds_read_b128 v[204:207], v155 offset:5120
	ds_read_b128 v[208:211], v155 offset:6144
	ds_read_b128 v[212:215], v155 offset:7168
	s_add_u32 s18, s16, 0x100
	s_addc_u32 s19, s17, 0
	s_cmpk_eq_i32 s48, 0x54
	s_cselect_b32 s23, s13, s19
	s_cselect_b32 s22, s12, s18
	s_cselect_b32 s21, s15, s47
	s_cselect_b32 s20, s14, s46
	s_add_i32 m0, s30, 0xc000
	v_lshl_add_u64 v[148:149], s[16:17], 0, v[138:139]
	global_load_lds_dwordx4 v[148:149], off
	v_lshl_add_u64 v[148:149], s[16:17], 0, v[136:137]
	s_add_i32 m0, s30, 0xe000
	s_nop 0
	global_load_lds_dwordx4 v[148:149], off
	s_waitcnt vmcnt(8)
	s_waitcnt lgkmcnt(0)
	s_barrier
	v_mfma_f32_16x16x32_bf16 v[124:127], v[144:147], v[184:187], v[124:127]
	v_mfma_f32_16x16x32_bf16 v[120:123], v[160:163], v[184:187], v[120:123]
	v_mfma_f32_16x16x32_bf16 v[116:119], v[144:147], v[192:195], v[116:119]
	v_mfma_f32_16x16x32_bf16 v[112:115], v[160:163], v[192:195], v[112:115]
	v_mfma_f32_16x16x32_bf16 v[92:95], v[144:147], v[200:203], v[92:95]
	v_mfma_f32_16x16x32_bf16 v[88:91], v[160:163], v[200:203], v[88:91]
	v_mfma_f32_16x16x32_bf16 v[84:87], v[144:147], v[208:211], v[84:87]
	v_mfma_f32_16x16x32_bf16 v[80:83], v[160:163], v[208:211], v[80:83]
	v_mfma_f32_16x16x32_bf16 v[124:127], v[156:159], v[188:191], v[124:127]
	v_mfma_f32_16x16x32_bf16 v[120:123], v[164:167], v[188:191], v[120:123]
	v_mfma_f32_16x16x32_bf16 v[116:119], v[156:159], v[196:199], v[116:119]
	v_mfma_f32_16x16x32_bf16 v[112:115], v[164:167], v[196:199], v[112:115]
	v_mfma_f32_16x16x32_bf16 v[92:95], v[156:159], v[204:207], v[92:95]
	v_mfma_f32_16x16x32_bf16 v[88:91], v[164:167], v[204:207], v[88:91]
	v_mfma_f32_16x16x32_bf16 v[84:87], v[156:159], v[212:215], v[84:87]
	v_mfma_f32_16x16x32_bf16 v[80:83], v[164:167], v[212:215], v[80:83]
	v_mfma_f32_16x16x32_bf16 v[108:111], v[168:171], v[184:187], v[108:111]
	v_mfma_f32_16x16x32_bf16 v[104:107], v[176:179], v[184:187], v[104:107]
	v_mfma_f32_16x16x32_bf16 v[100:103], v[168:171], v[192:195], v[100:103]
	v_mfma_f32_16x16x32_bf16 v[96:99], v[176:179], v[192:195], v[96:99]
	v_mfma_f32_16x16x32_bf16 v[76:79], v[168:171], v[200:203], v[76:79]
	v_mfma_f32_16x16x32_bf16 v[72:75], v[176:179], v[200:203], v[72:75]
	v_mfma_f32_16x16x32_bf16 v[68:71], v[168:171], v[208:211], v[68:71]
	v_mfma_f32_16x16x32_bf16 v[64:67], v[176:179], v[208:211], v[64:67]
	v_mfma_f32_16x16x32_bf16 v[108:111], v[172:175], v[188:191], v[108:111]
	v_mfma_f32_16x16x32_bf16 v[104:107], v[180:183], v[188:191], v[104:107]
	v_mfma_f32_16x16x32_bf16 v[100:103], v[172:175], v[196:199], v[100:103]
	v_mfma_f32_16x16x32_bf16 v[96:99], v[180:183], v[196:199], v[96:99]
	v_mfma_f32_16x16x32_bf16 v[76:79], v[172:175], v[204:207], v[76:79]
	v_mfma_f32_16x16x32_bf16 v[72:75], v[180:183], v[204:207], v[72:75]
	v_mfma_f32_16x16x32_bf16 v[68:71], v[172:175], v[212:215], v[68:71]
	v_mfma_f32_16x16x32_bf16 v[64:67], v[180:183], v[212:215], v[64:67]
	s_barrier
	ds_read_b128 v[184:187], v155 offset:16384
	ds_read_b128 v[188:191], v155 offset:17408
	ds_read_b128 v[192:195], v155 offset:18432
	ds_read_b128 v[196:199], v155 offset:19456
	ds_read_b128 v[200:203], v155 offset:20480
	ds_read_b128 v[204:207], v155 offset:21504
	ds_read_b128 v[208:211], v155 offset:22528
	ds_read_b128 v[212:215], v155 offset:23552
	s_add_i32 s16, s40, s29
	s_mov_b32 m0, s16
	v_lshl_add_u64 v[148:149], s[20:21], 0, v[130:131]
	global_load_lds_dwordx4 v[148:149], off
	s_add_i32 m0, s16, 0x2000
	s_add_u32 s16, s20, 0x160000
	v_lshl_add_u64 v[216:217], s[20:21], 0, v[134:135]
	s_addc_u32 s17, s21, 0
	s_add_i32 s49, s41, s29
	global_load_lds_dwordx4 v[216:217], off
	v_lshl_add_u64 v[218:219], s[16:17], 0, v[130:131]
	s_mov_b32 m0, s49
	v_lshl_add_u64 v[220:221], s[22:23], 0, v[132:133]
	global_load_lds_dwordx4 v[218:219], off
	v_lshl_add_u64 v[218:219], s[16:17], 0, v[134:135]
	s_add_i32 m0, s49, 0x2000
	s_nop 0
	global_load_lds_dwordx4 v[218:219], off
	v_lshl_add_u64 v[218:219], s[22:23], 0, v[128:129]
	s_mov_b32 m0, s30
	s_nop 0
	global_load_lds_dwordx4 v[218:219], off
	s_mov_b32 m0, s31
	s_nop 0
	global_load_lds_dwordx4 v[220:221], off
	s_waitcnt vmcnt(8)
	s_waitcnt lgkmcnt(0)
	s_barrier
; #define PG8_STAGE(bufoff, gbase, voff) do { _Pragma("unroll") for (int _i = 0; _i < 2; ++_i) \
;         __builtin_amdgcn_global_load_lds((const unsigned*)((const char*)(gbase) + (voff)[_i]), (PG8_LAS unsigned*)(lds + (bufoff) + ldsw + _i * 8192), 16, 0, 0); } while (0)
; #define PG8_LDA(dst, b, h) do { _Pragma("unroll") for (int m = 0; m < 4; ++m) _Pragma("unroll") for (int k = 0; k < 2; ++k) dst[m][k] = *(const PG8_LAS bf16x8*)(lds + PG8_SA(b, h) + aoff + m * 2048 + k * 1024); } while (0)
; #define PG8_LDB(dst, b, h) do { _Pragma("unroll") for (int n = 0; n < 2; ++n) _Pragma("unroll") for (int k = 0; k < 2; ++k) dst[n][k] = *(const PG8_LAS bf16x8*)(lds + PG8_SB(b, h) + boff + n * 2048 + k * 1024); } while (0)
; #define PG8_MMA(ai, bj, At, Bt) do { __builtin_amdgcn_s_setprio(1); _Pragma("unroll") for (int m = 0; m < 4; ++m) _Pragma("unroll") for (int n = 0; n < 2; ++n) _Pragma("unroll") for (int k = 0; k < 2; ++k) \
;         acc[ai][bj][m][n] = __builtin_amdgcn_mfma_f32_16x16x32_bf16(Bt[n][k], At[m][k], acc[ai][bj][m][n], 0, 0, 0); __builtin_amdgcn_s_setprio(0); } while (0)
; #define PG8_WAIT_V(n) asm volatile("s_waitcnt vmcnt(" #n ")" ::: "memory")
; #define PG8_WAIT_L(n) asm volatile("s_waitcnt lgkmcnt(" #n ")" ::: "memory")
; #define PG8_BAR __builtin_amdgcn_s_barrier()
; #define PG8_SCHED __builtin_amdgcn_sched_barrier(0)
; template <class Epi, class Sched, bool ALIGN_EPI = false, bool SP2 = false>
; __device__ __forceinline__ void gemm_phase(PG8_LAS unsigned char* lds, const Gemm g, const Sched& S, const Epi& E, const int wv0) {
;     ...
;             PG8_WAIT_V(8); PG8_WAIT_L(0); PG8_BAR; PG8_MMA(1, 0, At, B0); PG8_MMA(1, 1, At, B1); PG8_BAR; PG8_SCHED;
;             PG8_LDB(B0, 1, 0); PG8_LDB(B1, 1, 1); PG8_SCHED; PG8_LDA(At, 1, 0); PG8_STAGE(PG8_SA(0, 1), a2 + hstepA, voffA);
;             PG8_WAIT_V(8); PG8_WAIT_L(0); PG8_BAR; PG8_MMA(0, 0, At, B0); PG8_MMA(0, 1, At, B1); PG8_BAR; PG8_SCHED;
	v_mfma_f32_16x16x32_bf16 v[60:63], v[144:147], v[184:187], v[60:63]
	v_mfma_f32_16x16x32_bf16 v[56:59], v[160:163], v[184:187], v[56:59]
	v_mfma_f32_16x16x32_bf16 v[52:55], v[144:147], v[192:195], v[52:55]
	v_mfma_f32_16x16x32_bf16 v[48:51], v[160:163], v[192:195], v[48:51]
	v_mfma_f32_16x16x32_bf16 v[28:31], v[144:147], v[200:203], v[28:31]
	v_mfma_f32_16x16x32_bf16 v[24:27], v[160:163], v[200:203], v[24:27]
	v_mfma_f32_16x16x32_bf16 v[20:23], v[144:147], v[208:211], v[20:23]
	v_mfma_f32_16x16x32_bf16 v[16:19], v[160:163], v[208:211], v[16:19]
	v_mfma_f32_16x16x32_bf16 v[60:63], v[156:159], v[188:191], v[60:63]
	v_mfma_f32_16x16x32_bf16 v[56:59], v[164:167], v[188:191], v[56:59]
	v_mfma_f32_16x16x32_bf16 v[52:55], v[156:159], v[196:199], v[52:55]
	v_mfma_f32_16x16x32_bf16 v[48:51], v[164:167], v[196:199], v[48:51]
	v_mfma_f32_16x16x32_bf16 v[28:31], v[156:159], v[204:207], v[28:31]
	v_mfma_f32_16x16x32_bf16 v[24:27], v[164:167], v[204:207], v[24:27]
	v_mfma_f32_16x16x32_bf16 v[20:23], v[156:159], v[212:215], v[20:23]
	v_mfma_f32_16x16x32_bf16 v[16:19], v[164:167], v[212:215], v[16:19]
	v_mfma_f32_16x16x32_bf16 v[44:47], v[168:171], v[184:187], v[44:47]
	v_mfma_f32_16x16x32_bf16 v[40:43], v[176:179], v[184:187], v[40:43]
	v_mfma_f32_16x16x32_bf16 v[36:39], v[168:171], v[192:195], v[36:39]
	v_mfma_f32_16x16x32_bf16 v[32:35], v[176:179], v[192:195], v[32:35]
	v_mfma_f32_16x16x32_bf16 v[12:15], v[168:171], v[200:203], v[12:15]
	v_mfma_f32_16x16x32_bf16 v[8:11], v[176:179], v[200:203], v[8:11]
	v_mfma_f32_16x16x32_bf16 v[4:7], v[168:171], v[208:211], v[4:7]
	v_mfma_f32_16x16x32_bf16 v[0:3], v[176:179], v[208:211], v[0:3]
	v_mfma_f32_16x16x32_bf16 v[44:47], v[172:175], v[188:191], v[44:47]
	v_mfma_f32_16x16x32_bf16 v[40:43], v[180:183], v[188:191], v[40:43]
	v_mfma_f32_16x16x32_bf16 v[36:39], v[172:175], v[196:199], v[36:39]
	v_mfma_f32_16x16x32_bf16 v[32:35], v[180:183], v[196:199], v[32:35]
	v_mfma_f32_16x16x32_bf16 v[12:15], v[172:175], v[204:207], v[12:15]
	v_mfma_f32_16x16x32_bf16 v[8:11], v[180:183], v[204:207], v[8:11]
	v_mfma_f32_16x16x32_bf16 v[4:7], v[172:175], v[212:215], v[4:7]
	v_mfma_f32_16x16x32_bf16 v[0:3], v[180:183], v[212:215], v[0:3]
	s_barrier
	ds_read_b128 v[184:187], v155 offset:32768
	ds_read_b128 v[188:191], v155 offset:33792
	ds_read_b128 v[192:195], v155 offset:34816
	ds_read_b128 v[196:199], v155 offset:35840
	ds_read_b128 v[200:203], v155 offset:36864
	ds_read_b128 v[204:207], v155 offset:37888
	ds_read_b128 v[208:211], v155 offset:38912
	ds_read_b128 v[212:215], v155 offset:39936
	s_add_i32 s49, 0, 0x18000
	s_add_i32 s50, 0, 0x1c000
	v_add_u32_e32 v164, s49, v151
	v_add_u32_e32 v180, s50, v151
	ds_read_b128 v[144:147], v164
	ds_read_b128 v[156:159], v164 offset:1024
	ds_read_b128 v[160:163], v164 offset:2048
	ds_read_b128 v[164:167], v164 offset:3072
	ds_read_b128 v[168:171], v180
	ds_read_b128 v[172:175], v180 offset:1024
	ds_read_b128 v[176:179], v180 offset:2048
	ds_read_b128 v[180:183], v180 offset:3072
	s_add_u32 s16, s22, 0x160000
	s_addc_u32 s17, s23, 0
	s_mov_b32 m0, s34
	v_lshl_add_u64 v[222:223], s[16:17], 0, v[128:129]
	global_load_lds_dwordx4 v[222:223], off
	v_lshl_add_u64 v[222:223], s[16:17], 0, v[132:133]
	s_mov_b32 m0, s35
	s_nop 0
	global_load_lds_dwordx4 v[222:223], off
	s_waitcnt vmcnt(8)
	s_waitcnt lgkmcnt(0)
	s_barrier
	v_mfma_f32_16x16x32_bf16 v[124:127], v[144:147], v[184:187], v[124:127]
	v_mfma_f32_16x16x32_bf16 v[120:123], v[160:163], v[184:187], v[120:123]
	v_mfma_f32_16x16x32_bf16 v[116:119], v[144:147], v[192:195], v[116:119]
	v_mfma_f32_16x16x32_bf16 v[112:115], v[160:163], v[192:195], v[112:115]
	v_mfma_f32_16x16x32_bf16 v[92:95], v[144:147], v[200:203], v[92:95]
	v_mfma_f32_16x16x32_bf16 v[88:91], v[160:163], v[200:203], v[88:91]
	v_mfma_f32_16x16x32_bf16 v[84:87], v[144:147], v[208:211], v[84:87]
	v_mfma_f32_16x16x32_bf16 v[80:83], v[160:163], v[208:211], v[80:83]
	v_mfma_f32_16x16x32_bf16 v[124:127], v[156:159], v[188:191], v[124:127]
	v_mfma_f32_16x16x32_bf16 v[120:123], v[164:167], v[188:191], v[120:123]
	v_mfma_f32_16x16x32_bf16 v[116:119], v[156:159], v[196:199], v[116:119]
	v_mfma_f32_16x16x32_bf16 v[112:115], v[164:167], v[196:199], v[112:115]
	v_mfma_f32_16x16x32_bf16 v[92:95], v[156:159], v[204:207], v[92:95]
	v_mfma_f32_16x16x32_bf16 v[88:91], v[164:167], v[204:207], v[88:91]
	v_mfma_f32_16x16x32_bf16 v[84:87], v[156:159], v[212:215], v[84:87]
	v_mfma_f32_16x16x32_bf16 v[80:83], v[164:167], v[212:215], v[80:83]
	v_mfma_f32_16x16x32_bf16 v[108:111], v[168:171], v[184:187], v[108:111]
	v_mfma_f32_16x16x32_bf16 v[104:107], v[176:179], v[184:187], v[104:107]
	v_mfma_f32_16x16x32_bf16 v[100:103], v[168:171], v[192:195], v[100:103]
	v_mfma_f32_16x16x32_bf16 v[96:99], v[176:179], v[192:195], v[96:99]
	v_mfma_f32_16x16x32_bf16 v[76:79], v[168:171], v[200:203], v[76:79]
	v_mfma_f32_16x16x32_bf16 v[72:75], v[176:179], v[200:203], v[72:75]
	v_mfma_f32_16x16x32_bf16 v[68:71], v[168:171], v[208:211], v[68:71]
	v_mfma_f32_16x16x32_bf16 v[64:67], v[176:179], v[208:211], v[64:67]
	v_mfma_f32_16x16x32_bf16 v[108:111], v[172:175], v[188:191], v[108:111]
	v_mfma_f32_16x16x32_bf16 v[104:107], v[180:183], v[188:191], v[104:107]
	v_mfma_f32_16x16x32_bf16 v[100:103], v[172:175], v[196:199], v[100:103]
	v_mfma_f32_16x16x32_bf16 v[96:99], v[180:183], v[196:199], v[96:99]
	v_mfma_f32_16x16x32_bf16 v[76:79], v[172:175], v[204:207], v[76:79]
	v_mfma_f32_16x16x32_bf16 v[72:75], v[180:183], v[204:207], v[72:75]
	v_mfma_f32_16x16x32_bf16 v[68:71], v[172:175], v[212:215], v[68:71]
	v_mfma_f32_16x16x32_bf16 v[64:67], v[180:183], v[212:215], v[64:67]
	s_barrier
; #define PG8_STAGE(bufoff, gbase, voff) do { _Pragma("unroll") for (int _i = 0; _i < 2; ++_i) \
;         __builtin_amdgcn_global_load_lds((const unsigned*)((const char*)(gbase) + (voff)[_i]), (PG8_LAS unsigned*)(lds + (bufoff) + ldsw + _i * 8192), 16, 0, 0); } while (0)
; #define PG8_LDA(dst, b, h) do { _Pragma("unroll") for (int m = 0; m < 4; ++m) _Pragma("unroll") for (int k = 0; k < 2; ++k) dst[m][k] = *(const PG8_LAS bf16x8*)(lds + PG8_SA(b, h) + aoff + m * 2048 + k * 1024); } while (0)
; #define PG8_MMA(ai, bj, At, Bt) do { __builtin_amdgcn_s_setprio(1); _Pragma("unroll") for (int m = 0; m < 4; ++m) _Pragma("unroll") for (int n = 0; n < 2; ++n) _Pragma("unroll") for (int k = 0; k < 2; ++k) \
;         acc[ai][bj][m][n] = __builtin_amdgcn_mfma_f32_16x16x32_bf16(Bt[n][k], At[m][k], acc[ai][bj][m][n], 0, 0, 0); __builtin_amdgcn_s_setprio(0); } while (0)
; #define PG8_WAIT_V(n) asm volatile("s_waitcnt vmcnt(" #n ")" ::: "memory")
; #define PG8_WAIT_L(n) asm volatile("s_waitcnt lgkmcnt(" #n ")" ::: "memory")
; #define PG8_BAR __builtin_amdgcn_s_barrier()
; #define PG8_SCHED __builtin_amdgcn_sched_barrier(0)
; template <class Epi, class Sched, bool ALIGN_EPI = false, bool SP2 = false>
; __device__ __forceinline__ void gemm_phase(PG8_LAS unsigned char* lds, const Gemm g, const Sched& S, const Epi& E, const int wv0) {
;     ...
;         for (int t = 0; t < nt; t += 2) {
;             const bool last = (t == nt - 2);
;     ...
;             PG8_LDA(At, 1, 1); PG8_STAGE(PG8_SB(1, 0), b3, voffB); PG8_STAGE(PG8_SB(1, 1), b3 + hstepB, voffB); PG8_STAGE(PG8_SA(1, 0), a3, voffA);
;             PG8_WAIT_V(8); PG8_WAIT_L(0); PG8_BAR; PG8_MMA(1, 0, At, B0); PG8_MMA(1, 1, At, B1); PG8_BAR; PG8_SCHED;
;     ...
;         if constexpr (ALIGN_EPI) { if (wr == 0) PG8_BAR; }
	ds_read_b128 v[184:187], v155 offset:49152
	ds_read_b128 v[188:191], v155 offset:50176
	ds_read_b128 v[192:195], v155 offset:51200
	ds_read_b128 v[196:199], v155 offset:52224
	ds_read_b128 v[200:203], v155 offset:53248
	ds_read_b128 v[204:207], v155 offset:54272
	ds_read_b128 v[208:211], v155 offset:55296
	ds_read_b128 v[212:215], v155 offset:56320
	s_add_i32 s16, s49, s29
	s_mov_b32 m0, s16
	v_lshl_add_u64 v[148:149], v[148:149], 0, s[8:9]
	global_load_lds_dwordx4 v[148:149], off
	s_add_i32 m0, s16, 0x2000
	s_add_u32 s16, s20, 0x160080
	v_lshl_add_u64 v[148:149], v[216:217], 0, s[8:9]
	s_addc_u32 s17, s21, 0
	s_add_i32 s20, s50, s29
	global_load_lds_dwordx4 v[148:149], off
	v_lshl_add_u64 v[148:149], s[16:17], 0, v[130:131]
	s_mov_b32 m0, s20
	s_nop 0
	global_load_lds_dwordx4 v[148:149], off
	v_lshl_add_u64 v[148:149], s[16:17], 0, v[134:135]
	s_add_i32 m0, s20, 0x2000
	s_nop 0
	global_load_lds_dwordx4 v[148:149], off
	v_lshl_add_u64 v[148:149], v[218:219], 0, s[8:9]
	s_mov_b32 m0, s37
	s_nop 0
	global_load_lds_dwordx4 v[148:149], off
	v_lshl_add_u64 v[148:149], v[220:221], 0, s[8:9]
	s_mov_b32 m0, s38
	s_nop 0
	global_load_lds_dwordx4 v[148:149], off
	s_waitcnt vmcnt(8)
	s_waitcnt lgkmcnt(0)
	s_barrier
	v_mfma_f32_16x16x32_bf16 v[60:63], v[144:147], v[184:187], v[60:63]
	v_mfma_f32_16x16x32_bf16 v[56:59], v[160:163], v[184:187], v[56:59]
	v_mfma_f32_16x16x32_bf16 v[52:55], v[144:147], v[192:195], v[52:55]
	v_mfma_f32_16x16x32_bf16 v[48:51], v[160:163], v[192:195], v[48:51]
	v_mfma_f32_16x16x32_bf16 v[28:31], v[144:147], v[200:203], v[28:31]
	v_mfma_f32_16x16x32_bf16 v[24:27], v[160:163], v[200:203], v[24:27]
	v_mfma_f32_16x16x32_bf16 v[20:23], v[144:147], v[208:211], v[20:23]
	v_mfma_f32_16x16x32_bf16 v[16:19], v[160:163], v[208:211], v[16:19]
	v_mfma_f32_16x16x32_bf16 v[60:63], v[156:159], v[188:191], v[60:63]
	v_mfma_f32_16x16x32_bf16 v[56:59], v[164:167], v[188:191], v[56:59]
	v_mfma_f32_16x16x32_bf16 v[52:55], v[156:159], v[196:199], v[52:55]
	v_mfma_f32_16x16x32_bf16 v[48:51], v[164:167], v[196:199], v[48:51]
	v_mfma_f32_16x16x32_bf16 v[28:31], v[156:159], v[204:207], v[28:31]
	v_mfma_f32_16x16x32_bf16 v[24:27], v[164:167], v[204:207], v[24:27]
	v_mfma_f32_16x16x32_bf16 v[20:23], v[156:159], v[212:215], v[20:23]
	v_mfma_f32_16x16x32_bf16 v[16:19], v[164:167], v[212:215], v[16:19]
	v_mfma_f32_16x16x32_bf16 v[44:47], v[168:171], v[184:187], v[44:47]
	v_mfma_f32_16x16x32_bf16 v[40:43], v[176:179], v[184:187], v[40:43]
	v_mfma_f32_16x16x32_bf16 v[36:39], v[168:171], v[192:195], v[36:39]
	v_mfma_f32_16x16x32_bf16 v[32:35], v[176:179], v[192:195], v[32:35]
	v_mfma_f32_16x16x32_bf16 v[12:15], v[168:171], v[200:203], v[12:15]
	v_mfma_f32_16x16x32_bf16 v[8:11], v[176:179], v[200:203], v[8:11]
	v_mfma_f32_16x16x32_bf16 v[4:7], v[168:171], v[208:211], v[4:7]
	v_mfma_f32_16x16x32_bf16 v[0:3], v[176:179], v[208:211], v[0:3]
	v_mfma_f32_16x16x32_bf16 v[44:47], v[172:175], v[188:191], v[44:47]
	v_mfma_f32_16x16x32_bf16 v[40:43], v[180:183], v[188:191], v[40:43]
	v_mfma_f32_16x16x32_bf16 v[36:39], v[172:175], v[196:199], v[36:39]
	v_mfma_f32_16x16x32_bf16 v[32:35], v[180:183], v[196:199], v[32:35]
	v_mfma_f32_16x16x32_bf16 v[12:15], v[172:175], v[204:207], v[12:15]
	v_mfma_f32_16x16x32_bf16 v[8:11], v[180:183], v[204:207], v[8:11]
	v_mfma_f32_16x16x32_bf16 v[4:7], v[172:175], v[212:215], v[4:7]
	v_mfma_f32_16x16x32_bf16 v[0:3], v[180:183], v[212:215], v[0:3]
	s_barrier
	s_add_i32 s48, s48, 2
	s_add_u32 s46, s46, 0x100
	s_addc_u32 s47, s47, 0
	s_cmpk_gt_u32 s48, 0x55
	s_mov_b64 s[16:17], s[18:19]
	s_cbranch_scc0 .LBB0_1808
	s_and_b64 vcc, exec, s[10:11]
	s_cbranch_vccz .LBB0_1811
	s_barrier
